# DMA staging rebalanced 2/6 to 4/4 per phase in 12 K-loops (A half0 staged in SP1), vmcnt(6) in SP2
# speedup vs baseline: 1.0034x; 1.0034x over previous
;     __device__ __forceinline__ void a_ready(const Unit&) const { wait_cnt(w_ready, w_need); }
;     __device__ __forceinline__ void half_ready(const Unit& u) const { wait_cnt(g_ready + 64 * u.pm, g_need); }
; #define PG8_STAGE(bufoff, gbase, voff) do { _Pragma("unroll") for (int _i = 0; _i < 2; ++_i) \
;         asm volatile("s_mov_b32 m0, %0\n\ts_nop 0\n\tglobal_load_lds_dwordx4 %1, %2" :: "s"(ldsb + (unsigned)(bufoff) + ldsw + (unsigned)(_i * 8192)), "v"((voff)[_i]), "s"((const char*)(gbase)) : "memory", "m0"); } while (0)
; #define PG8_LDA(dst, b, h) do { _Pragma("unroll") for (int m = 0; m < 4; ++m) _Pragma("unroll") for (int k = 0; k < 2; ++k) dst[m][k] = *(const LAS bf16x8*)(lds + PG8_SA(b, h) + aoff + m * 2048 + k * 1024); } while (0)
; #define PG8_LDB(dst, b, h) do { _Pragma("unroll") for (int n = 0; n < 2; ++n) _Pragma("unroll") for (int k = 0; k < 2; ++k) dst[n][k] = *(const LAS bf16x8*)(lds + PG8_SB(b, h) + boff + n * 2048 + k * 1024); } while (0)
; #define PG8_WAIT_V(n) asm volatile("s_waitcnt vmcnt(" #n ")" ::: "memory")
; #define PG8_WAIT_L(n) asm volatile("s_waitcnt lgkmcnt(" #n ")" ::: "memory")
; template <class Epi, class Sched>
; __device__ __forceinline__ void gemm_phase(LAS unsigned char* lds, const Gemm g, const Sched& S, const Epi& E) {
;     ...
;             const bool last = (t == nt - 2);
;             if (last && has_next) S.a_ready(nxt);
;             if constexpr (Sched::TWO_HALVES) { if (t == KSW - 2) S.half_ready(cur); }
;             const char* a1 = cA + PG8_KOFF(t + 1) * (long)kstep;
;             const char* a2 = last ? nA : cA + PG8_KOFF(t + 2) * (long)kstep; const char* b2 = last ? nB : cB + PG8_KOFF(t + 2) * (long)kstep;
;             const char* a3 = a2 + kstep; const char* b3 = b2 + kstep;
;             if constexpr (Epi::HAS_MID) { if (t == Epi::MID_T) E.mid(acc, cur, wr, wc, fr, fq); }
;             PG8_LDB(B0, 0, 0); PG8_LDB(B1, 0, 1); PG8_SCHED; PG8_LDA(At, 0, 0); PG8_STAGE(PG8_SA(1, 1), a1 + hstepA, voffA);
;             PG8_WAIT_V(8); PG8_WAIT_L(0); PG8_BAR; PG8_MMA(0, 0, At, B0); PG8_MMA(0, 1, At, B1); PG8_BAR; PG8_SCHED;
;             PG8_LDA(At, 0, 1); PG8_STAGE(PG8_SB(0, 0), b2, voffB); PG8_STAGE(PG8_SB(0, 1), b2 + hstepB, voffB); PG8_STAGE(PG8_SA(0, 0), a2, voffA);
;             PG8_WAIT_V(8); PG8_WAIT_L(0); PG8_BAR; PG8_MMA(1, 0, At, B0); PG8_MMA(1, 1, At, B1); PG8_BAR; PG8_SCHED;
.LBB0_168:
	ds_read_b128 v[144:147], v138
	ds_read_b128 v[148:151], v138 offset:1024
	ds_read_b128 v[152:155], v138 offset:2048
	ds_read_b128 v[156:159], v138 offset:3072
	ds_read_b128 v[160:163], v139
	ds_read_b128 v[164:167], v139 offset:1024
	ds_read_b128 v[168:171], v139 offset:2048
	ds_read_b128 v[172:175], v139 offset:3072
	s_cmp_eq_u32 s42, 28
	s_cselect_b32 s54, s15, s38
	s_cselect_b32 s55, s11, s39
	s_cselect_b32 s52, s74, s40
	s_cselect_b32 s53, s13, s41
	s_add_u32 s44, s54, 0x80
	s_addc_u32 s45, s55, 0
	ds_read_b128 v[176:179], v140
	ds_read_b128 v[184:187], v140 offset:1024
	ds_read_b128 v[188:191], v140 offset:2048
	ds_read_b128 v[192:195], v140 offset:3072
	ds_read_b128 v[196:199], v140 offset:4096
	ds_read_b128 v[200:203], v140 offset:5120
	ds_read_b128 v[204:207], v140 offset:6144
	ds_read_b128 v[212:215], v140 offset:7168
	s_add_u32 s46, s38, 0xffffff80
	s_addc_u32 s47, s39, -1
	s_mov_b32 m0, s66
	s_nop 0
	global_load_lds_dwordx4 v132, s[46:47]
	s_mov_b32 m0, s67
	s_nop 0
	global_load_lds_dwordx4 v134, s[46:47]
	s_add_u32 s46, s38, 0x7ff80
	s_addc_u32 s47, s39, 0
	s_mov_b32 m0, s70
	s_nop 0
	global_load_lds_dwordx4 v132, s[46:47]
	s_nop 0
	s_mov_b32 m0, s71
	s_nop 0
	global_load_lds_dwordx4 v134, s[46:47]
	s_waitcnt vmcnt(8)
	s_waitcnt lgkmcnt(0)
	s_barrier
	s_setprio 1
	s_waitcnt lgkmcnt(7)
	v_mfma_f32_16x16x32_bf16 v[122:125], v[144:147], v[176:179], v[122:125]
	v_mfma_f32_16x16x32_bf16 v[114:117], v[152:155], v[176:179], v[114:117]
	s_waitcnt lgkmcnt(5)
	v_mfma_f32_16x16x32_bf16 v[110:113], v[144:147], v[188:191], v[110:113]
	v_mfma_f32_16x16x32_bf16 v[106:109], v[152:155], v[188:191], v[106:109]
	s_waitcnt lgkmcnt(3)
	v_mfma_f32_16x16x32_bf16 v[78:81], v[144:147], v[196:199], v[78:81]
	v_mfma_f32_16x16x32_bf16 v[66:69], v[152:155], v[196:199], v[66:69]
	s_waitcnt lgkmcnt(1)
	v_mfma_f32_16x16x32_bf16 v[38:41], v[144:147], v[204:207], v[38:41]
	v_mfma_f32_16x16x32_bf16 v[26:29], v[152:155], v[204:207], v[26:29]
	v_mfma_f32_16x16x32_bf16 v[122:125], v[148:151], v[184:187], v[122:125]
	v_mfma_f32_16x16x32_bf16 v[114:117], v[156:159], v[184:187], v[114:117]
	v_mfma_f32_16x16x32_bf16 v[110:113], v[148:151], v[192:195], v[110:113]
	v_mfma_f32_16x16x32_bf16 v[106:109], v[156:159], v[192:195], v[106:109]
	v_mfma_f32_16x16x32_bf16 v[78:81], v[148:151], v[200:203], v[78:81]
	v_mfma_f32_16x16x32_bf16 v[66:69], v[156:159], v[200:203], v[66:69]
	s_waitcnt lgkmcnt(0)
	v_mfma_f32_16x16x32_bf16 v[38:41], v[148:151], v[212:215], v[38:41]
	v_mfma_f32_16x16x32_bf16 v[26:29], v[156:159], v[212:215], v[26:29]
	s_setprio 0
	s_setprio 1
	v_mfma_f32_16x16x32_bf16 v[126:129], v[160:163], v[176:179], v[126:129]
	v_mfma_f32_16x16x32_bf16 v[118:121], v[168:171], v[176:179], v[118:121]
	v_mfma_f32_16x16x32_bf16 v[94:97], v[160:163], v[188:191], v[94:97]
	v_mfma_f32_16x16x32_bf16 v[90:93], v[168:171], v[188:191], v[90:93]
	v_mfma_f32_16x16x32_bf16 v[54:57], v[160:163], v[196:199], v[54:57]
	v_mfma_f32_16x16x32_bf16 v[50:53], v[168:171], v[196:199], v[50:53]
	v_mfma_f32_16x16x32_bf16 v[22:25], v[160:163], v[204:207], v[22:25]
	v_mfma_f32_16x16x32_bf16 v[18:21], v[168:171], v[204:207], v[18:21]
	v_mfma_f32_16x16x32_bf16 v[126:129], v[164:167], v[184:187], v[126:129]
	v_mfma_f32_16x16x32_bf16 v[118:121], v[172:175], v[184:187], v[118:121]
	v_mfma_f32_16x16x32_bf16 v[94:97], v[164:167], v[192:195], v[94:97]
	v_mfma_f32_16x16x32_bf16 v[90:93], v[172:175], v[192:195], v[90:93]
	v_mfma_f32_16x16x32_bf16 v[54:57], v[164:167], v[200:203], v[54:57]
	v_mfma_f32_16x16x32_bf16 v[50:53], v[172:175], v[200:203], v[50:53]
	v_mfma_f32_16x16x32_bf16 v[22:25], v[164:167], v[212:215], v[22:25]
	v_mfma_f32_16x16x32_bf16 v[18:21], v[172:175], v[212:215], v[18:21]
	s_setprio 0
	s_barrier
	ds_read_b128 v[176:179], v140 offset:16384
	ds_read_b128 v[184:187], v140 offset:17408
	ds_read_b128 v[188:191], v140 offset:18432
	ds_read_b128 v[192:195], v140 offset:19456
	ds_read_b128 v[196:199], v140 offset:20480
	ds_read_b128 v[200:203], v140 offset:21504
	ds_read_b128 v[204:207], v140 offset:22528
	ds_read_b128 v[212:215], v140 offset:23552
	s_mov_b32 m0, s57
	s_nop 0
	global_load_lds_dwordx4 v133, s[52:53]
	s_add_u32 s46, s52, 0x80000
	s_mov_b32 m0, s58
	s_nop 0
	global_load_lds_dwordx4 v135, s[52:53]
	s_addc_u32 s47, s53, 0
	s_mov_b32 m0, s59
	s_nop 0
	global_load_lds_dwordx4 v133, s[46:47]
	s_nop 0
	s_mov_b32 m0, s60
	s_nop 0
	global_load_lds_dwordx4 v135, s[46:47]
	s_nop 0
	s_waitcnt vmcnt(6)
	s_waitcnt lgkmcnt(0)
	s_barrier
; #define PG8_STAGE(bufoff, gbase, voff) do { _Pragma("unroll") for (int _i = 0; _i < 2; ++_i) \
;         asm volatile("s_mov_b32 m0, %0\n\ts_nop 0\n\tglobal_load_lds_dwordx4 %1, %2" :: "s"(ldsb + (unsigned)(bufoff) + ldsw + (unsigned)(_i * 8192)), "v"((voff)[_i]), "s"((const char*)(gbase)) : "memory", "m0"); } while (0)
; #define PG8_LDA(dst, b, h) do { _Pragma("unroll") for (int m = 0; m < 4; ++m) _Pragma("unroll") for (int k = 0; k < 2; ++k) dst[m][k] = *(const LAS bf16x8*)(lds + PG8_SA(b, h) + aoff + m * 2048 + k * 1024); } while (0)
; #define PG8_LDB(dst, b, h) do { _Pragma("unroll") for (int n = 0; n < 2; ++n) _Pragma("unroll") for (int k = 0; k < 2; ++k) dst[n][k] = *(const LAS bf16x8*)(lds + PG8_SB(b, h) + boff + n * 2048 + k * 1024); } while (0)
; #define PG8_MMA(ai, bj, At, Bt) do { __builtin_amdgcn_s_setprio(1); _Pragma("unroll") for (int m = 0; m < 4; ++m) _Pragma("unroll") for (int n = 0; n < 2; ++n) _Pragma("unroll") for (int k = 0; k < 2; ++k) \
;         acc[ai][bj][m][n] = __builtin_amdgcn_mfma_f32_16x16x32_bf16(Bt[n][k], At[m][k], acc[ai][bj][m][n], 0, 0, 0); __builtin_amdgcn_s_setprio(0); } while (0)
; #define PG8_WAIT_V(n) asm volatile("s_waitcnt vmcnt(" #n ")" ::: "memory")
; #define PG8_WAIT_L(n) asm volatile("s_waitcnt lgkmcnt(" #n ")" ::: "memory")
; #define PG8_BAR __builtin_amdgcn_s_barrier()
; #define PG8_SCHED __builtin_amdgcn_sched_barrier(0)
; template <class Epi, class Sched>
; __device__ __forceinline__ void gemm_phase(LAS unsigned char* lds, const Gemm g, const Sched& S, const Epi& E) {
;     ...
;             PG8_WAIT_V(8); PG8_WAIT_L(0); PG8_BAR; PG8_MMA(1, 0, At, B0); PG8_MMA(1, 1, At, B1); PG8_BAR; PG8_SCHED;
;             PG8_LDB(B0, 1, 0); PG8_LDB(B1, 1, 1); PG8_SCHED; PG8_LDA(At, 1, 0); PG8_STAGE(PG8_SA(0, 1), a2 + hstepA, voffA);
;             PG8_WAIT_V(8); PG8_WAIT_L(0); PG8_BAR; PG8_MMA(0, 0, At, B0); PG8_MMA(0, 1, At, B1); PG8_BAR; PG8_SCHED;
	s_setprio 1
	s_waitcnt lgkmcnt(7)
	v_mfma_f32_16x16x32_bf16 v[86:89], v[144:147], v[176:179], v[86:89]
	v_mfma_f32_16x16x32_bf16 v[82:85], v[152:155], v[176:179], v[82:85]
	s_waitcnt lgkmcnt(5)
	v_mfma_f32_16x16x32_bf16 v[62:65], v[144:147], v[188:191], v[62:65]
	v_mfma_f32_16x16x32_bf16 v[58:61], v[152:155], v[188:191], v[58:61]
	s_waitcnt lgkmcnt(3)
	v_mfma_f32_16x16x32_bf16 v[34:37], v[144:147], v[196:199], v[34:37]
	v_mfma_f32_16x16x32_bf16 v[30:33], v[152:155], v[196:199], v[30:33]
	s_waitcnt lgkmcnt(1)
	v_mfma_f32_16x16x32_bf16 v[6:9], v[144:147], v[204:207], v[6:9]
	v_mfma_f32_16x16x32_bf16 v[2:5], v[152:155], v[204:207], v[2:5]
	v_mfma_f32_16x16x32_bf16 v[86:89], v[148:151], v[184:187], v[86:89]
	v_mfma_f32_16x16x32_bf16 v[82:85], v[156:159], v[184:187], v[82:85]
	v_mfma_f32_16x16x32_bf16 v[62:65], v[148:151], v[192:195], v[62:65]
	v_mfma_f32_16x16x32_bf16 v[58:61], v[156:159], v[192:195], v[58:61]
	v_mfma_f32_16x16x32_bf16 v[34:37], v[148:151], v[200:203], v[34:37]
	v_mfma_f32_16x16x32_bf16 v[30:33], v[156:159], v[200:203], v[30:33]
	s_waitcnt lgkmcnt(0)
	v_mfma_f32_16x16x32_bf16 v[6:9], v[148:151], v[212:215], v[6:9]
	v_mfma_f32_16x16x32_bf16 v[2:5], v[156:159], v[212:215], v[2:5]
	s_setprio 0
	s_setprio 1
	v_mfma_f32_16x16x32_bf16 v[102:105], v[160:163], v[176:179], v[102:105]
	v_mfma_f32_16x16x32_bf16 v[98:101], v[168:171], v[176:179], v[98:101]
	v_mfma_f32_16x16x32_bf16 v[74:77], v[160:163], v[188:191], v[74:77]
	v_mfma_f32_16x16x32_bf16 v[70:73], v[168:171], v[188:191], v[70:73]
	v_mfma_f32_16x16x32_bf16 v[46:49], v[160:163], v[196:199], v[46:49]
	v_mfma_f32_16x16x32_bf16 v[42:45], v[168:171], v[196:199], v[42:45]
	v_mfma_f32_16x16x32_bf16 v[14:17], v[160:163], v[204:207], v[14:17]
	v_mfma_f32_16x16x32_bf16 v[10:13], v[168:171], v[204:207], v[10:13]
	v_mfma_f32_16x16x32_bf16 v[102:105], v[164:167], v[184:187], v[102:105]
	v_mfma_f32_16x16x32_bf16 v[98:101], v[172:175], v[184:187], v[98:101]
	v_mfma_f32_16x16x32_bf16 v[74:77], v[164:167], v[192:195], v[74:77]
	v_mfma_f32_16x16x32_bf16 v[70:73], v[172:175], v[192:195], v[70:73]
	v_mfma_f32_16x16x32_bf16 v[46:49], v[164:167], v[200:203], v[46:49]
	v_mfma_f32_16x16x32_bf16 v[42:45], v[172:175], v[200:203], v[42:45]
	v_mfma_f32_16x16x32_bf16 v[14:17], v[164:167], v[212:215], v[14:17]
	v_mfma_f32_16x16x32_bf16 v[10:13], v[172:175], v[212:215], v[10:13]
	s_setprio 0
	s_barrier
	ds_read_b128 v[144:147], v141
	ds_read_b128 v[148:151], v141 offset:1024
	ds_read_b128 v[152:155], v141 offset:2048
	ds_read_b128 v[156:159], v141 offset:3072
	ds_read_b128 v[160:163], v142
	ds_read_b128 v[164:167], v142 offset:1024
	ds_read_b128 v[168:171], v142 offset:2048
	ds_read_b128 v[172:175], v142 offset:3072
	ds_read_b128 v[176:179], v140 offset:32768
	ds_read_b128 v[184:187], v140 offset:33792
	ds_read_b128 v[188:191], v140 offset:34816
	ds_read_b128 v[192:195], v140 offset:35840
	ds_read_b128 v[196:199], v140 offset:36864
	ds_read_b128 v[200:203], v140 offset:37888
	ds_read_b128 v[204:207], v140 offset:38912
	ds_read_b128 v[212:215], v140 offset:39936
	s_mov_b32 m0, s56
	s_nop 0
	global_load_lds_dwordx4 v132, s[54:55]
	s_mov_b32 m0, s61
	s_nop 0
	global_load_lds_dwordx4 v134, s[54:55]
	s_add_u32 s46, s54, 0x80000
	s_addc_u32 s47, s55, 0
	s_mov_b32 m0, s62
	s_nop 0
	global_load_lds_dwordx4 v132, s[46:47]
	s_nop 0
	s_mov_b32 m0, s63
	s_nop 0
	global_load_lds_dwordx4 v134, s[46:47]
	s_waitcnt vmcnt(8)
	s_waitcnt lgkmcnt(0)
	s_barrier
; #define PG8_STAGE(bufoff, gbase, voff) do { _Pragma("unroll") for (int _i = 0; _i < 2; ++_i) \
;         asm volatile("s_mov_b32 m0, %0\n\ts_nop 0\n\tglobal_load_lds_dwordx4 %1, %2" :: "s"(ldsb + (unsigned)(bufoff) + ldsw + (unsigned)(_i * 8192)), "v"((voff)[_i]), "s"((const char*)(gbase)) : "memory", "m0"); } while (0)
; #define PG8_LDA(dst, b, h) do { _Pragma("unroll") for (int m = 0; m < 4; ++m) _Pragma("unroll") for (int k = 0; k < 2; ++k) dst[m][k] = *(const LAS bf16x8*)(lds + PG8_SA(b, h) + aoff + m * 2048 + k * 1024); } while (0)
; #define PG8_MMA(ai, bj, At, Bt) do { __builtin_amdgcn_s_setprio(1); _Pragma("unroll") for (int m = 0; m < 4; ++m) _Pragma("unroll") for (int n = 0; n < 2; ++n) _Pragma("unroll") for (int k = 0; k < 2; ++k) \
;         acc[ai][bj][m][n] = __builtin_amdgcn_mfma_f32_16x16x32_bf16(Bt[n][k], At[m][k], acc[ai][bj][m][n], 0, 0, 0); __builtin_amdgcn_s_setprio(0); } while (0)
; #define PG8_WAIT_V(n) asm volatile("s_waitcnt vmcnt(" #n ")" ::: "memory")
; #define PG8_WAIT_L(n) asm volatile("s_waitcnt lgkmcnt(" #n ")" ::: "memory")
; #define PG8_BAR __builtin_amdgcn_s_barrier()
; #define PG8_SCHED __builtin_amdgcn_sched_barrier(0)
; template <class Epi, class Sched>
; __device__ __forceinline__ void gemm_phase(LAS unsigned char* lds, const Gemm g, const Sched& S, const Epi& E) {
;     ...
;             PG8_WAIT_V(8); PG8_WAIT_L(0); PG8_BAR; PG8_MMA(0, 0, At, B0); PG8_MMA(0, 1, At, B1); PG8_BAR; PG8_SCHED;
;             PG8_LDA(At, 1, 1); PG8_STAGE(PG8_SB(1, 0), b3, voffB); PG8_STAGE(PG8_SB(1, 1), b3 + hstepB, voffB); PG8_STAGE(PG8_SA(1, 0), a3, voffA);
;             PG8_WAIT_V(8); PG8_WAIT_L(0); PG8_BAR; PG8_MMA(1, 0, At, B0); PG8_MMA(1, 1, At, B1); PG8_BAR; PG8_SCHED;
;         }
	s_setprio 1
	s_waitcnt lgkmcnt(7)
	v_mfma_f32_16x16x32_bf16 v[122:125], v[144:147], v[176:179], v[122:125]
	v_mfma_f32_16x16x32_bf16 v[114:117], v[152:155], v[176:179], v[114:117]
	s_waitcnt lgkmcnt(5)
	v_mfma_f32_16x16x32_bf16 v[110:113], v[144:147], v[188:191], v[110:113]
	v_mfma_f32_16x16x32_bf16 v[106:109], v[152:155], v[188:191], v[106:109]
	s_waitcnt lgkmcnt(3)
	v_mfma_f32_16x16x32_bf16 v[78:81], v[144:147], v[196:199], v[78:81]
	v_mfma_f32_16x16x32_bf16 v[66:69], v[152:155], v[196:199], v[66:69]
	s_waitcnt lgkmcnt(1)
	v_mfma_f32_16x16x32_bf16 v[38:41], v[144:147], v[204:207], v[38:41]
	v_mfma_f32_16x16x32_bf16 v[26:29], v[152:155], v[204:207], v[26:29]
	v_mfma_f32_16x16x32_bf16 v[122:125], v[148:151], v[184:187], v[122:125]
	v_mfma_f32_16x16x32_bf16 v[114:117], v[156:159], v[184:187], v[114:117]
	v_mfma_f32_16x16x32_bf16 v[110:113], v[148:151], v[192:195], v[110:113]
	v_mfma_f32_16x16x32_bf16 v[106:109], v[156:159], v[192:195], v[106:109]
	v_mfma_f32_16x16x32_bf16 v[78:81], v[148:151], v[200:203], v[78:81]
	v_mfma_f32_16x16x32_bf16 v[66:69], v[156:159], v[200:203], v[66:69]
	s_waitcnt lgkmcnt(0)
	v_mfma_f32_16x16x32_bf16 v[38:41], v[148:151], v[212:215], v[38:41]
	v_mfma_f32_16x16x32_bf16 v[26:29], v[156:159], v[212:215], v[26:29]
	s_setprio 0
	s_setprio 1
	v_mfma_f32_16x16x32_bf16 v[126:129], v[160:163], v[176:179], v[126:129]
	v_mfma_f32_16x16x32_bf16 v[118:121], v[168:171], v[176:179], v[118:121]
	v_mfma_f32_16x16x32_bf16 v[94:97], v[160:163], v[188:191], v[94:97]
	v_mfma_f32_16x16x32_bf16 v[90:93], v[168:171], v[188:191], v[90:93]
	v_mfma_f32_16x16x32_bf16 v[54:57], v[160:163], v[196:199], v[54:57]
	v_mfma_f32_16x16x32_bf16 v[50:53], v[168:171], v[196:199], v[50:53]
	v_mfma_f32_16x16x32_bf16 v[22:25], v[160:163], v[204:207], v[22:25]
	v_mfma_f32_16x16x32_bf16 v[18:21], v[168:171], v[204:207], v[18:21]
	v_mfma_f32_16x16x32_bf16 v[126:129], v[164:167], v[184:187], v[126:129]
	v_mfma_f32_16x16x32_bf16 v[118:121], v[172:175], v[184:187], v[118:121]
	v_mfma_f32_16x16x32_bf16 v[94:97], v[164:167], v[192:195], v[94:97]
	v_mfma_f32_16x16x32_bf16 v[90:93], v[172:175], v[192:195], v[90:93]
	v_mfma_f32_16x16x32_bf16 v[54:57], v[164:167], v[200:203], v[54:57]
	v_mfma_f32_16x16x32_bf16 v[50:53], v[172:175], v[200:203], v[50:53]
	v_mfma_f32_16x16x32_bf16 v[22:25], v[164:167], v[212:215], v[22:25]
	v_mfma_f32_16x16x32_bf16 v[18:21], v[172:175], v[212:215], v[18:21]
	s_setprio 0
	s_barrier
	ds_read_b128 v[176:179], v140 offset:49152
	ds_read_b128 v[184:187], v140 offset:50176
	ds_read_b128 v[188:191], v140 offset:51200
	ds_read_b128 v[192:195], v140 offset:52224
	ds_read_b128 v[196:199], v140 offset:53248
	ds_read_b128 v[200:203], v140 offset:54272
	ds_read_b128 v[204:207], v140 offset:55296
	ds_read_b128 v[212:215], v140 offset:56320
	s_add_u32 s46, s52, 0x80
	s_addc_u32 s47, s53, 0
	s_mov_b32 m0, s64
	s_nop 0
	global_load_lds_dwordx4 v133, s[46:47]
	s_nop 0
	s_mov_b32 m0, s65
	s_nop 0
	global_load_lds_dwordx4 v135, s[46:47]
	s_add_u32 s46, s52, 0x80080
	s_addc_u32 s47, s53, 0
	s_mov_b32 m0, s68
	s_nop 0
	global_load_lds_dwordx4 v133, s[46:47]
	s_nop 0
	s_mov_b32 m0, s69
	s_nop 0
	global_load_lds_dwordx4 v135, s[46:47]
	s_nop 0
	s_waitcnt vmcnt(6)
	s_waitcnt lgkmcnt(0)
	s_barrier
	s_setprio 1
	s_waitcnt lgkmcnt(7)
	v_mfma_f32_16x16x32_bf16 v[86:89], v[144:147], v[176:179], v[86:89]
	v_mfma_f32_16x16x32_bf16 v[82:85], v[152:155], v[176:179], v[82:85]
	s_waitcnt lgkmcnt(5)
	v_mfma_f32_16x16x32_bf16 v[62:65], v[144:147], v[188:191], v[62:65]
	v_mfma_f32_16x16x32_bf16 v[58:61], v[152:155], v[188:191], v[58:61]
	s_waitcnt lgkmcnt(3)
	v_mfma_f32_16x16x32_bf16 v[34:37], v[144:147], v[196:199], v[34:37]
	v_mfma_f32_16x16x32_bf16 v[30:33], v[152:155], v[196:199], v[30:33]
	s_waitcnt lgkmcnt(1)
	v_mfma_f32_16x16x32_bf16 v[6:9], v[144:147], v[204:207], v[6:9]
	v_mfma_f32_16x16x32_bf16 v[2:5], v[152:155], v[204:207], v[2:5]
	v_mfma_f32_16x16x32_bf16 v[86:89], v[148:151], v[184:187], v[86:89]
	v_mfma_f32_16x16x32_bf16 v[82:85], v[156:159], v[184:187], v[82:85]
	v_mfma_f32_16x16x32_bf16 v[62:65], v[148:151], v[192:195], v[62:65]
	v_mfma_f32_16x16x32_bf16 v[58:61], v[156:159], v[192:195], v[58:61]
	v_mfma_f32_16x16x32_bf16 v[34:37], v[148:151], v[200:203], v[34:37]
	v_mfma_f32_16x16x32_bf16 v[30:33], v[156:159], v[200:203], v[30:33]
	s_waitcnt lgkmcnt(0)
	v_mfma_f32_16x16x32_bf16 v[6:9], v[148:151], v[212:215], v[6:9]
	v_mfma_f32_16x16x32_bf16 v[2:5], v[156:159], v[212:215], v[2:5]
	s_setprio 0
	s_setprio 1
	v_mfma_f32_16x16x32_bf16 v[102:105], v[160:163], v[176:179], v[102:105]
	v_mfma_f32_16x16x32_bf16 v[98:101], v[168:171], v[176:179], v[98:101]
	v_mfma_f32_16x16x32_bf16 v[74:77], v[160:163], v[188:191], v[74:77]
	v_mfma_f32_16x16x32_bf16 v[70:73], v[168:171], v[188:191], v[70:73]
	v_mfma_f32_16x16x32_bf16 v[46:49], v[160:163], v[196:199], v[46:49]
	v_mfma_f32_16x16x32_bf16 v[42:45], v[168:171], v[196:199], v[42:45]
	v_mfma_f32_16x16x32_bf16 v[14:17], v[160:163], v[204:207], v[14:17]
	v_mfma_f32_16x16x32_bf16 v[10:13], v[168:171], v[204:207], v[10:13]
	v_mfma_f32_16x16x32_bf16 v[102:105], v[164:167], v[184:187], v[102:105]
	v_mfma_f32_16x16x32_bf16 v[98:101], v[172:175], v[184:187], v[98:101]
	v_mfma_f32_16x16x32_bf16 v[74:77], v[164:167], v[192:195], v[74:77]
	v_mfma_f32_16x16x32_bf16 v[70:73], v[172:175], v[192:195], v[70:73]
	v_mfma_f32_16x16x32_bf16 v[46:49], v[164:167], v[200:203], v[46:49]
	v_mfma_f32_16x16x32_bf16 v[42:45], v[172:175], v[200:203], v[42:45]
	v_mfma_f32_16x16x32_bf16 v[14:17], v[164:167], v[212:215], v[14:17]
	v_mfma_f32_16x16x32_bf16 v[10:13], v[172:175], v[212:215], v[10:13]
	s_setprio 0
	s_barrier
	s_add_i32 s42, s42, 2
	s_add_u32 s38, s38, 0x100
	s_addc_u32 s39, s39, 0
	s_add_u32 s40, s40, 0x100
	s_addc_u32 s41, s41, 0
	s_cmp_gt_u32 s42, 29
	s_cbranch_scc0 .LBB0_168

;     __device__ __forceinline__ void a_ready(const Unit&) const { wait_cnt(w_ready, w_need); }
;     __device__ __forceinline__ void half_ready(const Unit& u) const { wait_cnt(g_ready + 64 * u.pm, g_need); }
; #define PG8_STAGE(bufoff, gbase, voff) do { _Pragma("unroll") for (int _i = 0; _i < 2; ++_i) \
;         asm volatile("s_mov_b32 m0, %0\n\ts_nop 0\n\tglobal_load_lds_dwordx4 %1, %2" :: "s"(ldsb + (unsigned)(bufoff) + ldsw + (unsigned)(_i * 8192)), "v"((voff)[_i]), "s"((const char*)(gbase)) : "memory", "m0"); } while (0)
; #define PG8_LDA(dst, b, h) do { _Pragma("unroll") for (int m = 0; m < 4; ++m) _Pragma("unroll") for (int k = 0; k < 2; ++k) dst[m][k] = *(const LAS bf16x8*)(lds + PG8_SA(b, h) + aoff + m * 2048 + k * 1024); } while (0)
; #define PG8_WAIT_V(n) asm volatile("s_waitcnt vmcnt(" #n ")" ::: "memory")
; #define PG8_WAIT_L(n) asm volatile("s_waitcnt lgkmcnt(" #n ")" ::: "memory")
; #define PG8_BAR __builtin_amdgcn_s_barrier()
; template <class Epi, class Sched>
; __device__ __forceinline__ void gemm_phase(LAS unsigned char* lds, const Gemm g, const Sched& S, const Epi& E) {
;     ...
;             const bool last = (t == nt - 2);
;             if (last && has_next) S.a_ready(nxt);
;             if constexpr (Sched::TWO_HALVES) { if (t == KSW - 2) S.half_ready(cur); }
;             const char* a1 = cA + PG8_KOFF(t + 1) * (long)kstep;
;             const char* a2 = last ? nA : cA + PG8_KOFF(t + 2) * (long)kstep; const char* b2 = last ? nB : cB + PG8_KOFF(t + 2) * (long)kstep;
;             const char* a3 = a2 + kstep; const char* b3 = b2 + kstep;
;             if constexpr (Epi::HAS_MID) { if (t == Epi::MID_T) E.mid(acc, cur, wr, wc, fr, fq); }
;             PG8_LDB(B0, 0, 0); PG8_LDB(B1, 0, 1); PG8_SCHED; PG8_LDA(At, 0, 0); PG8_STAGE(PG8_SA(1, 1), a1 + hstepA, voffA);
;             PG8_WAIT_V(8); PG8_WAIT_L(0); PG8_BAR; PG8_MMA(0, 0, At, B0); PG8_MMA(0, 1, At, B1); PG8_BAR; PG8_SCHED;
;             PG8_LDA(At, 0, 1); PG8_STAGE(PG8_SB(0, 0), b2, voffB); PG8_STAGE(PG8_SB(0, 1), b2 + hstepB, voffB); PG8_STAGE(PG8_SA(0, 0), a2, voffA);
;             PG8_WAIT_V(8); PG8_WAIT_L(0); PG8_BAR; PG8_BAR; PG8_SCHED;
;             PG8_LDB(B0, 1, 0); PG8_LDB(B1, 1, 1); PG8_SCHED; PG8_LDA(At, 1, 0); PG8_STAGE(PG8_SA(0, 1), a2 + hstepA, voffA);
;             PG8_WAIT_V(8); PG8_WAIT_L(0); PG8_BAR; PG8_MMA(0, 0, At, B0); PG8_MMA(0, 1, At, B1); PG8_BAR; PG8_SCHED;
.LBB0_177:
	ds_read_b128 v[2:5], v138
	ds_read_b128 v[6:9], v138 offset:1024
	ds_read_b128 v[10:13], v138 offset:2048
	ds_read_b128 v[14:17], v138 offset:3072
	ds_read_b128 v[30:33], v139
	ds_read_b128 v[34:37], v139 offset:1024
	ds_read_b128 v[42:45], v139 offset:2048
	ds_read_b128 v[46:49], v139 offset:3072
	s_cmp_eq_u32 s38, 28
	s_cselect_b32 s54, s15, s77
	s_cselect_b32 s55, s11, s78
	s_cselect_b32 s52, s74, s75
	s_cselect_b32 s53, s13, s76
	s_add_u32 s44, s54, 0x80
	s_addc_u32 s45, s55, 0
	ds_read_b128 v[58:61], v140
	ds_read_b128 v[62:65], v140 offset:1024
	ds_read_b128 v[70:73], v140 offset:2048
	ds_read_b128 v[74:77], v140 offset:3072
	ds_read_b128 v[82:85], v140 offset:4096
	ds_read_b128 v[86:89], v140 offset:5120
	ds_read_b128 v[98:101], v140 offset:6144
	ds_read_b128 v[102:105], v140 offset:7168
	s_add_u32 s40, s77, 0xffffff80
	s_addc_u32 s41, s78, -1
	s_mov_b32 m0, s66
	s_nop 0
	global_load_lds_dwordx4 v132, s[40:41]
	s_mov_b32 m0, s67
	s_nop 0
	global_load_lds_dwordx4 v134, s[40:41]
	s_add_u32 s40, s77, 0x7ff80
	s_addc_u32 s41, s78, 0
	s_mov_b32 m0, s70
	s_nop 0
	global_load_lds_dwordx4 v132, s[40:41]
	s_nop 0
	s_mov_b32 m0, s71
	s_nop 0
	global_load_lds_dwordx4 v134, s[40:41]
	s_waitcnt vmcnt(8)
	s_waitcnt lgkmcnt(0)
	s_barrier
	s_setprio 1
	s_waitcnt lgkmcnt(7)
	v_mfma_f32_16x16x32_bf16 v[122:125], v[2:5], v[58:61], v[122:125]
	v_mfma_f32_16x16x32_bf16 v[114:117], v[10:13], v[58:61], v[114:117]
	s_waitcnt lgkmcnt(5)
	v_mfma_f32_16x16x32_bf16 v[110:113], v[2:5], v[70:73], v[110:113]
	v_mfma_f32_16x16x32_bf16 v[106:109], v[10:13], v[70:73], v[106:109]
	s_waitcnt lgkmcnt(3)
	v_mfma_f32_16x16x32_bf16 v[78:81], v[2:5], v[82:85], v[78:81]
	v_mfma_f32_16x16x32_bf16 v[66:69], v[10:13], v[82:85], v[66:69]
	s_waitcnt lgkmcnt(1)
	v_mfma_f32_16x16x32_bf16 v[2:5], v[2:5], v[98:101], v[38:41]
	v_mfma_f32_16x16x32_bf16 v[122:125], v[6:9], v[62:65], v[122:125]
	v_mfma_f32_16x16x32_bf16 v[114:117], v[14:17], v[62:65], v[114:117]
	v_mfma_f32_16x16x32_bf16 v[110:113], v[6:9], v[74:77], v[110:113]
	v_mfma_f32_16x16x32_bf16 v[106:109], v[14:17], v[74:77], v[106:109]
	v_mfma_f32_16x16x32_bf16 v[78:81], v[6:9], v[86:89], v[78:81]
	v_mfma_f32_16x16x32_bf16 v[66:69], v[14:17], v[86:89], v[66:69]
	s_waitcnt lgkmcnt(0)
	v_mfma_f32_16x16x32_bf16 v[2:5], v[6:9], v[102:105], v[2:5]
	v_mfma_f32_16x16x32_bf16 v[6:9], v[10:13], v[98:101], v[26:29]
	v_mfma_f32_16x16x32_bf16 v[6:9], v[14:17], v[102:105], v[6:9]
	s_setprio 0
	s_setprio 1
	v_mfma_f32_16x16x32_bf16 v[26:29], v[30:33], v[70:73], v[94:97]
	v_mfma_f32_16x16x32_bf16 v[10:13], v[30:33], v[58:61], v[126:129]
	v_mfma_f32_16x16x32_bf16 v[14:17], v[42:45], v[58:61], v[118:121]
	v_mfma_f32_16x16x32_bf16 v[58:61], v[34:37], v[74:77], v[26:29]
	v_mfma_f32_16x16x32_bf16 v[26:29], v[42:45], v[70:73], v[90:93]
	v_mfma_f32_16x16x32_bf16 v[10:13], v[34:37], v[62:65], v[10:13]
	v_mfma_f32_16x16x32_bf16 v[14:17], v[46:49], v[62:65], v[14:17]
	v_mfma_f32_16x16x32_bf16 v[62:65], v[46:49], v[74:77], v[26:29]
	v_mfma_f32_16x16x32_bf16 v[26:29], v[30:33], v[82:85], v[54:57]
	v_mfma_f32_16x16x32_bf16 v[54:57], v[34:37], v[86:89], v[26:29]
	v_mfma_f32_16x16x32_bf16 v[26:29], v[42:45], v[82:85], v[50:53]
	v_mfma_f32_16x16x32_bf16 v[22:25], v[30:33], v[98:101], v[22:25]
	v_mfma_f32_16x16x32_bf16 v[18:21], v[42:45], v[98:101], v[18:21]
	v_mfma_f32_16x16x32_bf16 v[50:53], v[46:49], v[86:89], v[26:29]
	v_mfma_f32_16x16x32_bf16 v[22:25], v[34:37], v[102:105], v[22:25]
	v_mfma_f32_16x16x32_bf16 v[18:21], v[46:49], v[102:105], v[18:21]
	s_setprio 0
	s_barrier
	s_mov_b32 m0, s57
	s_nop 0
	global_load_lds_dwordx4 v133, s[52:53]
	s_add_u32 s40, s52, 0x80000
	s_mov_b32 m0, s58
	s_nop 0
	global_load_lds_dwordx4 v135, s[52:53]
	s_addc_u32 s41, s53, 0
	s_mov_b32 m0, s59
	s_nop 0
	global_load_lds_dwordx4 v133, s[40:41]
	s_nop 0
	s_mov_b32 m0, s60
	s_nop 0
	global_load_lds_dwordx4 v135, s[40:41]
	s_nop 0
	s_waitcnt vmcnt(6)
	s_waitcnt lgkmcnt(0)
	s_barrier
	s_barrier
	ds_read_b128 v[26:29], v141
	ds_read_b128 v[30:33], v141 offset:1024
	ds_read_b128 v[34:37], v141 offset:2048
	ds_read_b128 v[42:45], v141 offset:3072
	ds_read_b128 v[46:49], v142
	ds_read_b128 v[70:73], v142 offset:1024
	ds_read_b128 v[74:77], v142 offset:2048
	ds_read_b128 v[82:85], v142 offset:3072
	ds_read_b128 v[86:89], v140 offset:32768
	ds_read_b128 v[90:93], v140 offset:33792
	ds_read_b128 v[98:101], v140 offset:34816
	ds_read_b128 v[102:105], v140 offset:35840
	ds_read_b128 v[144:147], v140 offset:36864
	ds_read_b128 v[148:151], v140 offset:37888
	ds_read_b128 v[152:155], v140 offset:38912
	ds_read_b128 v[156:159], v140 offset:39936
	s_mov_b32 m0, s56
	s_nop 0
	global_load_lds_dwordx4 v132, s[54:55]
	s_mov_b32 m0, s61
	s_nop 0
	global_load_lds_dwordx4 v134, s[54:55]
	s_add_u32 s40, s54, 0x80000
	s_addc_u32 s41, s55, 0
	s_mov_b32 m0, s62
	s_nop 0
	global_load_lds_dwordx4 v132, s[40:41]
	s_nop 0
	s_mov_b32 m0, s63
	s_nop 0
	global_load_lds_dwordx4 v134, s[40:41]
	s_waitcnt vmcnt(8)
	s_waitcnt lgkmcnt(0)
	s_barrier
; #define PG8_STAGE(bufoff, gbase, voff) do { _Pragma("unroll") for (int _i = 0; _i < 2; ++_i) \
;         asm volatile("s_mov_b32 m0, %0\n\ts_nop 0\n\tglobal_load_lds_dwordx4 %1, %2" :: "s"(ldsb + (unsigned)(bufoff) + ldsw + (unsigned)(_i * 8192)), "v"((voff)[_i]), "s"((const char*)(gbase)) : "memory", "m0"); } while (0)
; #define PG8_LDA(dst, b, h) do { _Pragma("unroll") for (int m = 0; m < 4; ++m) _Pragma("unroll") for (int k = 0; k < 2; ++k) dst[m][k] = *(const LAS bf16x8*)(lds + PG8_SA(b, h) + aoff + m * 2048 + k * 1024); } while (0)
; #define PG8_MMA(ai, bj, At, Bt) do { __builtin_amdgcn_s_setprio(1); _Pragma("unroll") for (int m = 0; m < 4; ++m) _Pragma("unroll") for (int n = 0; n < 2; ++n) _Pragma("unroll") for (int k = 0; k < 2; ++k) \
;         acc[ai][bj][m][n] = __builtin_amdgcn_mfma_f32_16x16x32_bf16(Bt[n][k], At[m][k], acc[ai][bj][m][n], 0, 0, 0); __builtin_amdgcn_s_setprio(0); } while (0)
; #define PG8_WAIT_V(n) asm volatile("s_waitcnt vmcnt(" #n ")" ::: "memory")
; #define PG8_WAIT_L(n) asm volatile("s_waitcnt lgkmcnt(" #n ")" ::: "memory")
; #define PG8_BAR __builtin_amdgcn_s_barrier()
; #define PG8_SCHED __builtin_amdgcn_sched_barrier(0)
; template <class Epi, class Sched>
; __device__ __forceinline__ void gemm_phase(LAS unsigned char* lds, const Gemm g, const Sched& S, const Epi& E) {
;     ...
;             PG8_WAIT_V(8); PG8_WAIT_L(0); PG8_BAR; PG8_MMA(0, 0, At, B0); PG8_MMA(0, 1, At, B1); PG8_BAR; PG8_SCHED;
;             PG8_LDA(At, 1, 1); PG8_STAGE(PG8_SB(1, 0), b3, voffB); PG8_STAGE(PG8_SB(1, 1), b3 + hstepB, voffB); PG8_STAGE(PG8_SA(1, 0), a3, voffA);
;             PG8_WAIT_V(8); PG8_WAIT_L(0); PG8_BAR; PG8_BAR; PG8_SCHED;
;         }
;     ...
;         for (int a = 0; a < 2; ++a)
; #pragma unroll
;             for (int b = 0; b < 2; ++b)
; #pragma unroll
;                 for (int m = 0; m < 4; ++m)
; #pragma unroll
;                     for (int n = 0; n < 2; ++n) acc[a][b][m][n] = (f32x4){0.f, 0.f, 0.f, 0.f};
	s_setprio 1
	s_waitcnt lgkmcnt(7)
	v_mfma_f32_16x16x32_bf16 v[38:41], v[26:29], v[86:89], v[122:125]
	s_waitcnt lgkmcnt(6)
	v_mfma_f32_16x16x32_bf16 v[122:125], v[30:33], v[90:93], v[38:41]
	v_mfma_f32_16x16x32_bf16 v[38:41], v[34:37], v[86:89], v[114:117]
	v_mfma_f32_16x16x32_bf16 v[114:117], v[42:45], v[90:93], v[38:41]
	s_waitcnt lgkmcnt(5)
	v_mfma_f32_16x16x32_bf16 v[38:41], v[26:29], v[98:101], v[110:113]
	s_waitcnt lgkmcnt(4)
	v_mfma_f32_16x16x32_bf16 v[110:113], v[30:33], v[102:105], v[38:41]
	v_mfma_f32_16x16x32_bf16 v[38:41], v[34:37], v[98:101], v[106:109]
	v_mfma_f32_16x16x32_bf16 v[106:109], v[42:45], v[102:105], v[38:41]
	s_waitcnt lgkmcnt(3)
	v_mfma_f32_16x16x32_bf16 v[38:41], v[26:29], v[144:147], v[78:81]
	s_waitcnt lgkmcnt(2)
	v_mfma_f32_16x16x32_bf16 v[78:81], v[30:33], v[148:151], v[38:41]
	v_mfma_f32_16x16x32_bf16 v[38:41], v[34:37], v[144:147], v[66:69]
	s_waitcnt lgkmcnt(1)
	v_mfma_f32_16x16x32_bf16 v[2:5], v[26:29], v[152:155], v[2:5]
	v_mfma_f32_16x16x32_bf16 v[66:69], v[42:45], v[148:151], v[38:41]
	s_waitcnt lgkmcnt(0)
	v_mfma_f32_16x16x32_bf16 v[38:41], v[30:33], v[156:159], v[2:5]
	v_mfma_f32_16x16x32_bf16 v[2:5], v[34:37], v[152:155], v[6:9]
	v_mfma_f32_16x16x32_bf16 v[26:29], v[42:45], v[156:159], v[2:5]
	s_setprio 0
	s_setprio 1
	v_mfma_f32_16x16x32_bf16 v[2:5], v[46:49], v[86:89], v[10:13]
	v_mfma_f32_16x16x32_bf16 v[126:129], v[70:73], v[90:93], v[2:5]
	v_mfma_f32_16x16x32_bf16 v[2:5], v[74:77], v[86:89], v[14:17]
	v_mfma_f32_16x16x32_bf16 v[118:121], v[82:85], v[90:93], v[2:5]
	v_mfma_f32_16x16x32_bf16 v[2:5], v[46:49], v[98:101], v[58:61]
	v_mfma_f32_16x16x32_bf16 v[94:97], v[70:73], v[102:105], v[2:5]
	v_mfma_f32_16x16x32_bf16 v[2:5], v[74:77], v[98:101], v[62:65]
	v_mfma_f32_16x16x32_bf16 v[90:93], v[82:85], v[102:105], v[2:5]
	v_mfma_f32_16x16x32_bf16 v[2:5], v[46:49], v[144:147], v[54:57]
	v_mfma_f32_16x16x32_bf16 v[54:57], v[70:73], v[148:151], v[2:5]
	v_mfma_f32_16x16x32_bf16 v[2:5], v[74:77], v[144:147], v[50:53]
	v_mfma_f32_16x16x32_bf16 v[50:53], v[82:85], v[148:151], v[2:5]
	v_mfma_f32_16x16x32_bf16 v[2:5], v[46:49], v[152:155], v[22:25]
	v_mfma_f32_16x16x32_bf16 v[22:25], v[70:73], v[156:159], v[2:5]
	v_mfma_f32_16x16x32_bf16 v[2:5], v[74:77], v[152:155], v[18:21]
	v_mfma_f32_16x16x32_bf16 v[18:21], v[82:85], v[156:159], v[2:5]
	s_setprio 0
	s_barrier
	s_add_u32 s40, s52, 0x80
	s_addc_u32 s41, s53, 0
	s_mov_b32 m0, s64
	s_nop 0
	global_load_lds_dwordx4 v133, s[40:41]
	s_nop 0
	s_mov_b32 m0, s65
	s_nop 0
	global_load_lds_dwordx4 v135, s[40:41]
	s_add_u32 s40, s52, 0x80080
	s_addc_u32 s41, s53, 0
	s_mov_b32 m0, s68
	s_nop 0
	global_load_lds_dwordx4 v133, s[40:41]
	s_nop 0
	s_mov_b32 m0, s69
	s_nop 0
	global_load_lds_dwordx4 v135, s[40:41]
	s_nop 0
	s_waitcnt vmcnt(6)
	s_waitcnt lgkmcnt(0)
	s_barrier
	s_barrier
	s_add_i32 s38, s38, 2
	s_add_u32 s77, s77, 0x100
	s_addc_u32 s78, s78, 0
	s_add_u32 s75, s75, 0x100
	s_addc_u32 s76, s76, 0
	s_cmp_gt_u32 s38, 29
	s_cbranch_scc0 .LBB0_177
	v_mov_b32_e32 v89, 0
	v_mov_b32_e32 v88, v89
	v_mov_b32_e32 v87, v89
	v_mov_b32_e32 v86, v89
	v_mov_b32_e32 v85, v89
	v_mov_b32_e32 v84, v89
	v_mov_b32_e32 v83, v89
	v_mov_b32_e32 v82, v89
	v_mov_b32_e32 v65, v89
	v_mov_b32_e32 v64, v89
	v_mov_b32_e32 v63, v89
	v_mov_b32_e32 v62, v89
	v_mov_b32_e32 v61, v89
	v_mov_b32_e32 v60, v89
	v_mov_b32_e32 v59, v89
	v_mov_b32_e32 v58, v89
	v_mov_b32_e32 v37, v89
	v_mov_b32_e32 v36, v89
	v_mov_b32_e32 v35, v89
	v_mov_b32_e32 v34, v89
	v_mov_b32_e32 v33, v89
	v_mov_b32_e32 v32, v89
	v_mov_b32_e32 v31, v89
	v_mov_b32_e32 v30, v89
	v_mov_b32_e32 v9, v89
	v_mov_b32_e32 v8, v89
	v_mov_b32_e32 v7, v89
	v_mov_b32_e32 v6, v89
	v_mov_b32_e32 v5, v89
	v_mov_b32_e32 v4, v89
	v_mov_b32_e32 v3, v89
	v_mov_b32_e32 v2, v89
	v_mov_b32_e32 v105, v89
	v_mov_b32_e32 v104, v89
	v_mov_b32_e32 v103, v89
	v_mov_b32_e32 v102, v89
	v_mov_b32_e32 v101, v89
	v_mov_b32_e32 v100, v89
	v_mov_b32_e32 v99, v89
	v_mov_b32_e32 v98, v89
	v_mov_b32_e32 v77, v89
	v_mov_b32_e32 v76, v89
	v_mov_b32_e32 v75, v89
	v_mov_b32_e32 v74, v89
	v_mov_b32_e32 v73, v89
	v_mov_b32_e32 v72, v89
	v_mov_b32_e32 v71, v89
	v_mov_b32_e32 v70, v89
	v_mov_b32_e32 v49, v89
	v_mov_b32_e32 v48, v89
	v_mov_b32_e32 v47, v89
	v_mov_b32_e32 v46, v89
	v_mov_b32_e32 v45, v89
	v_mov_b32_e32 v44, v89
	v_mov_b32_e32 v43, v89
	v_mov_b32_e32 v42, v89
	v_mov_b32_e32 v17, v89
	v_mov_b32_e32 v16, v89
	v_mov_b32_e32 v15, v89
	v_mov_b32_e32 v14, v89
	v_mov_b32_e32 v13, v89
	v_mov_b32_e32 v12, v89
	v_mov_b32_e32 v11, v89
	v_mov_b32_e32 v10, v89
	s_andn2_b64 vcc, exec, s[8:9]
	s_cbranch_vccz .LBB0_171
	s_branch .LBB0_172

;     __device__ __forceinline__ void a_ready(const Unit&) const { wait_cnt(w_ready, w_need); }
;     __device__ __forceinline__ void half_ready(const Unit& u) const { wait_cnt(g_ready + 64 * u.pm, g_need); }
; #define PG8_STAGE(bufoff, gbase, voff) do { _Pragma("unroll") for (int _i = 0; _i < 2; ++_i) \
;         asm volatile("s_mov_b32 m0, %0\n\ts_nop 0\n\tglobal_load_lds_dwordx4 %1, %2" :: "s"(ldsb + (unsigned)(bufoff) + ldsw + (unsigned)(_i * 8192)), "v"((voff)[_i]), "s"((const char*)(gbase)) : "memory", "m0"); } while (0)
; #define PG8_LDA(dst, b, h) do { _Pragma("unroll") for (int m = 0; m < 4; ++m) _Pragma("unroll") for (int k = 0; k < 2; ++k) dst[m][k] = *(const LAS bf16x8*)(lds + PG8_SA(b, h) + aoff + m * 2048 + k * 1024); } while (0)
; #define PG8_LDB(dst, b, h) do { _Pragma("unroll") for (int n = 0; n < 2; ++n) _Pragma("unroll") for (int k = 0; k < 2; ++k) dst[n][k] = *(const LAS bf16x8*)(lds + PG8_SB(b, h) + boff + n * 2048 + k * 1024); } while (0)
; #define PG8_WAIT_V(n) asm volatile("s_waitcnt vmcnt(" #n ")" ::: "memory")
; #define PG8_WAIT_L(n) asm volatile("s_waitcnt lgkmcnt(" #n ")" ::: "memory")
; #define PG8_BAR __builtin_amdgcn_s_barrier()
; #define PG8_SCHED __builtin_amdgcn_sched_barrier(0)
; template <class Epi, class Sched>
; __device__ __forceinline__ void gemm_phase(LAS unsigned char* lds, const Gemm g, const Sched& S, const Epi& E) {
;     ...
;             const bool last = (t == nt - 2);
;             if (last && has_next) S.a_ready(nxt);
;             if constexpr (Sched::TWO_HALVES) { if (t == KSW - 2) S.half_ready(cur); }
;             const char* a1 = cA + PG8_KOFF(t + 1) * (long)kstep;
;             const char* a2 = last ? nA : cA + PG8_KOFF(t + 2) * (long)kstep; const char* b2 = last ? nB : cB + PG8_KOFF(t + 2) * (long)kstep;
;             const char* a3 = a2 + kstep; const char* b3 = b2 + kstep;
;             if constexpr (Epi::HAS_MID) { if (t == Epi::MID_T) E.mid(acc, cur, wr, wc, fr, fq); }
;             PG8_LDB(B0, 0, 0); PG8_LDB(B1, 0, 1); PG8_SCHED; PG8_LDA(At, 0, 0); PG8_STAGE(PG8_SA(1, 1), a1 + hstepA, voffA);
;             PG8_WAIT_V(8); PG8_WAIT_L(0); PG8_BAR; PG8_MMA(0, 0, At, B0); PG8_MMA(0, 1, At, B1); PG8_BAR; PG8_SCHED;
;             PG8_LDA(At, 0, 1); PG8_STAGE(PG8_SB(0, 0), b2, voffB); PG8_STAGE(PG8_SB(0, 1), b2 + hstepB, voffB); PG8_STAGE(PG8_SA(0, 0), a2, voffA);
.LBB0_247:
	ds_read_b128 v[134:137], v189
	ds_read_b128 v[138:141], v189 offset:1024
	ds_read_b128 v[142:145], v189 offset:2048
	ds_read_b128 v[146:149], v189 offset:3072
	ds_read_b128 v[150:153], v190
	ds_read_b128 v[154:157], v190 offset:1024
	ds_read_b128 v[158:161], v190 offset:2048
	ds_read_b128 v[162:165], v190 offset:3072
	s_add_i32 s43, s42, 2
	s_cmp_eq_u32 s37, s42
	s_cselect_b32 s56, s4, s38
	s_cselect_b32 s57, s5, s39
	s_cselect_b32 s54, s30, s40
	s_cselect_b32 s55, s31, s41
	s_add_u32 s52, s56, 0x80
	s_addc_u32 s53, s57, 0
	ds_read_b128 v[166:169], v191
	ds_read_b128 v[170:173], v191 offset:1024
	ds_read_b128 v[174:177], v191 offset:2048
	ds_read_b128 v[178:181], v191 offset:3072
	ds_read_b128 v[196:199], v191 offset:4096
	ds_read_b128 v[200:203], v191 offset:5120
	ds_read_b128 v[204:207], v191 offset:6144
	ds_read_b128 v[212:215], v191 offset:7168
	s_add_u32 s46, s38, 0xffffff80
	s_addc_u32 s47, s39, -1
	s_mov_b32 m0, s64
	s_nop 0
	global_load_lds_dwordx4 v183, s[46:47]
	s_mov_b32 m0, s65
	s_nop 0
	global_load_lds_dwordx4 v185, s[46:47]
	s_add_u32 s46, s38, 0x15ff80
	s_addc_u32 s47, s39, 0
	s_mov_b32 m0, s68
	s_nop 0
	global_load_lds_dwordx4 v183, s[46:47]
	s_nop 0
	s_mov_b32 m0, s69
	s_nop 0
	global_load_lds_dwordx4 v185, s[46:47]
	s_waitcnt vmcnt(8)
	s_waitcnt lgkmcnt(0)
	s_barrier
	s_setprio 1
	s_waitcnt lgkmcnt(7)
	v_mfma_f32_16x16x32_bf16 v[62:65], v[134:137], v[166:169], v[62:65]
	v_mfma_f32_16x16x32_bf16 v[58:61], v[142:145], v[166:169], v[58:61]
	s_waitcnt lgkmcnt(5)
	v_mfma_f32_16x16x32_bf16 v[54:57], v[134:137], v[174:177], v[54:57]
	v_mfma_f32_16x16x32_bf16 v[50:53], v[142:145], v[174:177], v[50:53]
	s_waitcnt lgkmcnt(3)
	v_mfma_f32_16x16x32_bf16 v[46:49], v[134:137], v[196:199], v[46:49]
	v_mfma_f32_16x16x32_bf16 v[38:41], v[142:145], v[196:199], v[38:41]
	s_waitcnt lgkmcnt(1)
	v_mfma_f32_16x16x32_bf16 v[30:33], v[134:137], v[204:207], v[30:33]
	v_mfma_f32_16x16x32_bf16 v[22:25], v[142:145], v[204:207], v[22:25]
	v_mfma_f32_16x16x32_bf16 v[62:65], v[138:141], v[170:173], v[62:65]
	v_mfma_f32_16x16x32_bf16 v[58:61], v[146:149], v[170:173], v[58:61]
	v_mfma_f32_16x16x32_bf16 v[54:57], v[138:141], v[178:181], v[54:57]
	v_mfma_f32_16x16x32_bf16 v[50:53], v[146:149], v[178:181], v[50:53]
	v_mfma_f32_16x16x32_bf16 v[46:49], v[138:141], v[200:203], v[46:49]
	v_mfma_f32_16x16x32_bf16 v[38:41], v[146:149], v[200:203], v[38:41]
	s_waitcnt lgkmcnt(0)
	v_mfma_f32_16x16x32_bf16 v[30:33], v[138:141], v[212:215], v[30:33]
	v_mfma_f32_16x16x32_bf16 v[22:25], v[146:149], v[212:215], v[22:25]
	s_setprio 0
	s_setprio 1
	v_mfma_f32_16x16x32_bf16 v[42:45], v[150:153], v[166:169], v[42:45]
	v_mfma_f32_16x16x32_bf16 v[34:37], v[158:161], v[166:169], v[34:37]
	v_mfma_f32_16x16x32_bf16 v[26:29], v[150:153], v[174:177], v[26:29]
	v_mfma_f32_16x16x32_bf16 v[18:21], v[158:161], v[174:177], v[18:21]
	v_mfma_f32_16x16x32_bf16 v[14:17], v[150:153], v[196:199], v[14:17]
	v_mfma_f32_16x16x32_bf16 v[10:13], v[158:161], v[196:199], v[10:13]
	v_mfma_f32_16x16x32_bf16 v[6:9], v[150:153], v[204:207], v[6:9]
	v_mfma_f32_16x16x32_bf16 v[2:5], v[158:161], v[204:207], v[2:5]
	v_mfma_f32_16x16x32_bf16 v[42:45], v[154:157], v[170:173], v[42:45]
	v_mfma_f32_16x16x32_bf16 v[34:37], v[162:165], v[170:173], v[34:37]
	v_mfma_f32_16x16x32_bf16 v[26:29], v[154:157], v[178:181], v[26:29]
	v_mfma_f32_16x16x32_bf16 v[18:21], v[162:165], v[178:181], v[18:21]
	v_mfma_f32_16x16x32_bf16 v[14:17], v[154:157], v[200:203], v[14:17]
	v_mfma_f32_16x16x32_bf16 v[10:13], v[162:165], v[200:203], v[10:13]
	v_mfma_f32_16x16x32_bf16 v[6:9], v[154:157], v[212:215], v[6:9]
	v_mfma_f32_16x16x32_bf16 v[2:5], v[162:165], v[212:215], v[2:5]
	s_setprio 0
	s_barrier
	ds_read_b128 v[166:169], v191 offset:16384
	ds_read_b128 v[170:173], v191 offset:17408
	ds_read_b128 v[174:177], v191 offset:18432
	ds_read_b128 v[178:181], v191 offset:19456
	ds_read_b128 v[196:199], v191 offset:20480
	ds_read_b128 v[200:203], v191 offset:21504
	ds_read_b128 v[204:207], v191 offset:22528
	ds_read_b128 v[212:215], v191 offset:23552
	s_mov_b32 m0, s29
	s_nop 0
	global_load_lds_dwordx4 v184, s[54:55]
	s_add_u32 s46, s54, 0x160000
	s_mov_b32 m0, s34
	s_nop 0
	global_load_lds_dwordx4 v186, s[54:55]
	s_addc_u32 s47, s55, 0
	s_mov_b32 m0, s35
	s_nop 0
	global_load_lds_dwordx4 v184, s[46:47]
	s_nop 0
	s_mov_b32 m0, s58
	s_nop 0
	global_load_lds_dwordx4 v186, s[46:47]
	s_nop 0
	s_waitcnt vmcnt(6)
	s_waitcnt lgkmcnt(0)
	s_barrier
; #define PG8_STAGE(bufoff, gbase, voff) do { _Pragma("unroll") for (int _i = 0; _i < 2; ++_i) \
;         asm volatile("s_mov_b32 m0, %0\n\ts_nop 0\n\tglobal_load_lds_dwordx4 %1, %2" :: "s"(ldsb + (unsigned)(bufoff) + ldsw + (unsigned)(_i * 8192)), "v"((voff)[_i]), "s"((const char*)(gbase)) : "memory", "m0"); } while (0)
; #define PG8_LDA(dst, b, h) do { _Pragma("unroll") for (int m = 0; m < 4; ++m) _Pragma("unroll") for (int k = 0; k < 2; ++k) dst[m][k] = *(const LAS bf16x8*)(lds + PG8_SA(b, h) + aoff + m * 2048 + k * 1024); } while (0)
; #define PG8_LDB(dst, b, h) do { _Pragma("unroll") for (int n = 0; n < 2; ++n) _Pragma("unroll") for (int k = 0; k < 2; ++k) dst[n][k] = *(const LAS bf16x8*)(lds + PG8_SB(b, h) + boff + n * 2048 + k * 1024); } while (0)
; #define PG8_MMA(ai, bj, At, Bt) do { __builtin_amdgcn_s_setprio(1); _Pragma("unroll") for (int m = 0; m < 4; ++m) _Pragma("unroll") for (int n = 0; n < 2; ++n) _Pragma("unroll") for (int k = 0; k < 2; ++k) \
;         acc[ai][bj][m][n] = __builtin_amdgcn_mfma_f32_16x16x32_bf16(Bt[n][k], At[m][k], acc[ai][bj][m][n], 0, 0, 0); __builtin_amdgcn_s_setprio(0); } while (0)
; #define PG8_WAIT_V(n) asm volatile("s_waitcnt vmcnt(" #n ")" ::: "memory")
; #define PG8_WAIT_L(n) asm volatile("s_waitcnt lgkmcnt(" #n ")" ::: "memory")
; #define PG8_BAR __builtin_amdgcn_s_barrier()
; #define PG8_SCHED __builtin_amdgcn_sched_barrier(0)
; template <class Epi, class Sched>
; __device__ __forceinline__ void gemm_phase(LAS unsigned char* lds, const Gemm g, const Sched& S, const Epi& E) {
;     ...
;             PG8_WAIT_V(8); PG8_WAIT_L(0); PG8_BAR; PG8_MMA(1, 0, At, B0); PG8_MMA(1, 1, At, B1); PG8_BAR; PG8_SCHED;
;             PG8_LDB(B0, 1, 0); PG8_LDB(B1, 1, 1); PG8_SCHED; PG8_LDA(At, 1, 0); PG8_STAGE(PG8_SA(0, 1), a2 + hstepA, voffA);
;             PG8_WAIT_V(8); PG8_WAIT_L(0); PG8_BAR; PG8_MMA(0, 0, At, B0); PG8_MMA(0, 1, At, B1); PG8_BAR; PG8_SCHED;
	s_setprio 1
	s_waitcnt lgkmcnt(7)
	v_mfma_f32_16x16x32_bf16 v[126:129], v[134:137], v[166:169], v[126:129]
	v_mfma_f32_16x16x32_bf16 v[122:125], v[142:145], v[166:169], v[122:125]
	s_waitcnt lgkmcnt(5)
	v_mfma_f32_16x16x32_bf16 v[118:121], v[134:137], v[174:177], v[118:121]
	v_mfma_f32_16x16x32_bf16 v[114:117], v[142:145], v[174:177], v[114:117]
	s_waitcnt lgkmcnt(3)
	v_mfma_f32_16x16x32_bf16 v[106:109], v[134:137], v[196:199], v[106:109]
	v_mfma_f32_16x16x32_bf16 v[98:101], v[142:145], v[196:199], v[98:101]
	s_waitcnt lgkmcnt(1)
	v_mfma_f32_16x16x32_bf16 v[90:93], v[134:137], v[204:207], v[90:93]
	v_mfma_f32_16x16x32_bf16 v[82:85], v[142:145], v[204:207], v[82:85]
	v_mfma_f32_16x16x32_bf16 v[126:129], v[138:141], v[170:173], v[126:129]
	v_mfma_f32_16x16x32_bf16 v[122:125], v[146:149], v[170:173], v[122:125]
	v_mfma_f32_16x16x32_bf16 v[118:121], v[138:141], v[178:181], v[118:121]
	v_mfma_f32_16x16x32_bf16 v[114:117], v[146:149], v[178:181], v[114:117]
	v_mfma_f32_16x16x32_bf16 v[106:109], v[138:141], v[200:203], v[106:109]
	v_mfma_f32_16x16x32_bf16 v[98:101], v[146:149], v[200:203], v[98:101]
	s_waitcnt lgkmcnt(0)
	v_mfma_f32_16x16x32_bf16 v[90:93], v[138:141], v[212:215], v[90:93]
	v_mfma_f32_16x16x32_bf16 v[82:85], v[146:149], v[212:215], v[82:85]
	s_setprio 0
	s_setprio 1
	v_mfma_f32_16x16x32_bf16 v[110:113], v[150:153], v[166:169], v[110:113]
	v_mfma_f32_16x16x32_bf16 v[102:105], v[158:161], v[166:169], v[102:105]
	v_mfma_f32_16x16x32_bf16 v[94:97], v[150:153], v[174:177], v[94:97]
	v_mfma_f32_16x16x32_bf16 v[86:89], v[158:161], v[174:177], v[86:89]
	v_mfma_f32_16x16x32_bf16 v[78:81], v[150:153], v[196:199], v[78:81]
	v_mfma_f32_16x16x32_bf16 v[74:77], v[158:161], v[196:199], v[74:77]
	v_mfma_f32_16x16x32_bf16 v[70:73], v[150:153], v[204:207], v[70:73]
	v_mfma_f32_16x16x32_bf16 v[66:69], v[158:161], v[204:207], v[66:69]
	v_mfma_f32_16x16x32_bf16 v[110:113], v[154:157], v[170:173], v[110:113]
	v_mfma_f32_16x16x32_bf16 v[102:105], v[162:165], v[170:173], v[102:105]
	v_mfma_f32_16x16x32_bf16 v[94:97], v[154:157], v[178:181], v[94:97]
	v_mfma_f32_16x16x32_bf16 v[86:89], v[162:165], v[178:181], v[86:89]
	v_mfma_f32_16x16x32_bf16 v[78:81], v[154:157], v[200:203], v[78:81]
	v_mfma_f32_16x16x32_bf16 v[74:77], v[162:165], v[200:203], v[74:77]
	v_mfma_f32_16x16x32_bf16 v[70:73], v[154:157], v[212:215], v[70:73]
	v_mfma_f32_16x16x32_bf16 v[66:69], v[162:165], v[212:215], v[66:69]
	s_setprio 0
	s_barrier
	ds_read_b128 v[134:137], v192
	ds_read_b128 v[138:141], v192 offset:1024
	ds_read_b128 v[142:145], v192 offset:2048
	ds_read_b128 v[146:149], v192 offset:3072
	ds_read_b128 v[150:153], v193
	ds_read_b128 v[154:157], v193 offset:1024
	ds_read_b128 v[158:161], v193 offset:2048
	ds_read_b128 v[162:165], v193 offset:3072
	ds_read_b128 v[166:169], v191 offset:32768
	ds_read_b128 v[170:173], v191 offset:33792
	ds_read_b128 v[174:177], v191 offset:34816
	ds_read_b128 v[178:181], v191 offset:35840
	ds_read_b128 v[196:199], v191 offset:36864
	ds_read_b128 v[200:203], v191 offset:37888
	ds_read_b128 v[204:207], v191 offset:38912
	ds_read_b128 v[212:215], v191 offset:39936
	s_mov_b32 m0, s28
	s_nop 0
	global_load_lds_dwordx4 v183, s[56:57]
	s_mov_b32 m0, s59
	s_nop 0
	global_load_lds_dwordx4 v185, s[56:57]
	s_add_u32 s46, s56, 0x160000
	s_addc_u32 s47, s57, 0
	s_mov_b32 m0, s60
	s_nop 0
	global_load_lds_dwordx4 v183, s[46:47]
	s_nop 0
	s_mov_b32 m0, s61
	s_nop 0
	global_load_lds_dwordx4 v185, s[46:47]
	s_waitcnt vmcnt(8)
	s_waitcnt lgkmcnt(0)
	s_barrier
	s_setprio 1
	s_waitcnt lgkmcnt(7)
	v_mfma_f32_16x16x32_bf16 v[62:65], v[134:137], v[166:169], v[62:65]
	v_mfma_f32_16x16x32_bf16 v[58:61], v[142:145], v[166:169], v[58:61]
	s_waitcnt lgkmcnt(5)
	v_mfma_f32_16x16x32_bf16 v[54:57], v[134:137], v[174:177], v[54:57]
	v_mfma_f32_16x16x32_bf16 v[50:53], v[142:145], v[174:177], v[50:53]
	s_waitcnt lgkmcnt(3)
	v_mfma_f32_16x16x32_bf16 v[46:49], v[134:137], v[196:199], v[46:49]
	v_mfma_f32_16x16x32_bf16 v[38:41], v[142:145], v[196:199], v[38:41]
	s_waitcnt lgkmcnt(1)
	v_mfma_f32_16x16x32_bf16 v[30:33], v[134:137], v[204:207], v[30:33]
	v_mfma_f32_16x16x32_bf16 v[22:25], v[142:145], v[204:207], v[22:25]
	v_mfma_f32_16x16x32_bf16 v[62:65], v[138:141], v[170:173], v[62:65]
	v_mfma_f32_16x16x32_bf16 v[58:61], v[146:149], v[170:173], v[58:61]
	v_mfma_f32_16x16x32_bf16 v[54:57], v[138:141], v[178:181], v[54:57]
	v_mfma_f32_16x16x32_bf16 v[50:53], v[146:149], v[178:181], v[50:53]
	v_mfma_f32_16x16x32_bf16 v[46:49], v[138:141], v[200:203], v[46:49]
	v_mfma_f32_16x16x32_bf16 v[38:41], v[146:149], v[200:203], v[38:41]
	s_waitcnt lgkmcnt(0)
	v_mfma_f32_16x16x32_bf16 v[30:33], v[138:141], v[212:215], v[30:33]
	v_mfma_f32_16x16x32_bf16 v[22:25], v[146:149], v[212:215], v[22:25]
	s_setprio 0
	s_setprio 1
	v_mfma_f32_16x16x32_bf16 v[42:45], v[150:153], v[166:169], v[42:45]
	v_mfma_f32_16x16x32_bf16 v[34:37], v[158:161], v[166:169], v[34:37]
	v_mfma_f32_16x16x32_bf16 v[26:29], v[150:153], v[174:177], v[26:29]
	v_mfma_f32_16x16x32_bf16 v[18:21], v[158:161], v[174:177], v[18:21]
	v_mfma_f32_16x16x32_bf16 v[14:17], v[150:153], v[196:199], v[14:17]
	v_mfma_f32_16x16x32_bf16 v[10:13], v[158:161], v[196:199], v[10:13]
	v_mfma_f32_16x16x32_bf16 v[6:9], v[150:153], v[204:207], v[6:9]
	v_mfma_f32_16x16x32_bf16 v[2:5], v[158:161], v[204:207], v[2:5]
	v_mfma_f32_16x16x32_bf16 v[42:45], v[154:157], v[170:173], v[42:45]
	v_mfma_f32_16x16x32_bf16 v[34:37], v[162:165], v[170:173], v[34:37]
	v_mfma_f32_16x16x32_bf16 v[26:29], v[154:157], v[178:181], v[26:29]
	v_mfma_f32_16x16x32_bf16 v[18:21], v[162:165], v[178:181], v[18:21]
	v_mfma_f32_16x16x32_bf16 v[14:17], v[154:157], v[200:203], v[14:17]
	v_mfma_f32_16x16x32_bf16 v[10:13], v[162:165], v[200:203], v[10:13]
	v_mfma_f32_16x16x32_bf16 v[6:9], v[154:157], v[212:215], v[6:9]
	v_mfma_f32_16x16x32_bf16 v[2:5], v[162:165], v[212:215], v[2:5]
	s_setprio 0
	s_barrier
; #define PG8_STAGE(bufoff, gbase, voff) do { _Pragma("unroll") for (int _i = 0; _i < 2; ++_i) \
;         asm volatile("s_mov_b32 m0, %0\n\ts_nop 0\n\tglobal_load_lds_dwordx4 %1, %2" :: "s"(ldsb + (unsigned)(bufoff) + ldsw + (unsigned)(_i * 8192)), "v"((voff)[_i]), "s"((const char*)(gbase)) : "memory", "m0"); } while (0)
; #define PG8_LDA(dst, b, h) do { _Pragma("unroll") for (int m = 0; m < 4; ++m) _Pragma("unroll") for (int k = 0; k < 2; ++k) dst[m][k] = *(const LAS bf16x8*)(lds + PG8_SA(b, h) + aoff + m * 2048 + k * 1024); } while (0)
; #define PG8_MMA(ai, bj, At, Bt) do { __builtin_amdgcn_s_setprio(1); _Pragma("unroll") for (int m = 0; m < 4; ++m) _Pragma("unroll") for (int n = 0; n < 2; ++n) _Pragma("unroll") for (int k = 0; k < 2; ++k) \
;         acc[ai][bj][m][n] = __builtin_amdgcn_mfma_f32_16x16x32_bf16(Bt[n][k], At[m][k], acc[ai][bj][m][n], 0, 0, 0); __builtin_amdgcn_s_setprio(0); } while (0)
; #define PG8_WAIT_V(n) asm volatile("s_waitcnt vmcnt(" #n ")" ::: "memory")
; #define PG8_WAIT_L(n) asm volatile("s_waitcnt lgkmcnt(" #n ")" ::: "memory")
; #define PG8_BAR __builtin_amdgcn_s_barrier()
; #define PG8_SCHED __builtin_amdgcn_sched_barrier(0)
; __device__ __forceinline__ f32x4 res_lo(const u32x4 w) { return (f32x4){bf_lo(w.x), bf_hi(w.x), bf_lo(w.y), bf_hi(w.y)}; }
; __device__ __forceinline__ f32x4 res_hi(const u32x4 w) { return (f32x4){bf_lo(w.z), bf_hi(w.z), bf_lo(w.w), bf_hi(w.w)}; }
; template <class Epi, class Sched>
; __device__ __forceinline__ void gemm_phase(LAS unsigned char* lds, const Gemm g, const Sched& S, const Epi& E) {
;     ...
;             PG8_LDA(At, 1, 1); PG8_STAGE(PG8_SB(1, 0), b3, voffB); PG8_STAGE(PG8_SB(1, 1), b3 + hstepB, voffB); PG8_STAGE(PG8_SA(1, 0), a3, voffA);
;             PG8_WAIT_V(8); PG8_WAIT_L(0); PG8_BAR; PG8_MMA(1, 0, At, B0); PG8_MMA(1, 1, At, B1); PG8_BAR; PG8_SCHED;
;         }
;     __device__ __forceinline__ void operator()(const Acc& acc, const Unit& u, int wr, int wc, int fr, int fq) const {
;     ...
;                     const f32x4 v0 = res_lo(res[m][bj]) + 0.5f * acc[ai][bj][m][0], v1 = res_hi(res[m][bj]) + 0.5f * acc[ai][bj][m][1];
	ds_read_b128 v[166:169], v191 offset:49152
	ds_read_b128 v[170:173], v191 offset:50176
	ds_read_b128 v[174:177], v191 offset:51200
	ds_read_b128 v[178:181], v191 offset:52224
	ds_read_b128 v[196:199], v191 offset:53248
	ds_read_b128 v[200:203], v191 offset:54272
	ds_read_b128 v[204:207], v191 offset:55296
	ds_read_b128 v[212:215], v191 offset:56320
	s_add_u32 s46, s54, 0x80
	s_addc_u32 s47, s55, 0
	s_mov_b32 m0, s62
	s_nop 0
	global_load_lds_dwordx4 v184, s[46:47]
	s_nop 0
	s_mov_b32 m0, s63
	s_nop 0
	global_load_lds_dwordx4 v186, s[46:47]
	s_add_u32 s46, s54, 0x160080
	s_addc_u32 s47, s55, 0
	s_mov_b32 m0, s66
	s_nop 0
	global_load_lds_dwordx4 v184, s[46:47]
	s_nop 0
	s_mov_b32 m0, s67
	s_nop 0
	global_load_lds_dwordx4 v186, s[46:47]
	s_nop 0
	s_waitcnt vmcnt(6)
	s_waitcnt lgkmcnt(0)
	s_barrier
	s_setprio 1
	s_waitcnt lgkmcnt(7)
	v_mfma_f32_16x16x32_bf16 v[126:129], v[134:137], v[166:169], v[126:129]
	v_mfma_f32_16x16x32_bf16 v[122:125], v[142:145], v[166:169], v[122:125]
	s_waitcnt lgkmcnt(5)
	v_mfma_f32_16x16x32_bf16 v[118:121], v[134:137], v[174:177], v[118:121]
	v_mfma_f32_16x16x32_bf16 v[114:117], v[142:145], v[174:177], v[114:117]
	s_waitcnt lgkmcnt(3)
	v_mfma_f32_16x16x32_bf16 v[106:109], v[134:137], v[196:199], v[106:109]
	v_mfma_f32_16x16x32_bf16 v[98:101], v[142:145], v[196:199], v[98:101]
	s_waitcnt lgkmcnt(1)
	v_mfma_f32_16x16x32_bf16 v[90:93], v[134:137], v[204:207], v[90:93]
	v_mfma_f32_16x16x32_bf16 v[82:85], v[142:145], v[204:207], v[82:85]
	v_mfma_f32_16x16x32_bf16 v[126:129], v[138:141], v[170:173], v[126:129]
	v_mfma_f32_16x16x32_bf16 v[122:125], v[146:149], v[170:173], v[122:125]
	v_mfma_f32_16x16x32_bf16 v[118:121], v[138:141], v[178:181], v[118:121]
	v_mfma_f32_16x16x32_bf16 v[114:117], v[146:149], v[178:181], v[114:117]
	v_mfma_f32_16x16x32_bf16 v[106:109], v[138:141], v[200:203], v[106:109]
	v_mfma_f32_16x16x32_bf16 v[98:101], v[146:149], v[200:203], v[98:101]
	s_waitcnt lgkmcnt(0)
	v_mfma_f32_16x16x32_bf16 v[90:93], v[138:141], v[212:215], v[90:93]
	v_mfma_f32_16x16x32_bf16 v[82:85], v[146:149], v[212:215], v[82:85]
	s_setprio 0
	s_setprio 1
	v_mfma_f32_16x16x32_bf16 v[110:113], v[150:153], v[166:169], v[110:113]
	v_mfma_f32_16x16x32_bf16 v[102:105], v[158:161], v[166:169], v[102:105]
	v_mfma_f32_16x16x32_bf16 v[94:97], v[150:153], v[174:177], v[94:97]
	v_mfma_f32_16x16x32_bf16 v[86:89], v[158:161], v[174:177], v[86:89]
	v_mfma_f32_16x16x32_bf16 v[78:81], v[150:153], v[196:199], v[78:81]
	v_mfma_f32_16x16x32_bf16 v[74:77], v[158:161], v[196:199], v[74:77]
	v_mfma_f32_16x16x32_bf16 v[70:73], v[150:153], v[204:207], v[70:73]
	v_mfma_f32_16x16x32_bf16 v[66:69], v[158:161], v[204:207], v[66:69]
	v_mfma_f32_16x16x32_bf16 v[110:113], v[154:157], v[170:173], v[110:113]
	v_mfma_f32_16x16x32_bf16 v[102:105], v[162:165], v[170:173], v[102:105]
	v_mfma_f32_16x16x32_bf16 v[94:97], v[154:157], v[178:181], v[94:97]
	v_mfma_f32_16x16x32_bf16 v[86:89], v[162:165], v[178:181], v[86:89]
	v_mfma_f32_16x16x32_bf16 v[78:81], v[154:157], v[200:203], v[78:81]
	v_mfma_f32_16x16x32_bf16 v[74:77], v[162:165], v[200:203], v[74:77]
	v_mfma_f32_16x16x32_bf16 v[70:73], v[154:157], v[212:215], v[70:73]
	v_mfma_f32_16x16x32_bf16 v[66:69], v[162:165], v[212:215], v[66:69]
	s_setprio 0
	s_barrier
	s_add_u32 s38, s38, 0x100
	s_addc_u32 s39, s39, 0
	s_add_u32 s40, s40, 0x100
	s_addc_u32 s41, s41, 0
	s_cmp_ge_i32 s43, s33
	s_mov_b32 s42, s43
	s_cbranch_scc0 .LBB0_247
	v_pk_mul_f32 v[162:163], v[128:129], 0.5 op_sel_hi:[1,0]
	v_pk_mul_f32 v[164:165], v[126:127], 0.5 op_sel_hi:[1,0]
	v_pk_mul_f32 v[158:159], v[124:125], 0.5 op_sel_hi:[1,0]
	v_pk_mul_f32 v[160:161], v[122:123], 0.5 op_sel_hi:[1,0]
	v_pk_mul_f32 v[154:155], v[112:113], 0.5 op_sel_hi:[1,0]
	v_pk_mul_f32 v[156:157], v[110:111], 0.5 op_sel_hi:[1,0]
	v_pk_mul_f32 v[152:153], v[104:105], 0.5 op_sel_hi:[1,0]
	v_pk_mul_f32 v[150:151], v[102:103], 0.5 op_sel_hi:[1,0]
	v_pk_mul_f32 v[136:137], v[120:121], 0.5 op_sel_hi:[1,0]
	v_pk_mul_f32 v[134:135], v[118:119], 0.5 op_sel_hi:[1,0]
	v_pk_mul_f32 v[128:129], v[116:117], 0.5 op_sel_hi:[1,0]
	v_pk_mul_f32 v[126:127], v[114:115], 0.5 op_sel_hi:[1,0]
	v_pk_mul_f32 v[144:145], v[96:97], 0.5 op_sel_hi:[1,0]
	v_pk_mul_f32 v[142:143], v[94:95], 0.5 op_sel_hi:[1,0]
	v_pk_mul_f32 v[140:141], v[88:89], 0.5 op_sel_hi:[1,0]
	v_pk_mul_f32 v[138:139], v[86:87], 0.5 op_sel_hi:[1,0]
	v_pk_mul_f32 v[116:117], v[108:109], 0.5 op_sel_hi:[1,0]
	v_pk_mul_f32 v[114:115], v[106:107], 0.5 op_sel_hi:[1,0]
	v_pk_mul_f32 v[112:113], v[100:101], 0.5 op_sel_hi:[1,0]
	v_pk_mul_f32 v[110:111], v[98:99], 0.5 op_sel_hi:[1,0]
	v_pk_mul_f32 v[124:125], v[80:81], 0.5 op_sel_hi:[1,0]
	v_pk_mul_f32 v[122:123], v[78:79], 0.5 op_sel_hi:[1,0]
	v_pk_mul_f32 v[120:121], v[76:77], 0.5 op_sel_hi:[1,0]
	v_pk_mul_f32 v[118:119], v[74:75], 0.5 op_sel_hi:[1,0]
	v_pk_mul_f32 v[100:101], v[92:93], 0.5 op_sel_hi:[1,0]
	v_pk_mul_f32 v[98:99], v[90:91], 0.5 op_sel_hi:[1,0]
	v_pk_mul_f32 v[96:97], v[84:85], 0.5 op_sel_hi:[1,0]
	v_pk_mul_f32 v[94:95], v[82:83], 0.5 op_sel_hi:[1,0]
	v_pk_mul_f32 v[108:109], v[72:73], 0.5 op_sel_hi:[1,0]
	v_pk_mul_f32 v[106:107], v[70:71], 0.5 op_sel_hi:[1,0]
	v_pk_mul_f32 v[104:105], v[68:69], 0.5 op_sel_hi:[1,0]
	v_pk_mul_f32 v[102:103], v[66:67], 0.5 op_sel_hi:[1,0]

;     __device__ __forceinline__ void a_ready(const Unit&) const { wait_cnt(w_ready, w_need); }
;     __device__ __forceinline__ void half_ready(const Unit& u) const { wait_cnt(g_ready + 64 * u.pm, g_need); }
; #define PG8_STAGE(bufoff, gbase, voff) do { _Pragma("unroll") for (int _i = 0; _i < 2; ++_i) \
;         asm volatile("s_mov_b32 m0, %0\n\ts_nop 0\n\tglobal_load_lds_dwordx4 %1, %2" :: "s"(ldsb + (unsigned)(bufoff) + ldsw + (unsigned)(_i * 8192)), "v"((voff)[_i]), "s"((const char*)(gbase)) : "memory", "m0"); } while (0)
; #define PG8_LDA(dst, b, h) do { _Pragma("unroll") for (int m = 0; m < 4; ++m) _Pragma("unroll") for (int k = 0; k < 2; ++k) dst[m][k] = *(const LAS bf16x8*)(lds + PG8_SA(b, h) + aoff + m * 2048 + k * 1024); } while (0)
; #define PG8_LDB(dst, b, h) do { _Pragma("unroll") for (int n = 0; n < 2; ++n) _Pragma("unroll") for (int k = 0; k < 2; ++k) dst[n][k] = *(const LAS bf16x8*)(lds + PG8_SB(b, h) + boff + n * 2048 + k * 1024); } while (0)
; #define PG8_WAIT_V(n) asm volatile("s_waitcnt vmcnt(" #n ")" ::: "memory")
; template <class Epi, class Sched>
; __device__ __forceinline__ void gemm_phase(LAS unsigned char* lds, const Gemm g, const Sched& S, const Epi& E) {
;     ...
;             const bool last = (t == nt - 2);
;             if (last && has_next) S.a_ready(nxt);
;             if constexpr (Sched::TWO_HALVES) { if (t == KSW - 2) S.half_ready(cur); }
;             const char* a1 = cA + PG8_KOFF(t + 1) * (long)kstep;
;             const char* a2 = last ? nA : cA + PG8_KOFF(t + 2) * (long)kstep; const char* b2 = last ? nB : cB + PG8_KOFF(t + 2) * (long)kstep;
;             const char* a3 = a2 + kstep; const char* b3 = b2 + kstep;
;             if constexpr (Epi::HAS_MID) { if (t == Epi::MID_T) E.mid(acc, cur, wr, wc, fr, fq); }
;             PG8_LDB(B0, 0, 0); PG8_LDB(B1, 0, 1); PG8_SCHED; PG8_LDA(At, 0, 0); PG8_STAGE(PG8_SA(1, 1), a1 + hstepA, voffA);
;             PG8_WAIT_V(8); PG8_WAIT_L(0); PG8_BAR; PG8_MMA(0, 0, At, B0); PG8_MMA(0, 1, At, B1); PG8_BAR; PG8_SCHED;
;             PG8_LDA(At, 0, 1); PG8_STAGE(PG8_SB(0, 0), b2, voffB); PG8_STAGE(PG8_SB(0, 1), b2 + hstepB, voffB); PG8_STAGE(PG8_SA(0, 0), a2, voffA);
;             PG8_WAIT_V(8); PG8_WAIT_L(0); PG8_BAR; PG8_BAR; PG8_SCHED;
;             PG8_LDB(B0, 1, 0); PG8_LDB(B1, 1, 1); PG8_SCHED; PG8_LDA(At, 1, 0); PG8_STAGE(PG8_SA(0, 1), a2 + hstepA, voffA);
.LBB0_255:
	ds_read_b128 v[66:69], v189
	ds_read_b128 v[70:73], v189 offset:1024
	ds_read_b128 v[74:77], v189 offset:2048
	ds_read_b128 v[78:81], v189 offset:3072
	ds_read_b128 v[82:85], v190
	ds_read_b128 v[86:89], v190 offset:1024
	ds_read_b128 v[90:93], v190 offset:2048
	ds_read_b128 v[94:97], v190 offset:3072
	s_add_i32 s38, s39, 2
	s_cmp_eq_u32 s37, s39
	s_cselect_b32 s56, s4, s80
	s_cselect_b32 s57, s5, s81
	s_cselect_b32 s54, s30, s78
	s_cselect_b32 s55, s31, s79
	s_add_u32 s52, s56, 0x80
	s_addc_u32 s53, s57, 0
	ds_read_b128 v[98:101], v191
	ds_read_b128 v[102:105], v191 offset:1024
	ds_read_b128 v[106:109], v191 offset:2048
	ds_read_b128 v[110:113], v191 offset:3072
	ds_read_b128 v[114:117], v191 offset:4096
	ds_read_b128 v[118:121], v191 offset:5120
	ds_read_b128 v[122:125], v191 offset:6144
	ds_read_b128 v[126:129], v191 offset:7168
	s_add_u32 s40, s80, 0xffffff80
	s_addc_u32 s41, s81, -1
	s_mov_b32 m0, s64
	s_nop 0
	global_load_lds_dwordx4 v183, s[40:41]
	s_mov_b32 m0, s65
	s_nop 0
	global_load_lds_dwordx4 v185, s[40:41]
	s_add_u32 s40, s80, 0x15ff80
	s_addc_u32 s41, s81, 0
	s_mov_b32 m0, s68
	s_nop 0
	global_load_lds_dwordx4 v183, s[40:41]
	s_nop 0
	s_mov_b32 m0, s69
	s_nop 0
	global_load_lds_dwordx4 v185, s[40:41]
	s_waitcnt vmcnt(8)
	s_waitcnt lgkmcnt(0)
	s_barrier
	s_setprio 1
	s_waitcnt lgkmcnt(7)
	v_mfma_f32_16x16x32_bf16 v[62:65], v[66:69], v[98:101], v[62:65]
	v_mfma_f32_16x16x32_bf16 v[58:61], v[74:77], v[98:101], v[58:61]
	s_waitcnt lgkmcnt(5)
	v_mfma_f32_16x16x32_bf16 v[54:57], v[66:69], v[106:109], v[54:57]
	v_mfma_f32_16x16x32_bf16 v[50:53], v[74:77], v[106:109], v[50:53]
	s_waitcnt lgkmcnt(3)
	v_mfma_f32_16x16x32_bf16 v[46:49], v[66:69], v[114:117], v[46:49]
	v_mfma_f32_16x16x32_bf16 v[38:41], v[74:77], v[114:117], v[38:41]
	s_waitcnt lgkmcnt(1)
	v_mfma_f32_16x16x32_bf16 v[30:33], v[66:69], v[122:125], v[30:33]
	v_mfma_f32_16x16x32_bf16 v[22:25], v[74:77], v[122:125], v[22:25]
	v_mfma_f32_16x16x32_bf16 v[62:65], v[70:73], v[102:105], v[62:65]
	v_mfma_f32_16x16x32_bf16 v[58:61], v[78:81], v[102:105], v[58:61]
	v_mfma_f32_16x16x32_bf16 v[54:57], v[70:73], v[110:113], v[54:57]
	v_mfma_f32_16x16x32_bf16 v[50:53], v[78:81], v[110:113], v[50:53]
	v_mfma_f32_16x16x32_bf16 v[46:49], v[70:73], v[118:121], v[46:49]
	v_mfma_f32_16x16x32_bf16 v[38:41], v[78:81], v[118:121], v[38:41]
	s_waitcnt lgkmcnt(0)
	v_mfma_f32_16x16x32_bf16 v[30:33], v[70:73], v[126:129], v[30:33]
	v_mfma_f32_16x16x32_bf16 v[22:25], v[78:81], v[126:129], v[22:25]
	s_setprio 0
	s_setprio 1
	v_mfma_f32_16x16x32_bf16 v[42:45], v[82:85], v[98:101], v[42:45]
	v_mfma_f32_16x16x32_bf16 v[34:37], v[90:93], v[98:101], v[34:37]
	v_mfma_f32_16x16x32_bf16 v[26:29], v[82:85], v[106:109], v[26:29]
	v_mfma_f32_16x16x32_bf16 v[18:21], v[90:93], v[106:109], v[18:21]
	v_mfma_f32_16x16x32_bf16 v[14:17], v[82:85], v[114:117], v[14:17]
	v_mfma_f32_16x16x32_bf16 v[10:13], v[90:93], v[114:117], v[10:13]
	v_mfma_f32_16x16x32_bf16 v[6:9], v[82:85], v[122:125], v[6:9]
	v_mfma_f32_16x16x32_bf16 v[2:5], v[90:93], v[122:125], v[2:5]
	v_mfma_f32_16x16x32_bf16 v[42:45], v[86:89], v[102:105], v[42:45]
	v_mfma_f32_16x16x32_bf16 v[34:37], v[94:97], v[102:105], v[34:37]
	v_mfma_f32_16x16x32_bf16 v[26:29], v[86:89], v[110:113], v[26:29]
	v_mfma_f32_16x16x32_bf16 v[18:21], v[94:97], v[110:113], v[18:21]
	v_mfma_f32_16x16x32_bf16 v[14:17], v[86:89], v[118:121], v[14:17]
	v_mfma_f32_16x16x32_bf16 v[10:13], v[94:97], v[118:121], v[10:13]
	v_mfma_f32_16x16x32_bf16 v[6:9], v[86:89], v[126:129], v[6:9]
	v_mfma_f32_16x16x32_bf16 v[2:5], v[94:97], v[126:129], v[2:5]
	s_setprio 0
	s_barrier
	s_mov_b32 m0, s29
	s_nop 0
	global_load_lds_dwordx4 v184, s[54:55]
	s_add_u32 s40, s54, 0x160000
	s_mov_b32 m0, s34
	s_nop 0
	global_load_lds_dwordx4 v186, s[54:55]
	s_addc_u32 s41, s55, 0
	s_mov_b32 m0, s35
	s_nop 0
	global_load_lds_dwordx4 v184, s[40:41]
	s_nop 0
	s_mov_b32 m0, s58
	s_nop 0
	global_load_lds_dwordx4 v186, s[40:41]
	s_nop 0
	s_waitcnt vmcnt(6)
	s_waitcnt lgkmcnt(0)
	s_barrier
	s_barrier
	ds_read_b128 v[66:69], v192
	ds_read_b128 v[70:73], v192 offset:1024
	ds_read_b128 v[74:77], v192 offset:2048
	ds_read_b128 v[78:81], v192 offset:3072
	ds_read_b128 v[82:85], v193
	ds_read_b128 v[86:89], v193 offset:1024
	ds_read_b128 v[90:93], v193 offset:2048
	ds_read_b128 v[94:97], v193 offset:3072
	ds_read_b128 v[98:101], v191 offset:32768
	ds_read_b128 v[102:105], v191 offset:33792
	ds_read_b128 v[106:109], v191 offset:34816
	ds_read_b128 v[110:113], v191 offset:35840
	ds_read_b128 v[114:117], v191 offset:36864
	ds_read_b128 v[118:121], v191 offset:37888
	ds_read_b128 v[122:125], v191 offset:38912
	ds_read_b128 v[126:129], v191 offset:39936
	s_mov_b32 m0, s28
	s_nop 0
	global_load_lds_dwordx4 v183, s[56:57]
	s_mov_b32 m0, s59
	s_nop 0
	global_load_lds_dwordx4 v185, s[56:57]
	s_add_u32 s40, s56, 0x160000
	s_addc_u32 s41, s57, 0
	s_mov_b32 m0, s60
	s_nop 0
	global_load_lds_dwordx4 v183, s[40:41]
	s_nop 0
	s_mov_b32 m0, s61
	s_nop 0
	global_load_lds_dwordx4 v185, s[40:41]
	s_waitcnt vmcnt(8)
	s_waitcnt lgkmcnt(0)
	s_barrier
; #define PG8_STAGE(bufoff, gbase, voff) do { _Pragma("unroll") for (int _i = 0; _i < 2; ++_i) \
;         asm volatile("s_mov_b32 m0, %0\n\ts_nop 0\n\tglobal_load_lds_dwordx4 %1, %2" :: "s"(ldsb + (unsigned)(bufoff) + ldsw + (unsigned)(_i * 8192)), "v"((voff)[_i]), "s"((const char*)(gbase)) : "memory", "m0"); } while (0)
; #define PG8_LDA(dst, b, h) do { _Pragma("unroll") for (int m = 0; m < 4; ++m) _Pragma("unroll") for (int k = 0; k < 2; ++k) dst[m][k] = *(const LAS bf16x8*)(lds + PG8_SA(b, h) + aoff + m * 2048 + k * 1024); } while (0)
; #define PG8_MMA(ai, bj, At, Bt) do { __builtin_amdgcn_s_setprio(1); _Pragma("unroll") for (int m = 0; m < 4; ++m) _Pragma("unroll") for (int n = 0; n < 2; ++n) _Pragma("unroll") for (int k = 0; k < 2; ++k) \
;         acc[ai][bj][m][n] = __builtin_amdgcn_mfma_f32_16x16x32_bf16(Bt[n][k], At[m][k], acc[ai][bj][m][n], 0, 0, 0); __builtin_amdgcn_s_setprio(0); } while (0)
; #define PG8_WAIT_V(n) asm volatile("s_waitcnt vmcnt(" #n ")" ::: "memory")
; #define PG8_WAIT_L(n) asm volatile("s_waitcnt lgkmcnt(" #n ")" ::: "memory")
; #define PG8_BAR __builtin_amdgcn_s_barrier()
; #define PG8_SCHED __builtin_amdgcn_sched_barrier(0)
; template <class Epi, class Sched>
; __device__ __forceinline__ void gemm_phase(LAS unsigned char* lds, const Gemm g, const Sched& S, const Epi& E) {
;     ...
;             PG8_WAIT_V(8); PG8_WAIT_L(0); PG8_BAR; PG8_MMA(0, 0, At, B0); PG8_MMA(0, 1, At, B1); PG8_BAR; PG8_SCHED;
;             PG8_LDA(At, 1, 1); PG8_STAGE(PG8_SB(1, 0), b3, voffB); PG8_STAGE(PG8_SB(1, 1), b3 + hstepB, voffB); PG8_STAGE(PG8_SA(1, 0), a3, voffA);
;             PG8_WAIT_V(8); PG8_WAIT_L(0); PG8_BAR; PG8_BAR; PG8_SCHED;
;         }
;     ...
;         for (int a = 0; a < 2; ++a)
; #pragma unroll
;             for (int b = 0; b < 2; ++b)
; #pragma unroll
;                 for (int m = 0; m < 4; ++m)
; #pragma unroll
;                     for (int n = 0; n < 2; ++n) acc[a][b][m][n] = (f32x4){0.f, 0.f, 0.f, 0.f};
	s_setprio 1
	s_waitcnt lgkmcnt(7)
	v_mfma_f32_16x16x32_bf16 v[62:65], v[66:69], v[98:101], v[62:65]
	v_mfma_f32_16x16x32_bf16 v[58:61], v[74:77], v[98:101], v[58:61]
	s_waitcnt lgkmcnt(5)
	v_mfma_f32_16x16x32_bf16 v[54:57], v[66:69], v[106:109], v[54:57]
	v_mfma_f32_16x16x32_bf16 v[50:53], v[74:77], v[106:109], v[50:53]
	s_waitcnt lgkmcnt(3)
	v_mfma_f32_16x16x32_bf16 v[46:49], v[66:69], v[114:117], v[46:49]
	v_mfma_f32_16x16x32_bf16 v[38:41], v[74:77], v[114:117], v[38:41]
	s_waitcnt lgkmcnt(1)
	v_mfma_f32_16x16x32_bf16 v[30:33], v[66:69], v[122:125], v[30:33]
	v_mfma_f32_16x16x32_bf16 v[22:25], v[74:77], v[122:125], v[22:25]
	v_mfma_f32_16x16x32_bf16 v[62:65], v[70:73], v[102:105], v[62:65]
	v_mfma_f32_16x16x32_bf16 v[58:61], v[78:81], v[102:105], v[58:61]
	v_mfma_f32_16x16x32_bf16 v[54:57], v[70:73], v[110:113], v[54:57]
	v_mfma_f32_16x16x32_bf16 v[50:53], v[78:81], v[110:113], v[50:53]
	v_mfma_f32_16x16x32_bf16 v[46:49], v[70:73], v[118:121], v[46:49]
	v_mfma_f32_16x16x32_bf16 v[38:41], v[78:81], v[118:121], v[38:41]
	s_waitcnt lgkmcnt(0)
	v_mfma_f32_16x16x32_bf16 v[30:33], v[70:73], v[126:129], v[30:33]
	v_mfma_f32_16x16x32_bf16 v[22:25], v[78:81], v[126:129], v[22:25]
	s_setprio 0
	s_setprio 1
	v_mfma_f32_16x16x32_bf16 v[42:45], v[82:85], v[98:101], v[42:45]
	v_mfma_f32_16x16x32_bf16 v[34:37], v[90:93], v[98:101], v[34:37]
	v_mfma_f32_16x16x32_bf16 v[26:29], v[82:85], v[106:109], v[26:29]
	v_mfma_f32_16x16x32_bf16 v[18:21], v[90:93], v[106:109], v[18:21]
	v_mfma_f32_16x16x32_bf16 v[14:17], v[82:85], v[114:117], v[14:17]
	v_mfma_f32_16x16x32_bf16 v[10:13], v[90:93], v[114:117], v[10:13]
	v_mfma_f32_16x16x32_bf16 v[6:9], v[82:85], v[122:125], v[6:9]
	v_mfma_f32_16x16x32_bf16 v[2:5], v[90:93], v[122:125], v[2:5]
	v_mfma_f32_16x16x32_bf16 v[42:45], v[86:89], v[102:105], v[42:45]
	v_mfma_f32_16x16x32_bf16 v[34:37], v[94:97], v[102:105], v[34:37]
	v_mfma_f32_16x16x32_bf16 v[26:29], v[86:89], v[110:113], v[26:29]
	v_mfma_f32_16x16x32_bf16 v[18:21], v[94:97], v[110:113], v[18:21]
	v_mfma_f32_16x16x32_bf16 v[14:17], v[86:89], v[118:121], v[14:17]
	v_mfma_f32_16x16x32_bf16 v[10:13], v[94:97], v[118:121], v[10:13]
	v_mfma_f32_16x16x32_bf16 v[6:9], v[86:89], v[126:129], v[6:9]
	v_mfma_f32_16x16x32_bf16 v[2:5], v[94:97], v[126:129], v[2:5]
	s_setprio 0
	s_barrier
	s_add_u32 s40, s54, 0x80
	s_addc_u32 s41, s55, 0
	s_mov_b32 m0, s62
	s_nop 0
	global_load_lds_dwordx4 v184, s[40:41]
	s_nop 0
	s_mov_b32 m0, s63
	s_nop 0
	global_load_lds_dwordx4 v186, s[40:41]
	s_add_u32 s40, s54, 0x160080
	s_addc_u32 s41, s55, 0
	s_mov_b32 m0, s66
	s_nop 0
	global_load_lds_dwordx4 v184, s[40:41]
	s_nop 0
	s_mov_b32 m0, s67
	s_nop 0
	global_load_lds_dwordx4 v186, s[40:41]
	s_nop 0
	s_waitcnt vmcnt(6)
	s_waitcnt lgkmcnt(0)
	s_barrier
	s_barrier
	s_add_u32 s80, s80, 0x100
	s_addc_u32 s81, s81, 0
	s_add_u32 s78, s78, 0x100
	s_addc_u32 s79, s79, 0
	s_cmp_ge_i32 s38, s33
	s_mov_b32 s39, s38
	s_cbranch_scc0 .LBB0_255
	v_mov_b32_e32 v163, 0
	v_mov_b32_e32 v162, v163
	v_mov_b32_e32 v165, v163
	v_mov_b32_e32 v164, v163
	v_mov_b32_e32 v159, v163
	v_mov_b32_e32 v158, v163
	v_mov_b32_e32 v161, v163
	v_mov_b32_e32 v160, v163
	v_mov_b32_e32 v137, v163
	v_mov_b32_e32 v136, v163
	v_mov_b32_e32 v135, v163
	v_mov_b32_e32 v134, v163
	v_mov_b32_e32 v129, v163
	v_mov_b32_e32 v128, v163
	v_mov_b32_e32 v127, v163
	v_mov_b32_e32 v126, v163
	v_mov_b32_e32 v117, v163
	v_mov_b32_e32 v116, v163
	v_mov_b32_e32 v115, v163
	v_mov_b32_e32 v114, v163
	v_mov_b32_e32 v113, v163
	v_mov_b32_e32 v112, v163
	v_mov_b32_e32 v111, v163
	v_mov_b32_e32 v110, v163
	v_mov_b32_e32 v101, v163
	v_mov_b32_e32 v100, v163
	v_mov_b32_e32 v99, v163
	v_mov_b32_e32 v98, v163
	v_mov_b32_e32 v97, v163
	v_mov_b32_e32 v96, v163
	v_mov_b32_e32 v95, v163
	v_mov_b32_e32 v94, v163
	v_mov_b32_e32 v155, v163
	v_mov_b32_e32 v154, v163
	v_mov_b32_e32 v157, v163
	v_mov_b32_e32 v156, v163
	v_mov_b32_e32 v153, v163
	v_mov_b32_e32 v152, v163
	v_mov_b32_e32 v151, v163
	v_mov_b32_e32 v150, v163
	v_mov_b32_e32 v145, v163
	v_mov_b32_e32 v144, v163
	v_mov_b32_e32 v143, v163
	v_mov_b32_e32 v142, v163
	v_mov_b32_e32 v141, v163
	v_mov_b32_e32 v140, v163
	v_mov_b32_e32 v139, v163
	v_mov_b32_e32 v138, v163
	v_mov_b32_e32 v125, v163
	v_mov_b32_e32 v124, v163
	v_mov_b32_e32 v123, v163
	v_mov_b32_e32 v122, v163
	v_mov_b32_e32 v121, v163
	v_mov_b32_e32 v120, v163
	v_mov_b32_e32 v119, v163
	v_mov_b32_e32 v118, v163
	v_mov_b32_e32 v109, v163
	v_mov_b32_e32 v108, v163
	v_mov_b32_e32 v107, v163
	v_mov_b32_e32 v106, v163
	v_mov_b32_e32 v105, v163
	v_mov_b32_e32 v104, v163
	v_mov_b32_e32 v103, v163
	v_mov_b32_e32 v102, v163
	s_load_dwordx2 s[80:81], s[0:1], 0x138
	s_andn2_b64 vcc, exec, s[14:15]
	s_cbranch_vccz .LBB0_250

;     __device__ __forceinline__ void a_ready(const Unit&) const { wait_cnt(w_ready, w_need); }
;     __device__ __forceinline__ void half_ready(const Unit& u) const { wait_cnt(g_ready + 64 * u.pm, g_need); }
; #define PG8_STAGE(bufoff, gbase, voff) do { _Pragma("unroll") for (int _i = 0; _i < 2; ++_i) \
;         asm volatile("s_mov_b32 m0, %0\n\ts_nop 0\n\tglobal_load_lds_dwordx4 %1, %2" :: "s"(ldsb + (unsigned)(bufoff) + ldsw + (unsigned)(_i * 8192)), "v"((voff)[_i]), "s"((const char*)(gbase)) : "memory", "m0"); } while (0)
; #define PG8_LDA(dst, b, h) do { _Pragma("unroll") for (int m = 0; m < 4; ++m) _Pragma("unroll") for (int k = 0; k < 2; ++k) dst[m][k] = *(const LAS bf16x8*)(lds + PG8_SA(b, h) + aoff + m * 2048 + k * 1024); } while (0)
; #define PG8_LDB(dst, b, h) do { _Pragma("unroll") for (int n = 0; n < 2; ++n) _Pragma("unroll") for (int k = 0; k < 2; ++k) dst[n][k] = *(const LAS bf16x8*)(lds + PG8_SB(b, h) + boff + n * 2048 + k * 1024); } while (0)
; #define PG8_WAIT_V(n) asm volatile("s_waitcnt vmcnt(" #n ")" ::: "memory")
; #define PG8_WAIT_L(n) asm volatile("s_waitcnt lgkmcnt(" #n ")" ::: "memory")
; #define PG8_BAR __builtin_amdgcn_s_barrier()
; #define PG8_SCHED __builtin_amdgcn_sched_barrier(0)
; template <class Epi, class Sched>
; __device__ __forceinline__ void gemm_phase(LAS unsigned char* lds, const Gemm g, const Sched& S, const Epi& E) {
;     ...
;             const bool last = (t == nt - 2);
;             if (last && has_next) S.a_ready(nxt);
;             if constexpr (Sched::TWO_HALVES) { if (t == KSW - 2) S.half_ready(cur); }
;             const char* a1 = cA + PG8_KOFF(t + 1) * (long)kstep;
;             const char* a2 = last ? nA : cA + PG8_KOFF(t + 2) * (long)kstep; const char* b2 = last ? nB : cB + PG8_KOFF(t + 2) * (long)kstep;
;             const char* a3 = a2 + kstep; const char* b3 = b2 + kstep;
;             if constexpr (Epi::HAS_MID) { if (t == Epi::MID_T) E.mid(acc, cur, wr, wc, fr, fq); }
;             PG8_LDB(B0, 0, 0); PG8_LDB(B1, 0, 1); PG8_SCHED; PG8_LDA(At, 0, 0); PG8_STAGE(PG8_SA(1, 1), a1 + hstepA, voffA);
;             PG8_WAIT_V(8); PG8_WAIT_L(0); PG8_BAR; PG8_MMA(0, 0, At, B0); PG8_MMA(0, 1, At, B1); PG8_BAR; PG8_SCHED;
;             PG8_LDA(At, 0, 1); PG8_STAGE(PG8_SB(0, 0), b2, voffB); PG8_STAGE(PG8_SB(0, 1), b2 + hstepB, voffB); PG8_STAGE(PG8_SA(0, 0), a2, voffA);
.LBB0_347:
	s_or_b32 s18, s38, 1
	s_lshl_b64 s[40:41], s[18:19], 7
	s_add_i32 s18, s38, 2
	s_lshl_b64 s[42:43], s[18:19], 7
	s_add_u32 s39, s6, s42
	v_add_u32_e32 v183, 0, v146
	s_addc_u32 s48, s7, s43
	v_add_u32_e32 v154, 0x10000, v183
	v_add_u32_e32 v170, 0x14000, v183
	s_and_b64 s[46:47], s[74:75], exec
	ds_read_b128 v[132:135], v154
	ds_read_b128 v[136:139], v154 offset:1024
	ds_read_b128 v[150:153], v154 offset:2048
	ds_read_b128 v[154:157], v154 offset:3072
	ds_read_b128 v[158:161], v170
	ds_read_b128 v[162:165], v170 offset:1024
	ds_read_b128 v[166:169], v170 offset:2048
	ds_read_b128 v[170:173], v170 offset:3072
	s_cselect_b32 s85, s5, s48
	s_cselect_b32 s84, s73, s39
	s_add_u32 s39, s8, s42
	s_addc_u32 s46, s9, s43
	s_add_u32 s82, s84, 0x80
	s_addc_u32 s83, s85, 0
	s_and_b64 s[42:43], s[74:75], exec
	s_cselect_b32 s75, s89, s46
	s_cselect_b32 s74, s91, s39
	s_add_u32 s39, s6, s40
	s_addc_u32 s41, s7, s41
	v_add_u32_e32 v208, 0, v145
	ds_read_b128 v[174:177], v208
	ds_read_b128 v[178:181], v208 offset:1024
	ds_read_b128 v[184:187], v208 offset:2048
	ds_read_b128 v[188:191], v208 offset:3072
	ds_read_b128 v[192:195], v208 offset:4096
	ds_read_b128 v[196:199], v208 offset:5120
	ds_read_b128 v[200:203], v208 offset:6144
	ds_read_b128 v[204:207], v208 offset:7168
	s_mov_b32 s40, s39
	s_mov_b32 m0, s86
	s_nop 0
	global_load_lds_dwordx4 v140, s[40:41]
	s_mov_b32 m0, s34
	s_nop 0
	global_load_lds_dwordx4 v142, s[40:41]
	s_add_u32 s40, s39, 0x80000
	s_addc_u32 s41, s41, 0
	s_mov_b32 m0, s13
	s_nop 0
	global_load_lds_dwordx4 v140, s[40:41]
	s_nop 0
	s_mov_b32 m0, s28
	s_nop 0
	global_load_lds_dwordx4 v142, s[40:41]
	s_waitcnt vmcnt(8)
	s_waitcnt lgkmcnt(0)
	s_barrier
	s_setprio 1
	s_waitcnt lgkmcnt(7)
	v_mfma_f32_16x16x32_bf16 v[126:129], v[132:135], v[174:177], v[126:129]
	v_mfma_f32_16x16x32_bf16 v[122:125], v[150:153], v[174:177], v[122:125]
	s_waitcnt lgkmcnt(5)
	v_mfma_f32_16x16x32_bf16 v[110:113], v[132:135], v[184:187], v[110:113]
	v_mfma_f32_16x16x32_bf16 v[106:109], v[150:153], v[184:187], v[106:109]
	s_waitcnt lgkmcnt(3)
	v_mfma_f32_16x16x32_bf16 v[94:97], v[132:135], v[192:195], v[94:97]
	v_mfma_f32_16x16x32_bf16 v[90:93], v[150:153], v[192:195], v[90:93]
	s_waitcnt lgkmcnt(1)
	v_mfma_f32_16x16x32_bf16 v[70:73], v[132:135], v[200:203], v[70:73]
	v_mfma_f32_16x16x32_bf16 v[66:69], v[150:153], v[200:203], v[66:69]
	v_mfma_f32_16x16x32_bf16 v[126:129], v[136:139], v[178:181], v[126:129]
	v_mfma_f32_16x16x32_bf16 v[122:125], v[154:157], v[178:181], v[122:125]
	v_mfma_f32_16x16x32_bf16 v[110:113], v[136:139], v[188:191], v[110:113]
	v_mfma_f32_16x16x32_bf16 v[106:109], v[154:157], v[188:191], v[106:109]
	v_mfma_f32_16x16x32_bf16 v[94:97], v[136:139], v[196:199], v[94:97]
	v_mfma_f32_16x16x32_bf16 v[90:93], v[154:157], v[196:199], v[90:93]
	s_waitcnt lgkmcnt(0)
	v_mfma_f32_16x16x32_bf16 v[70:73], v[136:139], v[204:207], v[70:73]
	v_mfma_f32_16x16x32_bf16 v[66:69], v[154:157], v[204:207], v[66:69]
	s_setprio 0
	s_setprio 1
	v_mfma_f32_16x16x32_bf16 v[118:121], v[158:161], v[174:177], v[118:121]
	v_mfma_f32_16x16x32_bf16 v[114:117], v[166:169], v[174:177], v[114:117]
	v_mfma_f32_16x16x32_bf16 v[102:105], v[158:161], v[184:187], v[102:105]
	v_mfma_f32_16x16x32_bf16 v[98:101], v[166:169], v[184:187], v[98:101]
	v_mfma_f32_16x16x32_bf16 v[86:89], v[158:161], v[192:195], v[86:89]
	v_mfma_f32_16x16x32_bf16 v[82:85], v[166:169], v[192:195], v[82:85]
	v_mfma_f32_16x16x32_bf16 v[54:57], v[158:161], v[200:203], v[54:57]
	v_mfma_f32_16x16x32_bf16 v[50:53], v[166:169], v[200:203], v[50:53]
	v_mfma_f32_16x16x32_bf16 v[118:121], v[162:165], v[178:181], v[118:121]
	v_mfma_f32_16x16x32_bf16 v[114:117], v[170:173], v[178:181], v[114:117]
	v_mfma_f32_16x16x32_bf16 v[102:105], v[162:165], v[188:191], v[102:105]
	v_mfma_f32_16x16x32_bf16 v[98:101], v[170:173], v[188:191], v[98:101]
	v_mfma_f32_16x16x32_bf16 v[86:89], v[162:165], v[196:199], v[86:89]
	v_mfma_f32_16x16x32_bf16 v[82:85], v[170:173], v[196:199], v[82:85]
	v_mfma_f32_16x16x32_bf16 v[54:57], v[162:165], v[204:207], v[54:57]
	v_mfma_f32_16x16x32_bf16 v[50:53], v[170:173], v[204:207], v[50:53]
	s_setprio 0
	s_barrier
	ds_read_b128 v[174:177], v208 offset:16384
	ds_read_b128 v[178:181], v208 offset:17408
	ds_read_b128 v[184:187], v208 offset:18432
	ds_read_b128 v[188:191], v208 offset:19456
	ds_read_b128 v[192:195], v208 offset:20480
	ds_read_b128 v[196:199], v208 offset:21504
	ds_read_b128 v[200:203], v208 offset:22528
	ds_read_b128 v[204:207], v208 offset:23552
	s_mov_b32 m0, s44
	s_nop 0
	global_load_lds_dwordx4 v141, s[74:75]
	s_add_u32 s40, s74, 0x80000
	s_mov_b32 m0, s45
	s_nop 0
	global_load_lds_dwordx4 v143, s[74:75]
	s_addc_u32 s41, s75, 0
	s_mov_b32 m0, s80
	s_nop 0
	global_load_lds_dwordx4 v141, s[40:41]
	s_nop 0
	s_mov_b32 m0, s81
	s_nop 0
	global_load_lds_dwordx4 v143, s[40:41]
	s_nop 0
	s_waitcnt vmcnt(6)
	s_waitcnt lgkmcnt(0)
	s_barrier
; #define PG8_STAGE(bufoff, gbase, voff) do { _Pragma("unroll") for (int _i = 0; _i < 2; ++_i) \
;         asm volatile("s_mov_b32 m0, %0\n\ts_nop 0\n\tglobal_load_lds_dwordx4 %1, %2" :: "s"(ldsb + (unsigned)(bufoff) + ldsw + (unsigned)(_i * 8192)), "v"((voff)[_i]), "s"((const char*)(gbase)) : "memory", "m0"); } while (0)
; #define PG8_LDA(dst, b, h) do { _Pragma("unroll") for (int m = 0; m < 4; ++m) _Pragma("unroll") for (int k = 0; k < 2; ++k) dst[m][k] = *(const LAS bf16x8*)(lds + PG8_SA(b, h) + aoff + m * 2048 + k * 1024); } while (0)
; #define PG8_LDB(dst, b, h) do { _Pragma("unroll") for (int n = 0; n < 2; ++n) _Pragma("unroll") for (int k = 0; k < 2; ++k) dst[n][k] = *(const LAS bf16x8*)(lds + PG8_SB(b, h) + boff + n * 2048 + k * 1024); } while (0)
; #define PG8_MMA(ai, bj, At, Bt) do { __builtin_amdgcn_s_setprio(1); _Pragma("unroll") for (int m = 0; m < 4; ++m) _Pragma("unroll") for (int n = 0; n < 2; ++n) _Pragma("unroll") for (int k = 0; k < 2; ++k) \
;         acc[ai][bj][m][n] = __builtin_amdgcn_mfma_f32_16x16x32_bf16(Bt[n][k], At[m][k], acc[ai][bj][m][n], 0, 0, 0); __builtin_amdgcn_s_setprio(0); } while (0)
; #define PG8_WAIT_V(n) asm volatile("s_waitcnt vmcnt(" #n ")" ::: "memory")
; #define PG8_WAIT_L(n) asm volatile("s_waitcnt lgkmcnt(" #n ")" ::: "memory")
; #define PG8_BAR __builtin_amdgcn_s_barrier()
; #define PG8_SCHED __builtin_amdgcn_sched_barrier(0)
; template <class Epi, class Sched>
; __device__ __forceinline__ void gemm_phase(LAS unsigned char* lds, const Gemm g, const Sched& S, const Epi& E) {
;     ...
;             PG8_WAIT_V(8); PG8_WAIT_L(0); PG8_BAR; PG8_MMA(1, 0, At, B0); PG8_MMA(1, 1, At, B1); PG8_BAR; PG8_SCHED;
;             PG8_LDB(B0, 1, 0); PG8_LDB(B1, 1, 1); PG8_SCHED; PG8_LDA(At, 1, 0); PG8_STAGE(PG8_SA(0, 1), a2 + hstepA, voffA);
;             PG8_WAIT_V(8); PG8_WAIT_L(0); PG8_BAR; PG8_MMA(0, 0, At, B0); PG8_MMA(0, 1, At, B1); PG8_BAR; PG8_SCHED;
	s_setprio 1
	s_waitcnt lgkmcnt(7)
	v_mfma_f32_16x16x32_bf16 v[78:81], v[132:135], v[174:177], v[78:81]
	v_mfma_f32_16x16x32_bf16 v[74:77], v[150:153], v[174:177], v[74:77]
	s_waitcnt lgkmcnt(5)
	v_mfma_f32_16x16x32_bf16 v[46:49], v[132:135], v[184:187], v[46:49]
	v_mfma_f32_16x16x32_bf16 v[42:45], v[150:153], v[184:187], v[42:45]
	s_waitcnt lgkmcnt(3)
	v_mfma_f32_16x16x32_bf16 v[30:33], v[132:135], v[192:195], v[30:33]
	v_mfma_f32_16x16x32_bf16 v[26:29], v[150:153], v[192:195], v[26:29]
	s_waitcnt lgkmcnt(1)
	v_mfma_f32_16x16x32_bf16 v[14:17], v[132:135], v[200:203], v[14:17]
	v_mfma_f32_16x16x32_bf16 v[10:13], v[150:153], v[200:203], v[10:13]
	v_mfma_f32_16x16x32_bf16 v[78:81], v[136:139], v[178:181], v[78:81]
	v_mfma_f32_16x16x32_bf16 v[74:77], v[154:157], v[178:181], v[74:77]
	v_mfma_f32_16x16x32_bf16 v[46:49], v[136:139], v[188:191], v[46:49]
	v_mfma_f32_16x16x32_bf16 v[42:45], v[154:157], v[188:191], v[42:45]
	v_mfma_f32_16x16x32_bf16 v[30:33], v[136:139], v[196:199], v[30:33]
	v_mfma_f32_16x16x32_bf16 v[26:29], v[154:157], v[196:199], v[26:29]
	s_waitcnt lgkmcnt(0)
	v_mfma_f32_16x16x32_bf16 v[14:17], v[136:139], v[204:207], v[14:17]
	v_mfma_f32_16x16x32_bf16 v[10:13], v[154:157], v[204:207], v[10:13]
	s_setprio 0
	s_setprio 1
	v_mfma_f32_16x16x32_bf16 v[62:65], v[158:161], v[174:177], v[62:65]
	v_mfma_f32_16x16x32_bf16 v[58:61], v[166:169], v[174:177], v[58:61]
	v_mfma_f32_16x16x32_bf16 v[38:41], v[158:161], v[184:187], v[38:41]
	v_mfma_f32_16x16x32_bf16 v[34:37], v[166:169], v[184:187], v[34:37]
	v_mfma_f32_16x16x32_bf16 v[22:25], v[158:161], v[192:195], v[22:25]
	v_mfma_f32_16x16x32_bf16 v[18:21], v[166:169], v[192:195], v[18:21]
	v_mfma_f32_16x16x32_bf16 v[6:9], v[158:161], v[200:203], v[6:9]
	v_mfma_f32_16x16x32_bf16 v[2:5], v[166:169], v[200:203], v[2:5]
	v_mfma_f32_16x16x32_bf16 v[62:65], v[162:165], v[178:181], v[62:65]
	v_mfma_f32_16x16x32_bf16 v[58:61], v[170:173], v[178:181], v[58:61]
	v_mfma_f32_16x16x32_bf16 v[38:41], v[162:165], v[188:191], v[38:41]
	v_mfma_f32_16x16x32_bf16 v[34:37], v[170:173], v[188:191], v[34:37]
	v_mfma_f32_16x16x32_bf16 v[22:25], v[162:165], v[196:199], v[22:25]
	v_mfma_f32_16x16x32_bf16 v[18:21], v[170:173], v[196:199], v[18:21]
	v_mfma_f32_16x16x32_bf16 v[6:9], v[162:165], v[204:207], v[6:9]
	v_mfma_f32_16x16x32_bf16 v[2:5], v[170:173], v[204:207], v[2:5]
	s_setprio 0
	s_barrier
	v_add_u32_e32 v154, 0x18000, v183
	v_add_u32_e32 v170, 0x1c000, v183
	ds_read_b128 v[132:135], v154
	ds_read_b128 v[136:139], v154 offset:1024
	ds_read_b128 v[150:153], v154 offset:2048
	ds_read_b128 v[154:157], v154 offset:3072
	ds_read_b128 v[158:161], v170
	ds_read_b128 v[162:165], v170 offset:1024
	ds_read_b128 v[166:169], v170 offset:2048
	ds_read_b128 v[170:173], v170 offset:3072
	ds_read_b128 v[174:177], v208 offset:32768
	ds_read_b128 v[178:181], v208 offset:33792
	ds_read_b128 v[184:187], v208 offset:34816
	ds_read_b128 v[188:191], v208 offset:35840
	ds_read_b128 v[192:195], v208 offset:36864
	ds_read_b128 v[196:199], v208 offset:37888
	ds_read_b128 v[200:203], v208 offset:38912
	ds_read_b128 v[204:207], v208 offset:39936
	s_mov_b32 m0, s87
	s_nop 0
	global_load_lds_dwordx4 v140, s[84:85]
	s_mov_b32 m0, s33
	s_nop 0
	global_load_lds_dwordx4 v142, s[84:85]
	s_add_u32 s40, s84, 0x80000
	s_addc_u32 s41, s85, 0
	s_mov_b32 m0, s78
	s_nop 0
	global_load_lds_dwordx4 v140, s[40:41]
	s_nop 0
	s_mov_b32 m0, s79
	s_nop 0
	global_load_lds_dwordx4 v142, s[40:41]
	s_waitcnt vmcnt(8)
	s_waitcnt lgkmcnt(0)
	s_barrier
; #define PG8_STAGE(bufoff, gbase, voff) do { _Pragma("unroll") for (int _i = 0; _i < 2; ++_i) \
;         asm volatile("s_mov_b32 m0, %0\n\ts_nop 0\n\tglobal_load_lds_dwordx4 %1, %2" :: "s"(ldsb + (unsigned)(bufoff) + ldsw + (unsigned)(_i * 8192)), "v"((voff)[_i]), "s"((const char*)(gbase)) : "memory", "m0"); } while (0)
; #define PG8_LDA(dst, b, h) do { _Pragma("unroll") for (int m = 0; m < 4; ++m) _Pragma("unroll") for (int k = 0; k < 2; ++k) dst[m][k] = *(const LAS bf16x8*)(lds + PG8_SA(b, h) + aoff + m * 2048 + k * 1024); } while (0)
; #define PG8_MMA(ai, bj, At, Bt) do { __builtin_amdgcn_s_setprio(1); _Pragma("unroll") for (int m = 0; m < 4; ++m) _Pragma("unroll") for (int n = 0; n < 2; ++n) _Pragma("unroll") for (int k = 0; k < 2; ++k) \
;         acc[ai][bj][m][n] = __builtin_amdgcn_mfma_f32_16x16x32_bf16(Bt[n][k], At[m][k], acc[ai][bj][m][n], 0, 0, 0); __builtin_amdgcn_s_setprio(0); } while (0)
; #define PG8_WAIT_V(n) asm volatile("s_waitcnt vmcnt(" #n ")" ::: "memory")
; #define PG8_WAIT_L(n) asm volatile("s_waitcnt lgkmcnt(" #n ")" ::: "memory")
; #define PG8_BAR __builtin_amdgcn_s_barrier()
; #define PG8_SCHED __builtin_amdgcn_sched_barrier(0)
; template <class Epi, class Sched>
; __device__ __forceinline__ void gemm_phase(LAS unsigned char* lds, const Gemm g, const Sched& S, const Epi& E) {
;     ...
;             PG8_WAIT_V(8); PG8_WAIT_L(0); PG8_BAR; PG8_MMA(0, 0, At, B0); PG8_MMA(0, 1, At, B1); PG8_BAR; PG8_SCHED;
;             PG8_LDA(At, 1, 1); PG8_STAGE(PG8_SB(1, 0), b3, voffB); PG8_STAGE(PG8_SB(1, 1), b3 + hstepB, voffB); PG8_STAGE(PG8_SA(1, 0), a3, voffA);
;             PG8_WAIT_V(8); PG8_WAIT_L(0); PG8_BAR; PG8_MMA(1, 0, At, B0); PG8_MMA(1, 1, At, B1); PG8_BAR; PG8_SCHED;
;         }
	s_setprio 1
	s_waitcnt lgkmcnt(7)
	v_mfma_f32_16x16x32_bf16 v[126:129], v[132:135], v[174:177], v[126:129]
	v_mfma_f32_16x16x32_bf16 v[122:125], v[150:153], v[174:177], v[122:125]
	s_waitcnt lgkmcnt(5)
	v_mfma_f32_16x16x32_bf16 v[110:113], v[132:135], v[184:187], v[110:113]
	v_mfma_f32_16x16x32_bf16 v[106:109], v[150:153], v[184:187], v[106:109]
	s_waitcnt lgkmcnt(3)
	v_mfma_f32_16x16x32_bf16 v[94:97], v[132:135], v[192:195], v[94:97]
	v_mfma_f32_16x16x32_bf16 v[90:93], v[150:153], v[192:195], v[90:93]
	s_waitcnt lgkmcnt(1)
	v_mfma_f32_16x16x32_bf16 v[70:73], v[132:135], v[200:203], v[70:73]
	v_mfma_f32_16x16x32_bf16 v[66:69], v[150:153], v[200:203], v[66:69]
	v_mfma_f32_16x16x32_bf16 v[126:129], v[136:139], v[178:181], v[126:129]
	v_mfma_f32_16x16x32_bf16 v[122:125], v[154:157], v[178:181], v[122:125]
	v_mfma_f32_16x16x32_bf16 v[110:113], v[136:139], v[188:191], v[110:113]
	v_mfma_f32_16x16x32_bf16 v[106:109], v[154:157], v[188:191], v[106:109]
	v_mfma_f32_16x16x32_bf16 v[94:97], v[136:139], v[196:199], v[94:97]
	v_mfma_f32_16x16x32_bf16 v[90:93], v[154:157], v[196:199], v[90:93]
	s_waitcnt lgkmcnt(0)
	v_mfma_f32_16x16x32_bf16 v[70:73], v[136:139], v[204:207], v[70:73]
	v_mfma_f32_16x16x32_bf16 v[66:69], v[154:157], v[204:207], v[66:69]
	s_setprio 0
	s_setprio 1
	v_mfma_f32_16x16x32_bf16 v[118:121], v[158:161], v[174:177], v[118:121]
	v_mfma_f32_16x16x32_bf16 v[114:117], v[166:169], v[174:177], v[114:117]
	v_mfma_f32_16x16x32_bf16 v[102:105], v[158:161], v[184:187], v[102:105]
	v_mfma_f32_16x16x32_bf16 v[98:101], v[166:169], v[184:187], v[98:101]
	v_mfma_f32_16x16x32_bf16 v[86:89], v[158:161], v[192:195], v[86:89]
	v_mfma_f32_16x16x32_bf16 v[82:85], v[166:169], v[192:195], v[82:85]
	v_mfma_f32_16x16x32_bf16 v[54:57], v[158:161], v[200:203], v[54:57]
	v_mfma_f32_16x16x32_bf16 v[50:53], v[166:169], v[200:203], v[50:53]
	v_mfma_f32_16x16x32_bf16 v[118:121], v[162:165], v[178:181], v[118:121]
	v_mfma_f32_16x16x32_bf16 v[114:117], v[170:173], v[178:181], v[114:117]
	v_mfma_f32_16x16x32_bf16 v[102:105], v[162:165], v[188:191], v[102:105]
	v_mfma_f32_16x16x32_bf16 v[98:101], v[170:173], v[188:191], v[98:101]
	v_mfma_f32_16x16x32_bf16 v[86:89], v[162:165], v[196:199], v[86:89]
	v_mfma_f32_16x16x32_bf16 v[82:85], v[170:173], v[196:199], v[82:85]
	v_mfma_f32_16x16x32_bf16 v[54:57], v[162:165], v[204:207], v[54:57]
	v_mfma_f32_16x16x32_bf16 v[50:53], v[170:173], v[204:207], v[50:53]
	s_setprio 0
	s_barrier
	ds_read_b128 v[174:177], v208 offset:49152
	ds_read_b128 v[178:181], v208 offset:50176
	ds_read_b128 v[184:187], v208 offset:51200
	ds_read_b128 v[188:191], v208 offset:52224
	ds_read_b128 v[192:195], v208 offset:53248
	ds_read_b128 v[196:199], v208 offset:54272
	ds_read_b128 v[200:203], v208 offset:55296
	ds_read_b128 v[204:207], v208 offset:56320
	s_add_u32 s40, s74, 0x80
	s_addc_u32 s41, s75, 0
	s_mov_b32 m0, s70
	s_nop 0
	global_load_lds_dwordx4 v141, s[40:41]
	s_nop 0
	s_mov_b32 m0, s71
	s_nop 0
	global_load_lds_dwordx4 v143, s[40:41]
	s_add_u32 s40, s74, 0x80080
	s_addc_u32 s41, s75, 0
	s_mov_b32 m0, s35
	s_nop 0
	global_load_lds_dwordx4 v141, s[40:41]
	s_nop 0
	s_mov_b32 m0, s12
	s_nop 0
	global_load_lds_dwordx4 v143, s[40:41]
	s_nop 0
	s_waitcnt vmcnt(6)
	s_waitcnt lgkmcnt(0)
	s_barrier
	s_setprio 1
	s_waitcnt lgkmcnt(7)
	v_mfma_f32_16x16x32_bf16 v[78:81], v[132:135], v[174:177], v[78:81]
	v_mfma_f32_16x16x32_bf16 v[74:77], v[150:153], v[174:177], v[74:77]
	s_waitcnt lgkmcnt(5)
	v_mfma_f32_16x16x32_bf16 v[46:49], v[132:135], v[184:187], v[46:49]
	v_mfma_f32_16x16x32_bf16 v[42:45], v[150:153], v[184:187], v[42:45]
	s_waitcnt lgkmcnt(3)
	v_mfma_f32_16x16x32_bf16 v[30:33], v[132:135], v[192:195], v[30:33]
	v_mfma_f32_16x16x32_bf16 v[26:29], v[150:153], v[192:195], v[26:29]
	s_waitcnt lgkmcnt(1)
	v_mfma_f32_16x16x32_bf16 v[14:17], v[132:135], v[200:203], v[14:17]
	v_mfma_f32_16x16x32_bf16 v[10:13], v[150:153], v[200:203], v[10:13]
	v_mfma_f32_16x16x32_bf16 v[78:81], v[136:139], v[178:181], v[78:81]
	v_mfma_f32_16x16x32_bf16 v[74:77], v[154:157], v[178:181], v[74:77]
	v_mfma_f32_16x16x32_bf16 v[46:49], v[136:139], v[188:191], v[46:49]
	v_mfma_f32_16x16x32_bf16 v[42:45], v[154:157], v[188:191], v[42:45]
	v_mfma_f32_16x16x32_bf16 v[30:33], v[136:139], v[196:199], v[30:33]
	v_mfma_f32_16x16x32_bf16 v[26:29], v[154:157], v[196:199], v[26:29]
	s_waitcnt lgkmcnt(0)
	v_mfma_f32_16x16x32_bf16 v[14:17], v[136:139], v[204:207], v[14:17]
	v_mfma_f32_16x16x32_bf16 v[10:13], v[154:157], v[204:207], v[10:13]
	s_setprio 0
	s_setprio 1
	v_mfma_f32_16x16x32_bf16 v[62:65], v[158:161], v[174:177], v[62:65]
	v_mfma_f32_16x16x32_bf16 v[58:61], v[166:169], v[174:177], v[58:61]
	v_mfma_f32_16x16x32_bf16 v[38:41], v[158:161], v[184:187], v[38:41]
	v_mfma_f32_16x16x32_bf16 v[34:37], v[166:169], v[184:187], v[34:37]
	v_mfma_f32_16x16x32_bf16 v[22:25], v[158:161], v[192:195], v[22:25]
	v_mfma_f32_16x16x32_bf16 v[18:21], v[166:169], v[192:195], v[18:21]
	v_mfma_f32_16x16x32_bf16 v[6:9], v[158:161], v[200:203], v[6:9]
	v_mfma_f32_16x16x32_bf16 v[2:5], v[166:169], v[200:203], v[2:5]
	v_mfma_f32_16x16x32_bf16 v[62:65], v[162:165], v[178:181], v[62:65]
	v_mfma_f32_16x16x32_bf16 v[58:61], v[170:173], v[178:181], v[58:61]
	v_mfma_f32_16x16x32_bf16 v[38:41], v[162:165], v[188:191], v[38:41]
	v_mfma_f32_16x16x32_bf16 v[34:37], v[170:173], v[188:191], v[34:37]
	v_mfma_f32_16x16x32_bf16 v[22:25], v[162:165], v[196:199], v[22:25]
	v_mfma_f32_16x16x32_bf16 v[18:21], v[170:173], v[196:199], v[18:21]
	v_mfma_f32_16x16x32_bf16 v[6:9], v[162:165], v[204:207], v[6:9]
	v_mfma_f32_16x16x32_bf16 v[2:5], v[170:173], v[204:207], v[2:5]
	s_setprio 0
	s_barrier
	s_cmp_gt_u32 s38, 29
	s_cbranch_scc1 .LBB0_364
	s_mov_b32 s38, s18
	s_branch .LBB0_335

;     __device__ __forceinline__ void a_ready(const Unit&) const { wait_cnt(w_ready, w_need); }
;     __device__ __forceinline__ void half_ready(const Unit& u) const { wait_cnt(g_ready + 64 * u.pm, g_need); }
; #define PG8_STAGE(bufoff, gbase, voff) do { _Pragma("unroll") for (int _i = 0; _i < 2; ++_i) \
;         asm volatile("s_mov_b32 m0, %0\n\ts_nop 0\n\tglobal_load_lds_dwordx4 %1, %2" :: "s"(ldsb + (unsigned)(bufoff) + ldsw + (unsigned)(_i * 8192)), "v"((voff)[_i]), "s"((const char*)(gbase)) : "memory", "m0"); } while (0)
; #define PG8_LDA(dst, b, h) do { _Pragma("unroll") for (int m = 0; m < 4; ++m) _Pragma("unroll") for (int k = 0; k < 2; ++k) dst[m][k] = *(const LAS bf16x8*)(lds + PG8_SA(b, h) + aoff + m * 2048 + k * 1024); } while (0)
; #define PG8_LDB(dst, b, h) do { _Pragma("unroll") for (int n = 0; n < 2; ++n) _Pragma("unroll") for (int k = 0; k < 2; ++k) dst[n][k] = *(const LAS bf16x8*)(lds + PG8_SB(b, h) + boff + n * 2048 + k * 1024); } while (0)
; #define PG8_WAIT_V(n) asm volatile("s_waitcnt vmcnt(" #n ")" ::: "memory")
; #define PG8_WAIT_L(n) asm volatile("s_waitcnt lgkmcnt(" #n ")" ::: "memory")
; #define PG8_BAR __builtin_amdgcn_s_barrier()
; template <class Epi, class Sched>
; __device__ __forceinline__ void gemm_phase(LAS unsigned char* lds, const Gemm g, const Sched& S, const Epi& E) {
;     ...
;             const bool last = (t == nt - 2);
;             if (last && has_next) S.a_ready(nxt);
;             if constexpr (Sched::TWO_HALVES) { if (t == KSW - 2) S.half_ready(cur); }
;             const char* a1 = cA + PG8_KOFF(t + 1) * (long)kstep;
;             const char* a2 = last ? nA : cA + PG8_KOFF(t + 2) * (long)kstep; const char* b2 = last ? nB : cB + PG8_KOFF(t + 2) * (long)kstep;
;             const char* a3 = a2 + kstep; const char* b3 = b2 + kstep;
;             if constexpr (Epi::HAS_MID) { if (t == Epi::MID_T) E.mid(acc, cur, wr, wc, fr, fq); }
;             PG8_LDB(B0, 0, 0); PG8_LDB(B1, 0, 1); PG8_SCHED; PG8_LDA(At, 0, 0); PG8_STAGE(PG8_SA(1, 1), a1 + hstepA, voffA);
;             PG8_WAIT_V(8); PG8_WAIT_L(0); PG8_BAR; PG8_MMA(0, 0, At, B0); PG8_MMA(0, 1, At, B1); PG8_BAR; PG8_SCHED;
;             PG8_LDA(At, 0, 1); PG8_STAGE(PG8_SB(0, 0), b2, voffB); PG8_STAGE(PG8_SB(0, 1), b2 + hstepB, voffB); PG8_STAGE(PG8_SA(0, 0), a2, voffA);
;             PG8_WAIT_V(8); PG8_WAIT_L(0); PG8_BAR; PG8_BAR; PG8_SCHED;
.LBB0_353:
	s_or_b32 s18, s38, 1
	s_lshl_b64 s[40:41], s[18:19], 7
	s_add_i32 s18, s38, 2
	s_lshl_b64 s[42:43], s[18:19], 7
	s_add_u32 s39, s6, s42
	v_add_u32_e32 v132, 0, v146
	s_addc_u32 s48, s7, s43
	v_add_u32_e32 v14, 0x10000, v132
	v_add_u32_e32 v30, 0x14000, v132
	s_and_b64 s[46:47], s[82:83], exec
	ds_read_b128 v[2:5], v14
	ds_read_b128 v[6:9], v14 offset:1024
	ds_read_b128 v[10:13], v14 offset:2048
	ds_read_b128 v[14:17], v14 offset:3072
	ds_read_b128 v[18:21], v30
	ds_read_b128 v[22:25], v30 offset:1024
	ds_read_b128 v[26:29], v30 offset:2048
	ds_read_b128 v[30:33], v30 offset:3072
	s_cselect_b32 s85, s5, s48
	s_cselect_b32 s84, s73, s39
	s_add_u32 s39, s8, s42
	s_addc_u32 s46, s9, s43
	s_add_u32 s74, s84, 0x80
	s_addc_u32 s75, s85, 0
	s_and_b64 s[42:43], s[82:83], exec
	s_cselect_b32 s83, s89, s46
	s_cselect_b32 s82, s91, s39
	s_add_u32 s39, s6, s40
	s_addc_u32 s41, s7, s41
	v_add_u32_e32 v158, 0, v145
	ds_read_b128 v[34:37], v158
	ds_read_b128 v[38:41], v158 offset:1024
	ds_read_b128 v[42:45], v158 offset:2048
	ds_read_b128 v[46:49], v158 offset:3072
	ds_read_b128 v[58:61], v158 offset:4096
	ds_read_b128 v[62:65], v158 offset:5120
	ds_read_b128 v[74:77], v158 offset:6144
	ds_read_b128 v[78:81], v158 offset:7168
	s_mov_b32 s40, s39
	s_mov_b32 m0, s86
	s_nop 0
	global_load_lds_dwordx4 v140, s[40:41]
	s_mov_b32 m0, s34
	s_nop 0
	global_load_lds_dwordx4 v142, s[40:41]
	s_add_u32 s40, s39, 0x80000
	s_addc_u32 s41, s41, 0
	s_mov_b32 m0, s13
	s_nop 0
	global_load_lds_dwordx4 v140, s[40:41]
	s_nop 0
	s_mov_b32 m0, s28
	s_nop 0
	global_load_lds_dwordx4 v142, s[40:41]
	s_waitcnt vmcnt(8)
	s_waitcnt lgkmcnt(0)
	s_barrier
	s_setprio 1
	s_waitcnt lgkmcnt(7)
	v_mfma_f32_16x16x32_bf16 v[126:129], v[2:5], v[34:37], v[126:129]
	v_mfma_f32_16x16x32_bf16 v[122:125], v[10:13], v[34:37], v[122:125]
	s_waitcnt lgkmcnt(5)
	v_mfma_f32_16x16x32_bf16 v[110:113], v[2:5], v[42:45], v[110:113]
	v_mfma_f32_16x16x32_bf16 v[106:109], v[10:13], v[42:45], v[106:109]
	s_waitcnt lgkmcnt(3)
	v_mfma_f32_16x16x32_bf16 v[94:97], v[2:5], v[58:61], v[94:97]
	v_mfma_f32_16x16x32_bf16 v[90:93], v[10:13], v[58:61], v[90:93]
	s_waitcnt lgkmcnt(1)
	v_mfma_f32_16x16x32_bf16 v[2:5], v[2:5], v[74:77], v[70:73]
	v_mfma_f32_16x16x32_bf16 v[126:129], v[6:9], v[38:41], v[126:129]
	v_mfma_f32_16x16x32_bf16 v[122:125], v[14:17], v[38:41], v[122:125]
	v_mfma_f32_16x16x32_bf16 v[110:113], v[6:9], v[46:49], v[110:113]
	v_mfma_f32_16x16x32_bf16 v[106:109], v[14:17], v[46:49], v[106:109]
	v_mfma_f32_16x16x32_bf16 v[94:97], v[6:9], v[62:65], v[94:97]
	v_mfma_f32_16x16x32_bf16 v[90:93], v[14:17], v[62:65], v[90:93]
	s_waitcnt lgkmcnt(0)
	v_mfma_f32_16x16x32_bf16 v[2:5], v[6:9], v[78:81], v[2:5]
	v_mfma_f32_16x16x32_bf16 v[6:9], v[10:13], v[74:77], v[66:69]
	v_mfma_f32_16x16x32_bf16 v[6:9], v[14:17], v[78:81], v[6:9]
	s_setprio 0
	s_setprio 1
	v_mfma_f32_16x16x32_bf16 v[10:13], v[18:21], v[34:37], v[118:121]
	v_mfma_f32_16x16x32_bf16 v[14:17], v[26:29], v[34:37], v[114:117]
	v_mfma_f32_16x16x32_bf16 v[10:13], v[22:25], v[38:41], v[10:13]
	v_mfma_f32_16x16x32_bf16 v[14:17], v[30:33], v[38:41], v[14:17]
	v_mfma_f32_16x16x32_bf16 v[34:37], v[18:21], v[42:45], v[102:105]
	v_mfma_f32_16x16x32_bf16 v[38:41], v[26:29], v[42:45], v[98:101]
	v_mfma_f32_16x16x32_bf16 v[42:45], v[18:21], v[58:61], v[86:89]
	v_mfma_f32_16x16x32_bf16 v[18:21], v[18:21], v[74:77], v[54:57]
	v_mfma_f32_16x16x32_bf16 v[34:37], v[22:25], v[46:49], v[34:37]
	v_mfma_f32_16x16x32_bf16 v[38:41], v[30:33], v[46:49], v[38:41]
	v_mfma_f32_16x16x32_bf16 v[42:45], v[22:25], v[62:65], v[42:45]
	v_mfma_f32_16x16x32_bf16 v[46:49], v[26:29], v[58:61], v[82:85]
	v_mfma_f32_16x16x32_bf16 v[18:21], v[22:25], v[78:81], v[18:21]
	v_mfma_f32_16x16x32_bf16 v[22:25], v[26:29], v[74:77], v[50:53]
	v_mfma_f32_16x16x32_bf16 v[46:49], v[30:33], v[62:65], v[46:49]
	v_mfma_f32_16x16x32_bf16 v[22:25], v[30:33], v[78:81], v[22:25]
	s_setprio 0
	s_barrier
	s_mov_b32 m0, s44
	s_nop 0
	global_load_lds_dwordx4 v141, s[82:83]
	s_add_u32 s40, s82, 0x80000
	s_mov_b32 m0, s45
	s_nop 0
	global_load_lds_dwordx4 v143, s[82:83]
	s_addc_u32 s41, s83, 0
	s_mov_b32 m0, s80
	s_nop 0
	global_load_lds_dwordx4 v141, s[40:41]
	s_nop 0
	s_mov_b32 m0, s81
	s_nop 0
	global_load_lds_dwordx4 v143, s[40:41]
	s_nop 0
	s_waitcnt vmcnt(6)
	s_waitcnt lgkmcnt(0)
	s_barrier
; #define PG8_STAGE(bufoff, gbase, voff) do { _Pragma("unroll") for (int _i = 0; _i < 2; ++_i) \
;         asm volatile("s_mov_b32 m0, %0\n\ts_nop 0\n\tglobal_load_lds_dwordx4 %1, %2" :: "s"(ldsb + (unsigned)(bufoff) + ldsw + (unsigned)(_i * 8192)), "v"((voff)[_i]), "s"((const char*)(gbase)) : "memory", "m0"); } while (0)
; #define PG8_LDA(dst, b, h) do { _Pragma("unroll") for (int m = 0; m < 4; ++m) _Pragma("unroll") for (int k = 0; k < 2; ++k) dst[m][k] = *(const LAS bf16x8*)(lds + PG8_SA(b, h) + aoff + m * 2048 + k * 1024); } while (0)
; #define PG8_LDB(dst, b, h) do { _Pragma("unroll") for (int n = 0; n < 2; ++n) _Pragma("unroll") for (int k = 0; k < 2; ++k) dst[n][k] = *(const LAS bf16x8*)(lds + PG8_SB(b, h) + boff + n * 2048 + k * 1024); } while (0)
; #define PG8_MMA(ai, bj, At, Bt) do { __builtin_amdgcn_s_setprio(1); _Pragma("unroll") for (int m = 0; m < 4; ++m) _Pragma("unroll") for (int n = 0; n < 2; ++n) _Pragma("unroll") for (int k = 0; k < 2; ++k) \
;         acc[ai][bj][m][n] = __builtin_amdgcn_mfma_f32_16x16x32_bf16(Bt[n][k], At[m][k], acc[ai][bj][m][n], 0, 0, 0); __builtin_amdgcn_s_setprio(0); } while (0)
; #define PG8_WAIT_V(n) asm volatile("s_waitcnt vmcnt(" #n ")" ::: "memory")
; #define PG8_WAIT_L(n) asm volatile("s_waitcnt lgkmcnt(" #n ")" ::: "memory")
; #define PG8_BAR __builtin_amdgcn_s_barrier()
; #define PG8_SCHED __builtin_amdgcn_sched_barrier(0)
; template <class Epi, class Sched>
; __device__ __forceinline__ void gemm_phase(LAS unsigned char* lds, const Gemm g, const Sched& S, const Epi& E) {
;     ...
;             PG8_WAIT_V(8); PG8_WAIT_L(0); PG8_BAR; PG8_BAR; PG8_SCHED;
;             PG8_LDB(B0, 1, 0); PG8_LDB(B1, 1, 1); PG8_SCHED; PG8_LDA(At, 1, 0); PG8_STAGE(PG8_SA(0, 1), a2 + hstepA, voffA);
;             PG8_WAIT_V(8); PG8_WAIT_L(0); PG8_BAR; PG8_MMA(0, 0, At, B0); PG8_MMA(0, 1, At, B1); PG8_BAR; PG8_SCHED;
;             PG8_LDA(At, 1, 1); PG8_STAGE(PG8_SB(1, 0), b3, voffB); PG8_STAGE(PG8_SB(1, 1), b3 + hstepB, voffB); PG8_STAGE(PG8_SA(1, 0), a3, voffA);
;             PG8_WAIT_V(8); PG8_WAIT_L(0); PG8_BAR; PG8_BAR; PG8_SCHED;
;         }
	s_barrier
	v_add_u32_e32 v54, 0x18000, v132
	v_add_u32_e32 v66, 0x1c000, v132
	ds_read_b128 v[26:29], v54
	ds_read_b128 v[30:33], v54 offset:1024
	ds_read_b128 v[50:53], v54 offset:2048
	ds_read_b128 v[54:57], v54 offset:3072
	ds_read_b128 v[58:61], v66
	ds_read_b128 v[62:65], v66 offset:1024
	ds_read_b128 v[74:77], v66 offset:2048
	ds_read_b128 v[78:81], v66 offset:3072
	ds_read_b128 v[82:85], v158 offset:32768
	ds_read_b128 v[86:89], v158 offset:33792
	ds_read_b128 v[98:101], v158 offset:34816
	ds_read_b128 v[132:135], v158 offset:35840
	ds_read_b128 v[136:139], v158 offset:36864
	ds_read_b128 v[150:153], v158 offset:37888
	ds_read_b128 v[154:157], v158 offset:38912
	ds_read_b128 v[158:161], v158 offset:39936
	s_mov_b32 m0, s87
	s_nop 0
	global_load_lds_dwordx4 v140, s[84:85]
	s_mov_b32 m0, s33
	s_nop 0
	global_load_lds_dwordx4 v142, s[84:85]
	s_add_u32 s40, s84, 0x80000
	s_addc_u32 s41, s85, 0
	s_mov_b32 m0, s78
	s_nop 0
	global_load_lds_dwordx4 v140, s[40:41]
	s_nop 0
	s_mov_b32 m0, s79
	s_nop 0
	global_load_lds_dwordx4 v142, s[40:41]
	s_waitcnt vmcnt(8)
	s_waitcnt lgkmcnt(0)
	s_barrier
	s_setprio 1
	s_waitcnt lgkmcnt(7)
	v_mfma_f32_16x16x32_bf16 v[66:69], v[26:29], v[82:85], v[126:129]
	s_waitcnt lgkmcnt(6)
	v_mfma_f32_16x16x32_bf16 v[126:129], v[30:33], v[86:89], v[66:69]
	v_mfma_f32_16x16x32_bf16 v[66:69], v[50:53], v[82:85], v[122:125]
	v_mfma_f32_16x16x32_bf16 v[122:125], v[54:57], v[86:89], v[66:69]
	s_waitcnt lgkmcnt(5)
	v_mfma_f32_16x16x32_bf16 v[66:69], v[26:29], v[98:101], v[110:113]
	s_waitcnt lgkmcnt(4)
	v_mfma_f32_16x16x32_bf16 v[110:113], v[30:33], v[132:135], v[66:69]
	v_mfma_f32_16x16x32_bf16 v[66:69], v[50:53], v[98:101], v[106:109]
	v_mfma_f32_16x16x32_bf16 v[106:109], v[54:57], v[132:135], v[66:69]
	s_waitcnt lgkmcnt(3)
	v_mfma_f32_16x16x32_bf16 v[66:69], v[26:29], v[136:139], v[94:97]
	s_waitcnt lgkmcnt(1)
	v_mfma_f32_16x16x32_bf16 v[2:5], v[26:29], v[154:157], v[2:5]
	v_mfma_f32_16x16x32_bf16 v[94:97], v[30:33], v[150:153], v[66:69]
	v_mfma_f32_16x16x32_bf16 v[66:69], v[50:53], v[136:139], v[90:93]
	s_waitcnt lgkmcnt(0)
	v_mfma_f32_16x16x32_bf16 v[70:73], v[30:33], v[158:161], v[2:5]
	v_mfma_f32_16x16x32_bf16 v[2:5], v[50:53], v[154:157], v[6:9]
	v_mfma_f32_16x16x32_bf16 v[90:93], v[54:57], v[150:153], v[66:69]
	v_mfma_f32_16x16x32_bf16 v[66:69], v[54:57], v[158:161], v[2:5]
	s_setprio 0
	s_setprio 1
	v_mfma_f32_16x16x32_bf16 v[2:5], v[58:61], v[82:85], v[10:13]
	v_mfma_f32_16x16x32_bf16 v[118:121], v[62:65], v[86:89], v[2:5]
	v_mfma_f32_16x16x32_bf16 v[2:5], v[74:77], v[82:85], v[14:17]
	v_mfma_f32_16x16x32_bf16 v[114:117], v[78:81], v[86:89], v[2:5]
	v_mfma_f32_16x16x32_bf16 v[2:5], v[58:61], v[98:101], v[34:37]
	v_mfma_f32_16x16x32_bf16 v[102:105], v[62:65], v[132:135], v[2:5]
	v_mfma_f32_16x16x32_bf16 v[2:5], v[74:77], v[98:101], v[38:41]
	v_mfma_f32_16x16x32_bf16 v[98:101], v[78:81], v[132:135], v[2:5]
	v_mfma_f32_16x16x32_bf16 v[2:5], v[58:61], v[136:139], v[42:45]
	v_mfma_f32_16x16x32_bf16 v[86:89], v[62:65], v[150:153], v[2:5]
	v_mfma_f32_16x16x32_bf16 v[2:5], v[74:77], v[136:139], v[46:49]
	v_mfma_f32_16x16x32_bf16 v[82:85], v[78:81], v[150:153], v[2:5]
	v_mfma_f32_16x16x32_bf16 v[2:5], v[58:61], v[154:157], v[18:21]
	v_mfma_f32_16x16x32_bf16 v[54:57], v[62:65], v[158:161], v[2:5]
	v_mfma_f32_16x16x32_bf16 v[2:5], v[74:77], v[154:157], v[22:25]
	v_mfma_f32_16x16x32_bf16 v[50:53], v[78:81], v[158:161], v[2:5]
	s_setprio 0
	s_barrier
	s_add_u32 s40, s82, 0x80
	s_addc_u32 s41, s83, 0
	s_mov_b32 m0, s70
	s_nop 0
	global_load_lds_dwordx4 v141, s[40:41]
	s_nop 0
	s_mov_b32 m0, s71
	s_nop 0
	global_load_lds_dwordx4 v143, s[40:41]
	s_add_u32 s40, s82, 0x80080
	s_addc_u32 s41, s83, 0
	s_mov_b32 m0, s35
	s_nop 0
	global_load_lds_dwordx4 v141, s[40:41]
	s_nop 0
	s_mov_b32 m0, s12
	s_nop 0
	global_load_lds_dwordx4 v143, s[40:41]
	s_nop 0
	s_waitcnt vmcnt(6)
	s_waitcnt lgkmcnt(0)
	s_barrier
	s_barrier
	s_cmp_gt_u32 s38, 29
	s_mov_b32 s38, s18
	s_cbranch_scc1 .LBB0_498

;     __device__ __forceinline__ void a_ready(const Unit&) const { wait_cnt(w_ready, w_need); }
;     __device__ __forceinline__ void half_ready(const Unit& u) const { wait_cnt(g_ready + 64 * u.pm, g_need); }
; #define PG8_STAGE(bufoff, gbase, voff) do { _Pragma("unroll") for (int _i = 0; _i < 2; ++_i) \
;         asm volatile("s_mov_b32 m0, %0\n\ts_nop 0\n\tglobal_load_lds_dwordx4 %1, %2" :: "s"(ldsb + (unsigned)(bufoff) + ldsw + (unsigned)(_i * 8192)), "v"((voff)[_i]), "s"((const char*)(gbase)) : "memory", "m0"); } while (0)
; #define PG8_LDA(dst, b, h) do { _Pragma("unroll") for (int m = 0; m < 4; ++m) _Pragma("unroll") for (int k = 0; k < 2; ++k) dst[m][k] = *(const LAS bf16x8*)(lds + PG8_SA(b, h) + aoff + m * 2048 + k * 1024); } while (0)
; #define PG8_LDB(dst, b, h) do { _Pragma("unroll") for (int n = 0; n < 2; ++n) _Pragma("unroll") for (int k = 0; k < 2; ++k) dst[n][k] = *(const LAS bf16x8*)(lds + PG8_SB(b, h) + boff + n * 2048 + k * 1024); } while (0)
; #define PG8_WAIT_V(n) asm volatile("s_waitcnt vmcnt(" #n ")" ::: "memory")
; #define PG8_WAIT_L(n) asm volatile("s_waitcnt lgkmcnt(" #n ")" ::: "memory")
; #define PG8_BAR __builtin_amdgcn_s_barrier()
; #define PG8_SCHED __builtin_amdgcn_sched_barrier(0)
; template <class Epi, class Sched>
; __device__ __forceinline__ void gemm_phase(LAS unsigned char* lds, const Gemm g, const Sched& S, const Epi& E) {
;     ...
;             const bool last = (t == nt - 2);
;             if (last && has_next) S.a_ready(nxt);
;             if constexpr (Sched::TWO_HALVES) { if (t == KSW - 2) S.half_ready(cur); }
;             const char* a1 = cA + PG8_KOFF(t + 1) * (long)kstep;
;             const char* a2 = last ? nA : cA + PG8_KOFF(t + 2) * (long)kstep; const char* b2 = last ? nB : cB + PG8_KOFF(t + 2) * (long)kstep;
;             const char* a3 = a2 + kstep; const char* b3 = b2 + kstep;
;             if constexpr (Epi::HAS_MID) { if (t == Epi::MID_T) E.mid(acc, cur, wr, wc, fr, fq); }
;             PG8_LDB(B0, 0, 0); PG8_LDB(B1, 0, 1); PG8_SCHED; PG8_LDA(At, 0, 0); PG8_STAGE(PG8_SA(1, 1), a1 + hstepA, voffA);
;             PG8_WAIT_V(8); PG8_WAIT_L(0); PG8_BAR; PG8_MMA(0, 0, At, B0); PG8_MMA(0, 1, At, B1); PG8_BAR; PG8_SCHED;
;             PG8_LDA(At, 0, 1); PG8_STAGE(PG8_SB(0, 0), b2, voffB); PG8_STAGE(PG8_SB(0, 1), b2 + hstepB, voffB); PG8_STAGE(PG8_SA(0, 0), a2, voffA);
.LBB0_782:
	ds_read_b128 v[122:125], v243
	ds_read_b128 v[126:129], v243 offset:1024
	ds_read_b128 v[130:133], v243 offset:2048
	ds_read_b128 v[134:137], v243 offset:3072
	ds_read_b128 v[146:149], v244
	ds_read_b128 v[150:153], v244 offset:1024
	ds_read_b128 v[154:157], v244 offset:2048
	ds_read_b128 v[158:161], v244 offset:3072
	s_cmp_eq_u32 s50, 12
	s_cselect_b32 s74, s39, s46
	s_cselect_b32 s75, s5, s47
	s_cselect_b32 s72, s43, s48
	s_cselect_b32 s73, s41, s49
	s_add_u32 s36, s74, 0x80
	s_addc_u32 s37, s75, 0
	ds_read_b128 v[162:165], v245
	ds_read_b128 v[166:169], v245 offset:1024
	ds_read_b128 v[170:173], v245 offset:2048
	ds_read_b128 v[174:177], v245 offset:3072
	ds_read_b128 v[178:181], v245 offset:4096
	ds_read_b128 v[182:185], v245 offset:5120
	ds_read_b128 v[186:189], v245 offset:6144
	ds_read_b128 v[190:193], v245 offset:7168
	s_add_u32 s94, s46, 0xffffff80
	s_addc_u32 s95, s47, -1
	s_mov_b32 m0, s81
	s_nop 0
	global_load_lds_dwordx4 v237, s[94:95]
	s_mov_b32 m0, s82
	s_nop 0
	global_load_lds_dwordx4 v239, s[94:95]
	s_add_u32 s94, s46, 0x3ff80
	s_addc_u32 s95, s47, 0
	s_mov_b32 m0, s85
	s_nop 0
	global_load_lds_dwordx4 v237, s[94:95]
	s_nop 0
	s_mov_b32 m0, s86
	s_nop 0
	global_load_lds_dwordx4 v239, s[94:95]
	s_waitcnt vmcnt(8)
	s_waitcnt lgkmcnt(0)
	s_barrier
	s_setprio 1
	s_waitcnt lgkmcnt(7)
	v_mfma_f32_16x16x32_bf16 v[142:145], v[122:125], v[162:165], v[142:145]
	v_mfma_f32_16x16x32_bf16 v[138:141], v[130:133], v[162:165], v[138:141]
	s_waitcnt lgkmcnt(5)
	v_mfma_f32_16x16x32_bf16 v[110:113], v[122:125], v[170:173], v[110:113]
	v_mfma_f32_16x16x32_bf16 v[106:109], v[130:133], v[170:173], v[106:109]
	s_waitcnt lgkmcnt(3)
	v_mfma_f32_16x16x32_bf16 v[94:97], v[122:125], v[178:181], v[94:97]
	v_mfma_f32_16x16x32_bf16 v[90:93], v[130:133], v[178:181], v[90:93]
	s_waitcnt lgkmcnt(1)
	v_mfma_f32_16x16x32_bf16 v[62:65], v[122:125], v[186:189], v[62:65]
	v_mfma_f32_16x16x32_bf16 v[58:61], v[130:133], v[186:189], v[58:61]
	v_mfma_f32_16x16x32_bf16 v[142:145], v[126:129], v[166:169], v[142:145]
	v_mfma_f32_16x16x32_bf16 v[138:141], v[134:137], v[166:169], v[138:141]
	v_mfma_f32_16x16x32_bf16 v[110:113], v[126:129], v[174:177], v[110:113]
	v_mfma_f32_16x16x32_bf16 v[106:109], v[134:137], v[174:177], v[106:109]
	v_mfma_f32_16x16x32_bf16 v[94:97], v[126:129], v[182:185], v[94:97]
	v_mfma_f32_16x16x32_bf16 v[90:93], v[134:137], v[182:185], v[90:93]
	s_waitcnt lgkmcnt(0)
	v_mfma_f32_16x16x32_bf16 v[62:65], v[126:129], v[190:193], v[62:65]
	v_mfma_f32_16x16x32_bf16 v[58:61], v[134:137], v[190:193], v[58:61]
	s_setprio 0
	s_setprio 1
	v_mfma_f32_16x16x32_bf16 v[118:121], v[146:149], v[162:165], v[118:121]
	v_mfma_f32_16x16x32_bf16 v[114:117], v[154:157], v[162:165], v[114:117]
	v_mfma_f32_16x16x32_bf16 v[102:105], v[146:149], v[170:173], v[102:105]
	v_mfma_f32_16x16x32_bf16 v[98:101], v[154:157], v[170:173], v[98:101]
	v_mfma_f32_16x16x32_bf16 v[78:81], v[146:149], v[178:181], v[78:81]
	v_mfma_f32_16x16x32_bf16 v[74:77], v[154:157], v[178:181], v[74:77]
	v_mfma_f32_16x16x32_bf16 v[46:49], v[146:149], v[186:189], v[46:49]
	v_mfma_f32_16x16x32_bf16 v[42:45], v[154:157], v[186:189], v[42:45]
	v_mfma_f32_16x16x32_bf16 v[118:121], v[150:153], v[166:169], v[118:121]
	v_mfma_f32_16x16x32_bf16 v[114:117], v[158:161], v[166:169], v[114:117]
	v_mfma_f32_16x16x32_bf16 v[102:105], v[150:153], v[174:177], v[102:105]
	v_mfma_f32_16x16x32_bf16 v[98:101], v[158:161], v[174:177], v[98:101]
	v_mfma_f32_16x16x32_bf16 v[78:81], v[150:153], v[182:185], v[78:81]
	v_mfma_f32_16x16x32_bf16 v[74:77], v[158:161], v[182:185], v[74:77]
	v_mfma_f32_16x16x32_bf16 v[46:49], v[150:153], v[190:193], v[46:49]
	v_mfma_f32_16x16x32_bf16 v[42:45], v[158:161], v[190:193], v[42:45]
	s_setprio 0
	s_barrier
	ds_read_b128 v[162:165], v245 offset:16384
	ds_read_b128 v[166:169], v245 offset:17408
	ds_read_b128 v[170:173], v245 offset:18432
	ds_read_b128 v[174:177], v245 offset:19456
	ds_read_b128 v[178:181], v245 offset:20480
	ds_read_b128 v[182:185], v245 offset:21504
	ds_read_b128 v[186:189], v245 offset:22528
	ds_read_b128 v[190:193], v245 offset:23552
	s_mov_b32 m0, s31
	s_nop 0
	global_load_lds_dwordx4 v238, s[72:73]
	s_add_u32 s94, s72, 0x40000
	s_mov_b32 m0, s33
	s_nop 0
	global_load_lds_dwordx4 v240, s[72:73]
	s_addc_u32 s95, s73, 0
	s_mov_b32 m0, s34
	s_nop 0
	global_load_lds_dwordx4 v238, s[94:95]
	s_nop 0
	s_mov_b32 m0, s35
	s_nop 0
	global_load_lds_dwordx4 v240, s[94:95]
	s_nop 0
	s_waitcnt vmcnt(6)
	s_waitcnt lgkmcnt(0)
	s_barrier
; #define PG8_STAGE(bufoff, gbase, voff) do { _Pragma("unroll") for (int _i = 0; _i < 2; ++_i) \
;         asm volatile("s_mov_b32 m0, %0\n\ts_nop 0\n\tglobal_load_lds_dwordx4 %1, %2" :: "s"(ldsb + (unsigned)(bufoff) + ldsw + (unsigned)(_i * 8192)), "v"((voff)[_i]), "s"((const char*)(gbase)) : "memory", "m0"); } while (0)
; #define PG8_LDA(dst, b, h) do { _Pragma("unroll") for (int m = 0; m < 4; ++m) _Pragma("unroll") for (int k = 0; k < 2; ++k) dst[m][k] = *(const LAS bf16x8*)(lds + PG8_SA(b, h) + aoff + m * 2048 + k * 1024); } while (0)
; #define PG8_LDB(dst, b, h) do { _Pragma("unroll") for (int n = 0; n < 2; ++n) _Pragma("unroll") for (int k = 0; k < 2; ++k) dst[n][k] = *(const LAS bf16x8*)(lds + PG8_SB(b, h) + boff + n * 2048 + k * 1024); } while (0)
; #define PG8_MMA(ai, bj, At, Bt) do { __builtin_amdgcn_s_setprio(1); _Pragma("unroll") for (int m = 0; m < 4; ++m) _Pragma("unroll") for (int n = 0; n < 2; ++n) _Pragma("unroll") for (int k = 0; k < 2; ++k) \
;         acc[ai][bj][m][n] = __builtin_amdgcn_mfma_f32_16x16x32_bf16(Bt[n][k], At[m][k], acc[ai][bj][m][n], 0, 0, 0); __builtin_amdgcn_s_setprio(0); } while (0)
; #define PG8_WAIT_V(n) asm volatile("s_waitcnt vmcnt(" #n ")" ::: "memory")
; #define PG8_WAIT_L(n) asm volatile("s_waitcnt lgkmcnt(" #n ")" ::: "memory")
; #define PG8_BAR __builtin_amdgcn_s_barrier()
; #define PG8_SCHED __builtin_amdgcn_sched_barrier(0)
; template <class Epi, class Sched>
; __device__ __forceinline__ void gemm_phase(LAS unsigned char* lds, const Gemm g, const Sched& S, const Epi& E) {
;     ...
;             PG8_WAIT_V(8); PG8_WAIT_L(0); PG8_BAR; PG8_MMA(1, 0, At, B0); PG8_MMA(1, 1, At, B1); PG8_BAR; PG8_SCHED;
;             PG8_LDB(B0, 1, 0); PG8_LDB(B1, 1, 1); PG8_SCHED; PG8_LDA(At, 1, 0); PG8_STAGE(PG8_SA(0, 1), a2 + hstepA, voffA);
;             PG8_WAIT_V(8); PG8_WAIT_L(0); PG8_BAR; PG8_MMA(0, 0, At, B0); PG8_MMA(0, 1, At, B1); PG8_BAR; PG8_SCHED;
	s_setprio 1
	s_waitcnt lgkmcnt(7)
	v_mfma_f32_16x16x32_bf16 v[86:89], v[122:125], v[162:165], v[86:89]
	v_mfma_f32_16x16x32_bf16 v[82:85], v[130:133], v[162:165], v[82:85]
	s_waitcnt lgkmcnt(5)
	v_mfma_f32_16x16x32_bf16 v[54:57], v[122:125], v[170:173], v[54:57]
	v_mfma_f32_16x16x32_bf16 v[50:53], v[130:133], v[170:173], v[50:53]
	s_waitcnt lgkmcnt(3)
	v_mfma_f32_16x16x32_bf16 v[30:33], v[122:125], v[178:181], v[30:33]
	v_mfma_f32_16x16x32_bf16 v[26:29], v[130:133], v[178:181], v[26:29]
	s_waitcnt lgkmcnt(1)
	v_mfma_f32_16x16x32_bf16 v[14:17], v[122:125], v[186:189], v[14:17]
	v_mfma_f32_16x16x32_bf16 v[10:13], v[130:133], v[186:189], v[10:13]
	v_mfma_f32_16x16x32_bf16 v[86:89], v[126:129], v[166:169], v[86:89]
	v_mfma_f32_16x16x32_bf16 v[82:85], v[134:137], v[166:169], v[82:85]
	v_mfma_f32_16x16x32_bf16 v[54:57], v[126:129], v[174:177], v[54:57]
	v_mfma_f32_16x16x32_bf16 v[50:53], v[134:137], v[174:177], v[50:53]
	v_mfma_f32_16x16x32_bf16 v[30:33], v[126:129], v[182:185], v[30:33]
	v_mfma_f32_16x16x32_bf16 v[26:29], v[134:137], v[182:185], v[26:29]
	s_waitcnt lgkmcnt(0)
	v_mfma_f32_16x16x32_bf16 v[14:17], v[126:129], v[190:193], v[14:17]
	v_mfma_f32_16x16x32_bf16 v[10:13], v[134:137], v[190:193], v[10:13]
	s_setprio 0
	s_setprio 1
	v_mfma_f32_16x16x32_bf16 v[70:73], v[146:149], v[162:165], v[70:73]
	v_mfma_f32_16x16x32_bf16 v[66:69], v[154:157], v[162:165], v[66:69]
	v_mfma_f32_16x16x32_bf16 v[38:41], v[146:149], v[170:173], v[38:41]
	v_mfma_f32_16x16x32_bf16 v[34:37], v[154:157], v[170:173], v[34:37]
	v_mfma_f32_16x16x32_bf16 v[22:25], v[146:149], v[178:181], v[22:25]
	v_mfma_f32_16x16x32_bf16 v[18:21], v[154:157], v[178:181], v[18:21]
	v_mfma_f32_16x16x32_bf16 v[6:9], v[146:149], v[186:189], v[6:9]
	v_mfma_f32_16x16x32_bf16 v[2:5], v[154:157], v[186:189], v[2:5]
	v_mfma_f32_16x16x32_bf16 v[70:73], v[150:153], v[166:169], v[70:73]
	v_mfma_f32_16x16x32_bf16 v[66:69], v[158:161], v[166:169], v[66:69]
	v_mfma_f32_16x16x32_bf16 v[38:41], v[150:153], v[174:177], v[38:41]
	v_mfma_f32_16x16x32_bf16 v[34:37], v[158:161], v[174:177], v[34:37]
	v_mfma_f32_16x16x32_bf16 v[22:25], v[150:153], v[182:185], v[22:25]
	v_mfma_f32_16x16x32_bf16 v[18:21], v[158:161], v[182:185], v[18:21]
	v_mfma_f32_16x16x32_bf16 v[6:9], v[150:153], v[190:193], v[6:9]
	v_mfma_f32_16x16x32_bf16 v[2:5], v[158:161], v[190:193], v[2:5]
	s_setprio 0
	s_barrier
	ds_read_b128 v[122:125], v246
	ds_read_b128 v[126:129], v246 offset:1024
	ds_read_b128 v[130:133], v246 offset:2048
	ds_read_b128 v[134:137], v246 offset:3072
	ds_read_b128 v[146:149], v247
	ds_read_b128 v[150:153], v247 offset:1024
	ds_read_b128 v[154:157], v247 offset:2048
	ds_read_b128 v[158:161], v247 offset:3072
	ds_read_b128 v[162:165], v245 offset:32768
	ds_read_b128 v[166:169], v245 offset:33792
	ds_read_b128 v[170:173], v245 offset:34816
	ds_read_b128 v[174:177], v245 offset:35840
	ds_read_b128 v[178:181], v245 offset:36864
	ds_read_b128 v[182:185], v245 offset:37888
	ds_read_b128 v[186:189], v245 offset:38912
	ds_read_b128 v[190:193], v245 offset:39936
	s_mov_b32 m0, s29
	s_nop 0
	global_load_lds_dwordx4 v237, s[74:75]
	s_mov_b32 m0, s76
	s_nop 0
	global_load_lds_dwordx4 v239, s[74:75]
	s_add_u32 s74, s74, 0x40000
	s_addc_u32 s75, s75, 0
	s_mov_b32 m0, s77
	s_nop 0
	global_load_lds_dwordx4 v237, s[74:75]
	s_nop 0
	s_mov_b32 m0, s78
	s_nop 0
	global_load_lds_dwordx4 v239, s[74:75]
	s_waitcnt vmcnt(8)
	s_waitcnt lgkmcnt(0)
	s_barrier
; #define PG8_STAGE(bufoff, gbase, voff) do { _Pragma("unroll") for (int _i = 0; _i < 2; ++_i) \
;         asm volatile("s_mov_b32 m0, %0\n\ts_nop 0\n\tglobal_load_lds_dwordx4 %1, %2" :: "s"(ldsb + (unsigned)(bufoff) + ldsw + (unsigned)(_i * 8192)), "v"((voff)[_i]), "s"((const char*)(gbase)) : "memory", "m0"); } while (0)
; #define PG8_LDA(dst, b, h) do { _Pragma("unroll") for (int m = 0; m < 4; ++m) _Pragma("unroll") for (int k = 0; k < 2; ++k) dst[m][k] = *(const LAS bf16x8*)(lds + PG8_SA(b, h) + aoff + m * 2048 + k * 1024); } while (0)
; #define PG8_MMA(ai, bj, At, Bt) do { __builtin_amdgcn_s_setprio(1); _Pragma("unroll") for (int m = 0; m < 4; ++m) _Pragma("unroll") for (int n = 0; n < 2; ++n) _Pragma("unroll") for (int k = 0; k < 2; ++k) \
;         acc[ai][bj][m][n] = __builtin_amdgcn_mfma_f32_16x16x32_bf16(Bt[n][k], At[m][k], acc[ai][bj][m][n], 0, 0, 0); __builtin_amdgcn_s_setprio(0); } while (0)
; #define PG8_WAIT_V(n) asm volatile("s_waitcnt vmcnt(" #n ")" ::: "memory")
; #define PG8_WAIT_L(n) asm volatile("s_waitcnt lgkmcnt(" #n ")" ::: "memory")
; #define PG8_BAR __builtin_amdgcn_s_barrier()
; #define PG8_SCHED __builtin_amdgcn_sched_barrier(0)
; template <class Epi, class Sched>
; __device__ __forceinline__ void gemm_phase(LAS unsigned char* lds, const Gemm g, const Sched& S, const Epi& E) {
;     ...
;             PG8_WAIT_V(8); PG8_WAIT_L(0); PG8_BAR; PG8_MMA(0, 0, At, B0); PG8_MMA(0, 1, At, B1); PG8_BAR; PG8_SCHED;
;             PG8_LDA(At, 1, 1); PG8_STAGE(PG8_SB(1, 0), b3, voffB); PG8_STAGE(PG8_SB(1, 1), b3 + hstepB, voffB); PG8_STAGE(PG8_SA(1, 0), a3, voffA);
;             PG8_WAIT_V(8); PG8_WAIT_L(0); PG8_BAR; PG8_MMA(1, 0, At, B0); PG8_MMA(1, 1, At, B1); PG8_BAR; PG8_SCHED;
;         }
	s_setprio 1
	s_waitcnt lgkmcnt(7)
	v_mfma_f32_16x16x32_bf16 v[142:145], v[122:125], v[162:165], v[142:145]
	v_mfma_f32_16x16x32_bf16 v[138:141], v[130:133], v[162:165], v[138:141]
	s_waitcnt lgkmcnt(5)
	v_mfma_f32_16x16x32_bf16 v[110:113], v[122:125], v[170:173], v[110:113]
	v_mfma_f32_16x16x32_bf16 v[106:109], v[130:133], v[170:173], v[106:109]
	s_waitcnt lgkmcnt(3)
	v_mfma_f32_16x16x32_bf16 v[94:97], v[122:125], v[178:181], v[94:97]
	v_mfma_f32_16x16x32_bf16 v[90:93], v[130:133], v[178:181], v[90:93]
	s_waitcnt lgkmcnt(1)
	v_mfma_f32_16x16x32_bf16 v[62:65], v[122:125], v[186:189], v[62:65]
	v_mfma_f32_16x16x32_bf16 v[58:61], v[130:133], v[186:189], v[58:61]
	v_mfma_f32_16x16x32_bf16 v[142:145], v[126:129], v[166:169], v[142:145]
	v_mfma_f32_16x16x32_bf16 v[138:141], v[134:137], v[166:169], v[138:141]
	v_mfma_f32_16x16x32_bf16 v[110:113], v[126:129], v[174:177], v[110:113]
	v_mfma_f32_16x16x32_bf16 v[106:109], v[134:137], v[174:177], v[106:109]
	v_mfma_f32_16x16x32_bf16 v[94:97], v[126:129], v[182:185], v[94:97]
	v_mfma_f32_16x16x32_bf16 v[90:93], v[134:137], v[182:185], v[90:93]
	s_waitcnt lgkmcnt(0)
	v_mfma_f32_16x16x32_bf16 v[62:65], v[126:129], v[190:193], v[62:65]
	v_mfma_f32_16x16x32_bf16 v[58:61], v[134:137], v[190:193], v[58:61]
	s_setprio 0
	s_setprio 1
	v_mfma_f32_16x16x32_bf16 v[118:121], v[146:149], v[162:165], v[118:121]
	v_mfma_f32_16x16x32_bf16 v[114:117], v[154:157], v[162:165], v[114:117]
	v_mfma_f32_16x16x32_bf16 v[102:105], v[146:149], v[170:173], v[102:105]
	v_mfma_f32_16x16x32_bf16 v[98:101], v[154:157], v[170:173], v[98:101]
	v_mfma_f32_16x16x32_bf16 v[78:81], v[146:149], v[178:181], v[78:81]
	v_mfma_f32_16x16x32_bf16 v[74:77], v[154:157], v[178:181], v[74:77]
	v_mfma_f32_16x16x32_bf16 v[46:49], v[146:149], v[186:189], v[46:49]
	v_mfma_f32_16x16x32_bf16 v[42:45], v[154:157], v[186:189], v[42:45]
	v_mfma_f32_16x16x32_bf16 v[118:121], v[150:153], v[166:169], v[118:121]
	v_mfma_f32_16x16x32_bf16 v[114:117], v[158:161], v[166:169], v[114:117]
	v_mfma_f32_16x16x32_bf16 v[102:105], v[150:153], v[174:177], v[102:105]
	v_mfma_f32_16x16x32_bf16 v[98:101], v[158:161], v[174:177], v[98:101]
	v_mfma_f32_16x16x32_bf16 v[78:81], v[150:153], v[182:185], v[78:81]
	v_mfma_f32_16x16x32_bf16 v[74:77], v[158:161], v[182:185], v[74:77]
	v_mfma_f32_16x16x32_bf16 v[46:49], v[150:153], v[190:193], v[46:49]
	v_mfma_f32_16x16x32_bf16 v[42:45], v[158:161], v[190:193], v[42:45]
	s_setprio 0
	s_barrier
	ds_read_b128 v[162:165], v245 offset:49152
	ds_read_b128 v[166:169], v245 offset:50176
	ds_read_b128 v[170:173], v245 offset:51200
	ds_read_b128 v[174:177], v245 offset:52224
	ds_read_b128 v[178:181], v245 offset:53248
	ds_read_b128 v[182:185], v245 offset:54272
	ds_read_b128 v[186:189], v245 offset:55296
	ds_read_b128 v[190:193], v245 offset:56320
	s_add_u32 s74, s72, 0x80
	s_addc_u32 s75, s73, 0
	s_mov_b32 m0, s79
	s_nop 0
	global_load_lds_dwordx4 v238, s[74:75]
	s_add_u32 s72, s72, 0x40080
	s_mov_b32 m0, s80
	s_nop 0
	global_load_lds_dwordx4 v240, s[74:75]
	s_addc_u32 s73, s73, 0
	s_mov_b32 m0, s83
	s_nop 0
	global_load_lds_dwordx4 v238, s[72:73]
	s_nop 0
	s_mov_b32 m0, s84
	s_nop 0
	global_load_lds_dwordx4 v240, s[72:73]
	s_nop 0
	s_waitcnt vmcnt(6)
	s_waitcnt lgkmcnt(0)
	s_barrier
	s_setprio 1
	s_waitcnt lgkmcnt(7)
	v_mfma_f32_16x16x32_bf16 v[86:89], v[122:125], v[162:165], v[86:89]
	v_mfma_f32_16x16x32_bf16 v[82:85], v[130:133], v[162:165], v[82:85]
	s_waitcnt lgkmcnt(5)
	v_mfma_f32_16x16x32_bf16 v[54:57], v[122:125], v[170:173], v[54:57]
	v_mfma_f32_16x16x32_bf16 v[50:53], v[130:133], v[170:173], v[50:53]
	s_waitcnt lgkmcnt(3)
	v_mfma_f32_16x16x32_bf16 v[30:33], v[122:125], v[178:181], v[30:33]
	v_mfma_f32_16x16x32_bf16 v[26:29], v[130:133], v[178:181], v[26:29]
	s_waitcnt lgkmcnt(1)
	v_mfma_f32_16x16x32_bf16 v[14:17], v[122:125], v[186:189], v[14:17]
	v_mfma_f32_16x16x32_bf16 v[10:13], v[130:133], v[186:189], v[10:13]
	v_mfma_f32_16x16x32_bf16 v[86:89], v[126:129], v[166:169], v[86:89]
	v_mfma_f32_16x16x32_bf16 v[82:85], v[134:137], v[166:169], v[82:85]
	v_mfma_f32_16x16x32_bf16 v[54:57], v[126:129], v[174:177], v[54:57]
	v_mfma_f32_16x16x32_bf16 v[50:53], v[134:137], v[174:177], v[50:53]
	v_mfma_f32_16x16x32_bf16 v[30:33], v[126:129], v[182:185], v[30:33]
	v_mfma_f32_16x16x32_bf16 v[26:29], v[134:137], v[182:185], v[26:29]
	s_waitcnt lgkmcnt(0)
	v_mfma_f32_16x16x32_bf16 v[14:17], v[126:129], v[190:193], v[14:17]
	v_mfma_f32_16x16x32_bf16 v[10:13], v[134:137], v[190:193], v[10:13]
	s_setprio 0
	s_setprio 1
	v_mfma_f32_16x16x32_bf16 v[70:73], v[146:149], v[162:165], v[70:73]
	v_mfma_f32_16x16x32_bf16 v[66:69], v[154:157], v[162:165], v[66:69]
	v_mfma_f32_16x16x32_bf16 v[38:41], v[146:149], v[170:173], v[38:41]
	v_mfma_f32_16x16x32_bf16 v[34:37], v[154:157], v[170:173], v[34:37]
	v_mfma_f32_16x16x32_bf16 v[22:25], v[146:149], v[178:181], v[22:25]
	v_mfma_f32_16x16x32_bf16 v[18:21], v[154:157], v[178:181], v[18:21]
	v_mfma_f32_16x16x32_bf16 v[6:9], v[146:149], v[186:189], v[6:9]
	v_mfma_f32_16x16x32_bf16 v[2:5], v[154:157], v[186:189], v[2:5]
	v_mfma_f32_16x16x32_bf16 v[70:73], v[150:153], v[166:169], v[70:73]
	v_mfma_f32_16x16x32_bf16 v[66:69], v[158:161], v[166:169], v[66:69]
	v_mfma_f32_16x16x32_bf16 v[38:41], v[150:153], v[174:177], v[38:41]
	v_mfma_f32_16x16x32_bf16 v[34:37], v[158:161], v[174:177], v[34:37]
	v_mfma_f32_16x16x32_bf16 v[22:25], v[150:153], v[182:185], v[22:25]
	v_mfma_f32_16x16x32_bf16 v[18:21], v[158:161], v[182:185], v[18:21]
	v_mfma_f32_16x16x32_bf16 v[6:9], v[150:153], v[190:193], v[6:9]
	v_mfma_f32_16x16x32_bf16 v[2:5], v[158:161], v[190:193], v[2:5]
	s_setprio 0
	s_barrier
	s_add_i32 s50, s50, 2
	s_add_u32 s46, s46, 0x100
	s_addc_u32 s47, s47, 0
	s_add_u32 s48, s48, 0x100
	s_addc_u32 s49, s49, 0
	s_cmp_gt_u32 s50, 13
	s_cbranch_scc0 .LBB0_782

;     __device__ __forceinline__ void a_ready(const Unit&) const { wait_cnt(w_ready, w_need); }
;     __device__ __forceinline__ void half_ready(const Unit& u) const { wait_cnt(g_ready + 64 * u.pm, g_need); }
; #define PG8_STAGE(bufoff, gbase, voff) do { _Pragma("unroll") for (int _i = 0; _i < 2; ++_i) \
;         asm volatile("s_mov_b32 m0, %0\n\ts_nop 0\n\tglobal_load_lds_dwordx4 %1, %2" :: "s"(ldsb + (unsigned)(bufoff) + ldsw + (unsigned)(_i * 8192)), "v"((voff)[_i]), "s"((const char*)(gbase)) : "memory", "m0"); } while (0)
; #define PG8_LDA(dst, b, h) do { _Pragma("unroll") for (int m = 0; m < 4; ++m) _Pragma("unroll") for (int k = 0; k < 2; ++k) dst[m][k] = *(const LAS bf16x8*)(lds + PG8_SA(b, h) + aoff + m * 2048 + k * 1024); } while (0)
; #define PG8_LDB(dst, b, h) do { _Pragma("unroll") for (int n = 0; n < 2; ++n) _Pragma("unroll") for (int k = 0; k < 2; ++k) dst[n][k] = *(const LAS bf16x8*)(lds + PG8_SB(b, h) + boff + n * 2048 + k * 1024); } while (0)
; #define PG8_WAIT_V(n) asm volatile("s_waitcnt vmcnt(" #n ")" ::: "memory")
; template <class Epi, class Sched>
; __device__ __forceinline__ void gemm_phase(LAS unsigned char* lds, const Gemm g, const Sched& S, const Epi& E) {
;     ...
;             const bool last = (t == nt - 2);
;             if (last && has_next) S.a_ready(nxt);
;             if constexpr (Sched::TWO_HALVES) { if (t == KSW - 2) S.half_ready(cur); }
;             const char* a1 = cA + PG8_KOFF(t + 1) * (long)kstep;
;             const char* a2 = last ? nA : cA + PG8_KOFF(t + 2) * (long)kstep; const char* b2 = last ? nB : cB + PG8_KOFF(t + 2) * (long)kstep;
;             const char* a3 = a2 + kstep; const char* b3 = b2 + kstep;
;             if constexpr (Epi::HAS_MID) { if (t == Epi::MID_T) E.mid(acc, cur, wr, wc, fr, fq); }
;             PG8_LDB(B0, 0, 0); PG8_LDB(B1, 0, 1); PG8_SCHED; PG8_LDA(At, 0, 0); PG8_STAGE(PG8_SA(1, 1), a1 + hstepA, voffA);
;             PG8_WAIT_V(8); PG8_WAIT_L(0); PG8_BAR; PG8_MMA(0, 0, At, B0); PG8_MMA(0, 1, At, B1); PG8_BAR; PG8_SCHED;
;             PG8_LDA(At, 0, 1); PG8_STAGE(PG8_SB(0, 0), b2, voffB); PG8_STAGE(PG8_SB(0, 1), b2 + hstepB, voffB); PG8_STAGE(PG8_SA(0, 0), a2, voffA);
;             PG8_WAIT_V(8); PG8_WAIT_L(0); PG8_BAR; PG8_BAR; PG8_SCHED;
;             PG8_LDB(B0, 1, 0); PG8_LDB(B1, 1, 1); PG8_SCHED; PG8_LDA(At, 1, 0); PG8_STAGE(PG8_SA(0, 1), a2 + hstepA, voffA);
.LBB0_807:
	s_waitcnt lgkmcnt(0)
	ds_read_b128 v[2:5], v243
	ds_read_b128 v[6:9], v243 offset:1024
	ds_read_b128 v[10:13], v243 offset:2048
	ds_read_b128 v[14:17], v243 offset:3072
	ds_read_b128 v[18:21], v244
	ds_read_b128 v[22:25], v244 offset:1024
	ds_read_b128 v[26:29], v244 offset:2048
	ds_read_b128 v[30:33], v244 offset:3072
	s_cmp_eq_u32 s46, 12
	s_cselect_b32 s74, s39, s91
	s_cselect_b32 s75, s5, s92
	s_cselect_b32 s72, s43, s89
	s_cselect_b32 s73, s41, s90
	s_add_u32 s36, s74, 0x80
	s_addc_u32 s37, s75, 0
	ds_read_b128 v[34:37], v245
	ds_read_b128 v[38:41], v245 offset:1024
	ds_read_b128 v[50:53], v245 offset:2048
	ds_read_b128 v[54:57], v245 offset:3072
	ds_read_b128 v[66:69], v245 offset:4096
	ds_read_b128 v[70:73], v245 offset:5120
	ds_read_b128 v[82:85], v245 offset:6144
	ds_read_b128 v[86:89], v245 offset:7168
	s_add_u32 s48, s91, 0xffffff80
	s_addc_u32 s49, s92, -1
	s_mov_b32 m0, s81
	s_nop 0
	global_load_lds_dwordx4 v237, s[48:49]
	s_mov_b32 m0, s82
	s_nop 0
	global_load_lds_dwordx4 v239, s[48:49]
	s_add_u32 s48, s91, 0x3ff80
	s_addc_u32 s49, s92, 0
	s_mov_b32 m0, s85
	s_nop 0
	global_load_lds_dwordx4 v237, s[48:49]
	s_nop 0
	s_mov_b32 m0, s86
	s_nop 0
	global_load_lds_dwordx4 v239, s[48:49]
	s_waitcnt vmcnt(8)
	s_waitcnt lgkmcnt(0)
	s_barrier
	s_setprio 1
	s_waitcnt lgkmcnt(7)
	v_mfma_f32_16x16x32_bf16 v[122:125], v[2:5], v[34:37], v[142:145]
	s_waitcnt lgkmcnt(5)
	v_mfma_f32_16x16x32_bf16 v[110:113], v[2:5], v[50:53], v[110:113]
	v_mfma_f32_16x16x32_bf16 v[106:109], v[10:13], v[50:53], v[106:109]
	s_waitcnt lgkmcnt(3)
	v_mfma_f32_16x16x32_bf16 v[94:97], v[2:5], v[66:69], v[94:97]
	v_mfma_f32_16x16x32_bf16 v[90:93], v[10:13], v[66:69], v[90:93]
	s_waitcnt lgkmcnt(1)
	v_mfma_f32_16x16x32_bf16 v[2:5], v[2:5], v[82:85], v[62:65]
	v_mfma_f32_16x16x32_bf16 v[122:125], v[6:9], v[38:41], v[122:125]
	v_mfma_f32_16x16x32_bf16 v[126:129], v[10:13], v[34:37], v[138:141]
	v_mfma_f32_16x16x32_bf16 v[110:113], v[6:9], v[54:57], v[110:113]
	v_mfma_f32_16x16x32_bf16 v[106:109], v[14:17], v[54:57], v[106:109]
	v_mfma_f32_16x16x32_bf16 v[94:97], v[6:9], v[70:73], v[94:97]
	v_mfma_f32_16x16x32_bf16 v[90:93], v[14:17], v[70:73], v[90:93]
	s_waitcnt lgkmcnt(0)
	v_mfma_f32_16x16x32_bf16 v[2:5], v[6:9], v[86:89], v[2:5]
	v_mfma_f32_16x16x32_bf16 v[6:9], v[10:13], v[82:85], v[58:61]
	v_mfma_f32_16x16x32_bf16 v[126:129], v[14:17], v[38:41], v[126:129]
	v_mfma_f32_16x16x32_bf16 v[6:9], v[14:17], v[86:89], v[6:9]
	s_setprio 0
	s_setprio 1
	v_mfma_f32_16x16x32_bf16 v[10:13], v[18:21], v[34:37], v[118:121]
	v_mfma_f32_16x16x32_bf16 v[14:17], v[26:29], v[34:37], v[114:117]
	v_mfma_f32_16x16x32_bf16 v[10:13], v[22:25], v[38:41], v[10:13]
	v_mfma_f32_16x16x32_bf16 v[14:17], v[30:33], v[38:41], v[14:17]
	v_mfma_f32_16x16x32_bf16 v[34:37], v[18:21], v[50:53], v[102:105]
	v_mfma_f32_16x16x32_bf16 v[38:41], v[26:29], v[50:53], v[98:101]
	v_mfma_f32_16x16x32_bf16 v[50:53], v[18:21], v[66:69], v[78:81]
	v_mfma_f32_16x16x32_bf16 v[18:21], v[18:21], v[82:85], v[46:49]
	v_mfma_f32_16x16x32_bf16 v[34:37], v[22:25], v[54:57], v[34:37]
	v_mfma_f32_16x16x32_bf16 v[38:41], v[30:33], v[54:57], v[38:41]
	v_mfma_f32_16x16x32_bf16 v[50:53], v[22:25], v[70:73], v[50:53]
	v_mfma_f32_16x16x32_bf16 v[54:57], v[26:29], v[66:69], v[74:77]
	v_mfma_f32_16x16x32_bf16 v[18:21], v[22:25], v[86:89], v[18:21]
	v_mfma_f32_16x16x32_bf16 v[22:25], v[26:29], v[82:85], v[42:45]
	v_mfma_f32_16x16x32_bf16 v[54:57], v[30:33], v[70:73], v[54:57]
	v_mfma_f32_16x16x32_bf16 v[22:25], v[30:33], v[86:89], v[22:25]
	s_setprio 0
	s_barrier
	s_mov_b32 m0, s31
	s_nop 0
	global_load_lds_dwordx4 v238, s[72:73]
	s_add_u32 s48, s72, 0x40000
	s_mov_b32 m0, s33
	s_nop 0
	global_load_lds_dwordx4 v240, s[72:73]
	s_addc_u32 s49, s73, 0
	s_mov_b32 m0, s34
	s_nop 0
	global_load_lds_dwordx4 v238, s[48:49]
	s_nop 0
	s_mov_b32 m0, s35
	s_nop 0
	global_load_lds_dwordx4 v240, s[48:49]
	s_nop 0
	s_waitcnt vmcnt(6)
	s_waitcnt lgkmcnt(0)
	s_barrier
	s_barrier
	ds_read_b128 v[26:29], v246
	ds_read_b128 v[30:33], v246 offset:1024
	ds_read_b128 v[42:45], v246 offset:2048
	ds_read_b128 v[46:49], v246 offset:3072
	ds_read_b128 v[66:69], v247
	ds_read_b128 v[70:73], v247 offset:1024
	ds_read_b128 v[82:85], v247 offset:2048
	ds_read_b128 v[86:89], v247 offset:3072
	ds_read_b128 v[74:77], v245 offset:32768
	ds_read_b128 v[78:81], v245 offset:33792
	ds_read_b128 v[98:101], v245 offset:34816
	ds_read_b128 v[130:133], v245 offset:35840
	ds_read_b128 v[134:137], v245 offset:36864
	ds_read_b128 v[146:149], v245 offset:37888
	ds_read_b128 v[150:153], v245 offset:38912
	ds_read_b128 v[154:157], v245 offset:39936
	s_mov_b32 m0, s29
	s_nop 0
	global_load_lds_dwordx4 v237, s[74:75]
	s_mov_b32 m0, s76
	s_nop 0
	global_load_lds_dwordx4 v239, s[74:75]
	s_add_u32 s48, s74, 0x40000
	s_addc_u32 s49, s75, 0
	s_mov_b32 m0, s77
	s_nop 0
	global_load_lds_dwordx4 v237, s[48:49]
	s_nop 0
	s_mov_b32 m0, s78
	s_nop 0
	global_load_lds_dwordx4 v239, s[48:49]
	s_waitcnt vmcnt(8)
	s_waitcnt lgkmcnt(0)
	s_barrier
; #define PG8_STAGE(bufoff, gbase, voff) do { _Pragma("unroll") for (int _i = 0; _i < 2; ++_i) \
;         asm volatile("s_mov_b32 m0, %0\n\ts_nop 0\n\tglobal_load_lds_dwordx4 %1, %2" :: "s"(ldsb + (unsigned)(bufoff) + ldsw + (unsigned)(_i * 8192)), "v"((voff)[_i]), "s"((const char*)(gbase)) : "memory", "m0"); } while (0)
; #define PG8_LDA(dst, b, h) do { _Pragma("unroll") for (int m = 0; m < 4; ++m) _Pragma("unroll") for (int k = 0; k < 2; ++k) dst[m][k] = *(const LAS bf16x8*)(lds + PG8_SA(b, h) + aoff + m * 2048 + k * 1024); } while (0)
; #define PG8_MMA(ai, bj, At, Bt) do { __builtin_amdgcn_s_setprio(1); _Pragma("unroll") for (int m = 0; m < 4; ++m) _Pragma("unroll") for (int n = 0; n < 2; ++n) _Pragma("unroll") for (int k = 0; k < 2; ++k) \
;         acc[ai][bj][m][n] = __builtin_amdgcn_mfma_f32_16x16x32_bf16(Bt[n][k], At[m][k], acc[ai][bj][m][n], 0, 0, 0); __builtin_amdgcn_s_setprio(0); } while (0)
; #define PG8_WAIT_V(n) asm volatile("s_waitcnt vmcnt(" #n ")" ::: "memory")
; #define PG8_WAIT_L(n) asm volatile("s_waitcnt lgkmcnt(" #n ")" ::: "memory")
; #define PG8_BAR __builtin_amdgcn_s_barrier()
; #define PG8_SCHED __builtin_amdgcn_sched_barrier(0)
; template <class Epi, class Sched>
; __device__ __forceinline__ void gemm_phase(LAS unsigned char* lds, const Gemm g, const Sched& S, const Epi& E) {
;     ...
;             PG8_WAIT_V(8); PG8_WAIT_L(0); PG8_BAR; PG8_MMA(0, 0, At, B0); PG8_MMA(0, 1, At, B1); PG8_BAR; PG8_SCHED;
;             PG8_LDA(At, 1, 1); PG8_STAGE(PG8_SB(1, 0), b3, voffB); PG8_STAGE(PG8_SB(1, 1), b3 + hstepB, voffB); PG8_STAGE(PG8_SA(1, 0), a3, voffA);
;             PG8_WAIT_V(8); PG8_WAIT_L(0); PG8_BAR; PG8_BAR; PG8_SCHED;
;         }
;     ...
;         for (int a = 0; a < 2; ++a)
; #pragma unroll
;             for (int b = 0; b < 2; ++b)
; #pragma unroll
;                 for (int m = 0; m < 4; ++m)
; #pragma unroll
;                     for (int n = 0; n < 2; ++n) acc[a][b][m][n] = (f32x4){0.f, 0.f, 0.f, 0.f};
	s_setprio 1
	s_waitcnt lgkmcnt(7)
	v_mfma_f32_16x16x32_bf16 v[58:61], v[26:29], v[74:77], v[122:125]
	s_waitcnt lgkmcnt(6)
	v_mfma_f32_16x16x32_bf16 v[142:145], v[30:33], v[78:81], v[58:61]
	v_mfma_f32_16x16x32_bf16 v[58:61], v[42:45], v[74:77], v[126:129]
	v_mfma_f32_16x16x32_bf16 v[138:141], v[46:49], v[78:81], v[58:61]
	s_waitcnt lgkmcnt(5)
	v_mfma_f32_16x16x32_bf16 v[58:61], v[26:29], v[98:101], v[110:113]
	s_waitcnt lgkmcnt(4)
	v_mfma_f32_16x16x32_bf16 v[110:113], v[30:33], v[130:133], v[58:61]
	v_mfma_f32_16x16x32_bf16 v[58:61], v[42:45], v[98:101], v[106:109]
	v_mfma_f32_16x16x32_bf16 v[106:109], v[46:49], v[130:133], v[58:61]
	s_waitcnt lgkmcnt(3)
	v_mfma_f32_16x16x32_bf16 v[58:61], v[26:29], v[134:137], v[94:97]
	s_waitcnt lgkmcnt(1)
	v_mfma_f32_16x16x32_bf16 v[2:5], v[26:29], v[150:153], v[2:5]
	v_mfma_f32_16x16x32_bf16 v[94:97], v[30:33], v[146:149], v[58:61]
	v_mfma_f32_16x16x32_bf16 v[58:61], v[42:45], v[134:137], v[90:93]
	s_waitcnt lgkmcnt(0)
	v_mfma_f32_16x16x32_bf16 v[62:65], v[30:33], v[154:157], v[2:5]
	v_mfma_f32_16x16x32_bf16 v[2:5], v[42:45], v[150:153], v[6:9]
	v_mfma_f32_16x16x32_bf16 v[90:93], v[46:49], v[146:149], v[58:61]
	v_mfma_f32_16x16x32_bf16 v[58:61], v[46:49], v[154:157], v[2:5]
	s_setprio 0
	s_setprio 1
	v_mfma_f32_16x16x32_bf16 v[2:5], v[66:69], v[74:77], v[10:13]
	v_mfma_f32_16x16x32_bf16 v[118:121], v[70:73], v[78:81], v[2:5]
	v_mfma_f32_16x16x32_bf16 v[2:5], v[82:85], v[74:77], v[14:17]
	v_mfma_f32_16x16x32_bf16 v[114:117], v[86:89], v[78:81], v[2:5]
	v_mfma_f32_16x16x32_bf16 v[2:5], v[66:69], v[98:101], v[34:37]
	v_mfma_f32_16x16x32_bf16 v[102:105], v[70:73], v[130:133], v[2:5]
	v_mfma_f32_16x16x32_bf16 v[2:5], v[82:85], v[98:101], v[38:41]
	v_mfma_f32_16x16x32_bf16 v[98:101], v[86:89], v[130:133], v[2:5]
	v_mfma_f32_16x16x32_bf16 v[2:5], v[66:69], v[134:137], v[50:53]
	v_mfma_f32_16x16x32_bf16 v[78:81], v[70:73], v[146:149], v[2:5]
	v_mfma_f32_16x16x32_bf16 v[2:5], v[82:85], v[134:137], v[54:57]
	v_mfma_f32_16x16x32_bf16 v[74:77], v[86:89], v[146:149], v[2:5]
	v_mfma_f32_16x16x32_bf16 v[2:5], v[66:69], v[150:153], v[18:21]
	v_mfma_f32_16x16x32_bf16 v[46:49], v[70:73], v[154:157], v[2:5]
	v_mfma_f32_16x16x32_bf16 v[2:5], v[82:85], v[150:153], v[22:25]
	v_mfma_f32_16x16x32_bf16 v[42:45], v[86:89], v[154:157], v[2:5]
	s_setprio 0
	s_barrier
	s_add_u32 s48, s72, 0x80
	s_addc_u32 s49, s73, 0
	s_mov_b32 m0, s79
	s_nop 0
	global_load_lds_dwordx4 v238, s[48:49]
	s_nop 0
	s_mov_b32 m0, s80
	s_nop 0
	global_load_lds_dwordx4 v240, s[48:49]
	s_add_u32 s48, s72, 0x40080
	s_addc_u32 s49, s73, 0
	s_mov_b32 m0, s83
	s_nop 0
	global_load_lds_dwordx4 v238, s[48:49]
	s_nop 0
	s_mov_b32 m0, s84
	s_nop 0
	global_load_lds_dwordx4 v240, s[48:49]
	s_nop 0
	s_waitcnt vmcnt(6)
	s_waitcnt lgkmcnt(0)
	s_barrier
	s_barrier
	s_add_i32 s46, s46, 2
	s_add_u32 s91, s91, 0x100
	s_addc_u32 s92, s92, 0
	s_add_u32 s89, s89, 0x100
	s_addc_u32 s90, s90, 0
	s_cmp_gt_u32 s46, 13
	s_cbranch_scc0 .LBB0_807
	v_mov_b32_e32 v89, 0
	v_mov_b32_e32 v88, v89
	v_mov_b32_e32 v87, v89
	v_mov_b32_e32 v86, v89
	v_mov_b32_e32 v85, v89
	v_mov_b32_e32 v84, v89
	v_mov_b32_e32 v83, v89
	v_mov_b32_e32 v82, v89
	v_mov_b32_e32 v57, v89
	v_mov_b32_e32 v56, v89
	v_mov_b32_e32 v55, v89
	v_mov_b32_e32 v54, v89
	v_mov_b32_e32 v53, v89
	v_mov_b32_e32 v52, v89
	v_mov_b32_e32 v51, v89
	v_mov_b32_e32 v50, v89
	v_mov_b32_e32 v33, v89
	v_mov_b32_e32 v32, v89
	v_mov_b32_e32 v31, v89
	v_mov_b32_e32 v30, v89
	v_mov_b32_e32 v29, v89
	v_mov_b32_e32 v28, v89
	v_mov_b32_e32 v27, v89
	v_mov_b32_e32 v26, v89
	v_mov_b32_e32 v17, v89
	v_mov_b32_e32 v16, v89
	v_mov_b32_e32 v15, v89
	v_mov_b32_e32 v14, v89
	v_mov_b32_e32 v13, v89
	v_mov_b32_e32 v12, v89
	v_mov_b32_e32 v11, v89
	v_mov_b32_e32 v10, v89
	v_mov_b32_e32 v73, v89
	v_mov_b32_e32 v72, v89
	v_mov_b32_e32 v71, v89
	v_mov_b32_e32 v70, v89
	v_mov_b32_e32 v69, v89
	v_mov_b32_e32 v68, v89
	v_mov_b32_e32 v67, v89
	v_mov_b32_e32 v66, v89
	v_mov_b32_e32 v41, v89
	v_mov_b32_e32 v40, v89
	v_mov_b32_e32 v39, v89
	v_mov_b32_e32 v38, v89
	v_mov_b32_e32 v37, v89
	v_mov_b32_e32 v36, v89
	v_mov_b32_e32 v35, v89
	v_mov_b32_e32 v34, v89
	v_mov_b32_e32 v25, v89
	v_mov_b32_e32 v24, v89
	v_mov_b32_e32 v23, v89
	v_mov_b32_e32 v22, v89
	v_mov_b32_e32 v21, v89
	v_mov_b32_e32 v20, v89
	v_mov_b32_e32 v19, v89
	v_mov_b32_e32 v18, v89
	v_mov_b32_e32 v9, v89
	v_mov_b32_e32 v8, v89
	v_mov_b32_e32 v7, v89
	v_mov_b32_e32 v6, v89
	v_mov_b32_e32 v5, v89
	v_mov_b32_e32 v4, v89
	v_mov_b32_e32 v3, v89
	v_mov_b32_e32 v2, v89
	s_andn2_b64 vcc, exec, s[22:23]
	s_cbranch_vccz .LBB0_785
	s_branch .LBB0_786

;     __device__ __forceinline__ void a_ready(const Unit&) const { wait_cnt(w_ready, w_need); }
;     __device__ __forceinline__ void half_ready(const Unit& u) const { wait_cnt(g_ready + 64 * u.pm, g_need); }
; #define PG8_STAGE(bufoff, gbase, voff) do { _Pragma("unroll") for (int _i = 0; _i < 2; ++_i) \
;         asm volatile("s_mov_b32 m0, %0\n\ts_nop 0\n\tglobal_load_lds_dwordx4 %1, %2" :: "s"(ldsb + (unsigned)(bufoff) + ldsw + (unsigned)(_i * 8192)), "v"((voff)[_i]), "s"((const char*)(gbase)) : "memory", "m0"); } while (0)
; #define PG8_LDA(dst, b, h) do { _Pragma("unroll") for (int m = 0; m < 4; ++m) _Pragma("unroll") for (int k = 0; k < 2; ++k) dst[m][k] = *(const LAS bf16x8*)(lds + PG8_SA(b, h) + aoff + m * 2048 + k * 1024); } while (0)
; #define PG8_LDB(dst, b, h) do { _Pragma("unroll") for (int n = 0; n < 2; ++n) _Pragma("unroll") for (int k = 0; k < 2; ++k) dst[n][k] = *(const LAS bf16x8*)(lds + PG8_SB(b, h) + boff + n * 2048 + k * 1024); } while (0)
; #define PG8_WAIT_V(n) asm volatile("s_waitcnt vmcnt(" #n ")" ::: "memory")
; #define PG8_WAIT_L(n) asm volatile("s_waitcnt lgkmcnt(" #n ")" ::: "memory")
; #define PG8_BAR __builtin_amdgcn_s_barrier()
; #define PG8_SCHED __builtin_amdgcn_sched_barrier(0)
; template <class Epi, class Sched>
; __device__ __forceinline__ void gemm_phase(LAS unsigned char* lds, const Gemm g, const Sched& S, const Epi& E) {
;     ...
;             const bool last = (t == nt - 2);
;             if (last && has_next) S.a_ready(nxt);
;             if constexpr (Sched::TWO_HALVES) { if (t == KSW - 2) S.half_ready(cur); }
;             const char* a1 = cA + PG8_KOFF(t + 1) * (long)kstep;
;             const char* a2 = last ? nA : cA + PG8_KOFF(t + 2) * (long)kstep; const char* b2 = last ? nB : cB + PG8_KOFF(t + 2) * (long)kstep;
;             const char* a3 = a2 + kstep; const char* b3 = b2 + kstep;
;             if constexpr (Epi::HAS_MID) { if (t == Epi::MID_T) E.mid(acc, cur, wr, wc, fr, fq); }
;             PG8_LDB(B0, 0, 0); PG8_LDB(B1, 0, 1); PG8_SCHED; PG8_LDA(At, 0, 0); PG8_STAGE(PG8_SA(1, 1), a1 + hstepA, voffA);
;             PG8_WAIT_V(8); PG8_WAIT_L(0); PG8_BAR; PG8_MMA(0, 0, At, B0); PG8_MMA(0, 1, At, B1); PG8_BAR; PG8_SCHED;
;             PG8_LDA(At, 0, 1); PG8_STAGE(PG8_SB(0, 0), b2, voffB); PG8_STAGE(PG8_SB(0, 1), b2 + hstepB, voffB); PG8_STAGE(PG8_SA(0, 0), a2, voffA);
.LBB0_1010:
	s_or_b32 s4, s65, 1
	s_lshl_b64 s[66:67], s[4:5], 7
	s_add_i32 s4, s65, 2
	s_lshl_b64 s[42:43], s[4:5], 7
	s_add_u32 s68, s30, s42
	v_add_u32_e32 v141, 0, v137
	s_addc_u32 s69, s31, s43
	v_add_u32_e32 v154, 0x10000, v141
	v_add_u32_e32 v170, 0x14000, v141
	s_and_b64 s[44:45], s[40:41], exec
	ds_read_b128 v[142:145], v154
	ds_read_b128 v[146:149], v154 offset:1024
	ds_read_b128 v[150:153], v154 offset:2048
	ds_read_b128 v[154:157], v154 offset:3072
	ds_read_b128 v[158:161], v170
	ds_read_b128 v[162:165], v170 offset:1024
	ds_read_b128 v[166:169], v170 offset:2048
	ds_read_b128 v[170:173], v170 offset:3072
	s_cselect_b32 s45, s13, s69
	s_cselect_b32 s44, s21, s68
	s_add_u32 s68, s36, s42
	s_addc_u32 s69, s37, s43
	s_add_u32 s42, s44, 0x80
	s_addc_u32 s43, s45, 0
	s_and_b64 s[40:41], s[40:41], exec
	s_cselect_b32 s41, s15, s69
	s_cselect_b32 s40, s64, s68
	s_add_u32 s66, s30, s66
	s_addc_u32 s67, s31, s67
	v_add_u32_e32 v206, 0, v136
	ds_read_b128 v[174:177], v206
	ds_read_b128 v[178:181], v206 offset:1024
	ds_read_b128 v[182:185], v206 offset:2048
	ds_read_b128 v[186:189], v206 offset:3072
	ds_read_b128 v[190:193], v206 offset:4096
	ds_read_b128 v[194:197], v206 offset:5120
	ds_read_b128 v[198:201], v206 offset:6144
	ds_read_b128 v[202:205], v206 offset:7168
	s_mov_b32 m0, s55
	s_nop 0
	global_load_lds_dwordx4 v1, s[66:67]
	s_mov_b32 m0, s56
	s_nop 0
	global_load_lds_dwordx4 v133, s[66:67]
	s_add_u32 s66, s66, 0x80000
	s_addc_u32 s67, s67, 0
	s_mov_b32 m0, s59
	s_nop 0
	global_load_lds_dwordx4 v1, s[66:67]
	s_nop 0
	s_mov_b32 m0, s60
	s_nop 0
	global_load_lds_dwordx4 v133, s[66:67]
	s_waitcnt vmcnt(8)
	s_waitcnt lgkmcnt(0)
	s_barrier
	s_setprio 1
	s_waitcnt lgkmcnt(7)
	v_mfma_f32_16x16x32_bf16 v[122:125], v[142:145], v[174:177], v[122:125]
	v_mfma_f32_16x16x32_bf16 v[114:117], v[150:153], v[174:177], v[114:117]
	s_waitcnt lgkmcnt(5)
	v_mfma_f32_16x16x32_bf16 v[94:97], v[142:145], v[182:185], v[94:97]
	v_mfma_f32_16x16x32_bf16 v[86:89], v[150:153], v[182:185], v[86:89]
	s_waitcnt lgkmcnt(3)
	v_mfma_f32_16x16x32_bf16 v[54:57], v[142:145], v[190:193], v[54:57]
	v_mfma_f32_16x16x32_bf16 v[50:53], v[150:153], v[190:193], v[50:53]
	s_waitcnt lgkmcnt(1)
	v_mfma_f32_16x16x32_bf16 v[14:17], v[142:145], v[198:201], v[14:17]
	v_mfma_f32_16x16x32_bf16 v[10:13], v[150:153], v[198:201], v[10:13]
	v_mfma_f32_16x16x32_bf16 v[122:125], v[146:149], v[178:181], v[122:125]
	v_mfma_f32_16x16x32_bf16 v[114:117], v[154:157], v[178:181], v[114:117]
	v_mfma_f32_16x16x32_bf16 v[94:97], v[146:149], v[186:189], v[94:97]
	v_mfma_f32_16x16x32_bf16 v[86:89], v[154:157], v[186:189], v[86:89]
	v_mfma_f32_16x16x32_bf16 v[54:57], v[146:149], v[194:197], v[54:57]
	v_mfma_f32_16x16x32_bf16 v[50:53], v[154:157], v[194:197], v[50:53]
	s_waitcnt lgkmcnt(0)
	v_mfma_f32_16x16x32_bf16 v[14:17], v[146:149], v[202:205], v[14:17]
	v_mfma_f32_16x16x32_bf16 v[10:13], v[154:157], v[202:205], v[10:13]
	s_setprio 0
	s_setprio 1
	v_mfma_f32_16x16x32_bf16 v[126:129], v[158:161], v[174:177], v[126:129]
	v_mfma_f32_16x16x32_bf16 v[118:121], v[166:169], v[174:177], v[118:121]
	v_mfma_f32_16x16x32_bf16 v[70:73], v[158:161], v[182:185], v[70:73]
	v_mfma_f32_16x16x32_bf16 v[66:69], v[166:169], v[182:185], v[66:69]
	v_mfma_f32_16x16x32_bf16 v[38:41], v[158:161], v[190:193], v[38:41]
	v_mfma_f32_16x16x32_bf16 v[34:37], v[166:169], v[190:193], v[34:37]
	v_mfma_f32_16x16x32_bf16 v[6:9], v[158:161], v[198:201], v[6:9]
	v_mfma_f32_16x16x32_bf16 v[2:5], v[166:169], v[198:201], v[2:5]
	v_mfma_f32_16x16x32_bf16 v[126:129], v[162:165], v[178:181], v[126:129]
	v_mfma_f32_16x16x32_bf16 v[118:121], v[170:173], v[178:181], v[118:121]
	v_mfma_f32_16x16x32_bf16 v[70:73], v[162:165], v[186:189], v[70:73]
	v_mfma_f32_16x16x32_bf16 v[66:69], v[170:173], v[186:189], v[66:69]
	v_mfma_f32_16x16x32_bf16 v[38:41], v[162:165], v[194:197], v[38:41]
	v_mfma_f32_16x16x32_bf16 v[34:37], v[170:173], v[194:197], v[34:37]
	v_mfma_f32_16x16x32_bf16 v[6:9], v[162:165], v[202:205], v[6:9]
	v_mfma_f32_16x16x32_bf16 v[2:5], v[170:173], v[202:205], v[2:5]
	s_setprio 0
	s_barrier
	ds_read_b128 v[174:177], v206 offset:16384
	ds_read_b128 v[178:181], v206 offset:17408
	ds_read_b128 v[182:185], v206 offset:18432
	ds_read_b128 v[186:189], v206 offset:19456
	ds_read_b128 v[190:193], v206 offset:20480
	ds_read_b128 v[194:197], v206 offset:21504
	ds_read_b128 v[198:201], v206 offset:22528
	ds_read_b128 v[202:205], v206 offset:23552
	s_mov_b32 m0, s46
	s_nop 0
	global_load_lds_dwordx4 v132, s[40:41]
	s_add_u32 s66, s40, 0x80000
	s_mov_b32 m0, s47
	s_nop 0
	global_load_lds_dwordx4 v134, s[40:41]
	s_addc_u32 s67, s41, 0
	s_mov_b32 m0, s48
	s_nop 0
	global_load_lds_dwordx4 v132, s[66:67]
	s_nop 0
	s_mov_b32 m0, s49
	s_nop 0
	global_load_lds_dwordx4 v134, s[66:67]
	s_nop 0
	s_waitcnt vmcnt(6)
	s_waitcnt lgkmcnt(0)
	s_barrier
; #define PG8_STAGE(bufoff, gbase, voff) do { _Pragma("unroll") for (int _i = 0; _i < 2; ++_i) \
;         asm volatile("s_mov_b32 m0, %0\n\ts_nop 0\n\tglobal_load_lds_dwordx4 %1, %2" :: "s"(ldsb + (unsigned)(bufoff) + ldsw + (unsigned)(_i * 8192)), "v"((voff)[_i]), "s"((const char*)(gbase)) : "memory", "m0"); } while (0)
; #define PG8_LDA(dst, b, h) do { _Pragma("unroll") for (int m = 0; m < 4; ++m) _Pragma("unroll") for (int k = 0; k < 2; ++k) dst[m][k] = *(const LAS bf16x8*)(lds + PG8_SA(b, h) + aoff + m * 2048 + k * 1024); } while (0)
; #define PG8_LDB(dst, b, h) do { _Pragma("unroll") for (int n = 0; n < 2; ++n) _Pragma("unroll") for (int k = 0; k < 2; ++k) dst[n][k] = *(const LAS bf16x8*)(lds + PG8_SB(b, h) + boff + n * 2048 + k * 1024); } while (0)
; #define PG8_MMA(ai, bj, At, Bt) do { __builtin_amdgcn_s_setprio(1); _Pragma("unroll") for (int m = 0; m < 4; ++m) _Pragma("unroll") for (int n = 0; n < 2; ++n) _Pragma("unroll") for (int k = 0; k < 2; ++k) \
;         acc[ai][bj][m][n] = __builtin_amdgcn_mfma_f32_16x16x32_bf16(Bt[n][k], At[m][k], acc[ai][bj][m][n], 0, 0, 0); __builtin_amdgcn_s_setprio(0); } while (0)
; #define PG8_WAIT_V(n) asm volatile("s_waitcnt vmcnt(" #n ")" ::: "memory")
; #define PG8_WAIT_L(n) asm volatile("s_waitcnt lgkmcnt(" #n ")" ::: "memory")
; #define PG8_BAR __builtin_amdgcn_s_barrier()
; #define PG8_SCHED __builtin_amdgcn_sched_barrier(0)
; template <class Epi, class Sched>
; __device__ __forceinline__ void gemm_phase(LAS unsigned char* lds, const Gemm g, const Sched& S, const Epi& E) {
;     ...
;             PG8_WAIT_V(8); PG8_WAIT_L(0); PG8_BAR; PG8_MMA(1, 0, At, B0); PG8_MMA(1, 1, At, B1); PG8_BAR; PG8_SCHED;
;             PG8_LDB(B0, 1, 0); PG8_LDB(B1, 1, 1); PG8_SCHED; PG8_LDA(At, 1, 0); PG8_STAGE(PG8_SA(0, 1), a2 + hstepA, voffA);
;             PG8_WAIT_V(8); PG8_WAIT_L(0); PG8_BAR; PG8_MMA(0, 0, At, B0); PG8_MMA(0, 1, At, B1); PG8_BAR; PG8_SCHED;
	s_setprio 1
	s_waitcnt lgkmcnt(7)
	v_mfma_f32_16x16x32_bf16 v[102:105], v[142:145], v[174:177], v[102:105]
	v_mfma_f32_16x16x32_bf16 v[98:101], v[150:153], v[174:177], v[98:101]
	s_waitcnt lgkmcnt(5)
	v_mfma_f32_16x16x32_bf16 v[78:81], v[142:145], v[182:185], v[78:81]
	v_mfma_f32_16x16x32_bf16 v[74:77], v[150:153], v[182:185], v[74:77]
	s_waitcnt lgkmcnt(3)
	v_mfma_f32_16x16x32_bf16 v[46:49], v[142:145], v[190:193], v[46:49]
	v_mfma_f32_16x16x32_bf16 v[42:45], v[150:153], v[190:193], v[42:45]
	s_waitcnt lgkmcnt(1)
	v_mfma_f32_16x16x32_bf16 v[22:25], v[142:145], v[198:201], v[22:25]
	v_mfma_f32_16x16x32_bf16 v[18:21], v[150:153], v[198:201], v[18:21]
	v_mfma_f32_16x16x32_bf16 v[102:105], v[146:149], v[178:181], v[102:105]
	v_mfma_f32_16x16x32_bf16 v[98:101], v[154:157], v[178:181], v[98:101]
	v_mfma_f32_16x16x32_bf16 v[78:81], v[146:149], v[186:189], v[78:81]
	v_mfma_f32_16x16x32_bf16 v[74:77], v[154:157], v[186:189], v[74:77]
	v_mfma_f32_16x16x32_bf16 v[46:49], v[146:149], v[194:197], v[46:49]
	v_mfma_f32_16x16x32_bf16 v[42:45], v[154:157], v[194:197], v[42:45]
	s_waitcnt lgkmcnt(0)
	v_mfma_f32_16x16x32_bf16 v[22:25], v[146:149], v[202:205], v[22:25]
	v_mfma_f32_16x16x32_bf16 v[18:21], v[154:157], v[202:205], v[18:21]
	s_setprio 0
	s_setprio 1
	v_mfma_f32_16x16x32_bf16 v[110:113], v[158:161], v[174:177], v[110:113]
	v_mfma_f32_16x16x32_bf16 v[106:109], v[166:169], v[174:177], v[106:109]
	v_mfma_f32_16x16x32_bf16 v[90:93], v[158:161], v[182:185], v[90:93]
	v_mfma_f32_16x16x32_bf16 v[82:85], v[166:169], v[182:185], v[82:85]
	v_mfma_f32_16x16x32_bf16 v[62:65], v[158:161], v[190:193], v[62:65]
	v_mfma_f32_16x16x32_bf16 v[58:61], v[166:169], v[190:193], v[58:61]
	v_mfma_f32_16x16x32_bf16 v[30:33], v[158:161], v[198:201], v[30:33]
	v_mfma_f32_16x16x32_bf16 v[26:29], v[166:169], v[198:201], v[26:29]
	v_mfma_f32_16x16x32_bf16 v[110:113], v[162:165], v[178:181], v[110:113]
	v_mfma_f32_16x16x32_bf16 v[106:109], v[170:173], v[178:181], v[106:109]
	v_mfma_f32_16x16x32_bf16 v[90:93], v[162:165], v[186:189], v[90:93]
	v_mfma_f32_16x16x32_bf16 v[82:85], v[170:173], v[186:189], v[82:85]
	v_mfma_f32_16x16x32_bf16 v[62:65], v[162:165], v[194:197], v[62:65]
	v_mfma_f32_16x16x32_bf16 v[58:61], v[170:173], v[194:197], v[58:61]
	v_mfma_f32_16x16x32_bf16 v[30:33], v[162:165], v[202:205], v[30:33]
	v_mfma_f32_16x16x32_bf16 v[26:29], v[170:173], v[202:205], v[26:29]
	s_setprio 0
	s_barrier
	v_add_u32_e32 v154, 0x18000, v141
	v_add_u32_e32 v141, 0x1c000, v141
	ds_read_b128 v[142:145], v154
	ds_read_b128 v[146:149], v154 offset:1024
	ds_read_b128 v[150:153], v154 offset:2048
	ds_read_b128 v[154:157], v154 offset:3072
	ds_read_b128 v[158:161], v141
	ds_read_b128 v[162:165], v141 offset:1024
	ds_read_b128 v[166:169], v141 offset:2048
	ds_read_b128 v[170:173], v141 offset:3072
	ds_read_b128 v[174:177], v206 offset:32768
	ds_read_b128 v[178:181], v206 offset:33792
	ds_read_b128 v[182:185], v206 offset:34816
	ds_read_b128 v[186:189], v206 offset:35840
	ds_read_b128 v[190:193], v206 offset:36864
	ds_read_b128 v[194:197], v206 offset:37888
	ds_read_b128 v[198:201], v206 offset:38912
	ds_read_b128 v[202:205], v206 offset:39936
	s_mov_b32 m0, s35
	s_nop 0
	global_load_lds_dwordx4 v1, s[44:45]
	s_mov_b32 m0, s50
	s_nop 0
	global_load_lds_dwordx4 v133, s[44:45]
	s_add_u32 s44, s44, 0x80000
	s_addc_u32 s45, s45, 0
	s_mov_b32 m0, s51
	s_nop 0
	global_load_lds_dwordx4 v1, s[44:45]
	s_nop 0
	s_mov_b32 m0, s52
	s_nop 0
	global_load_lds_dwordx4 v133, s[44:45]
	s_waitcnt vmcnt(8)
	s_waitcnt lgkmcnt(0)
	s_barrier
; #define PG8_STAGE(bufoff, gbase, voff) do { _Pragma("unroll") for (int _i = 0; _i < 2; ++_i) \
;         asm volatile("s_mov_b32 m0, %0\n\ts_nop 0\n\tglobal_load_lds_dwordx4 %1, %2" :: "s"(ldsb + (unsigned)(bufoff) + ldsw + (unsigned)(_i * 8192)), "v"((voff)[_i]), "s"((const char*)(gbase)) : "memory", "m0"); } while (0)
; #define PG8_LDA(dst, b, h) do { _Pragma("unroll") for (int m = 0; m < 4; ++m) _Pragma("unroll") for (int k = 0; k < 2; ++k) dst[m][k] = *(const LAS bf16x8*)(lds + PG8_SA(b, h) + aoff + m * 2048 + k * 1024); } while (0)
; #define PG8_MMA(ai, bj, At, Bt) do { __builtin_amdgcn_s_setprio(1); _Pragma("unroll") for (int m = 0; m < 4; ++m) _Pragma("unroll") for (int n = 0; n < 2; ++n) _Pragma("unroll") for (int k = 0; k < 2; ++k) \
;         acc[ai][bj][m][n] = __builtin_amdgcn_mfma_f32_16x16x32_bf16(Bt[n][k], At[m][k], acc[ai][bj][m][n], 0, 0, 0); __builtin_amdgcn_s_setprio(0); } while (0)
; #define PG8_WAIT_V(n) asm volatile("s_waitcnt vmcnt(" #n ")" ::: "memory")
; #define PG8_WAIT_L(n) asm volatile("s_waitcnt lgkmcnt(" #n ")" ::: "memory")
; #define PG8_BAR __builtin_amdgcn_s_barrier()
; #define PG8_SCHED __builtin_amdgcn_sched_barrier(0)
; template <class Epi, class Sched>
; __device__ __forceinline__ void gemm_phase(LAS unsigned char* lds, const Gemm g, const Sched& S, const Epi& E) {
;     ...
;             PG8_WAIT_V(8); PG8_WAIT_L(0); PG8_BAR; PG8_MMA(0, 0, At, B0); PG8_MMA(0, 1, At, B1); PG8_BAR; PG8_SCHED;
;             PG8_LDA(At, 1, 1); PG8_STAGE(PG8_SB(1, 0), b3, voffB); PG8_STAGE(PG8_SB(1, 1), b3 + hstepB, voffB); PG8_STAGE(PG8_SA(1, 0), a3, voffA);
;             PG8_WAIT_V(8); PG8_WAIT_L(0); PG8_BAR; PG8_MMA(1, 0, At, B0); PG8_MMA(1, 1, At, B1); PG8_BAR; PG8_SCHED;
;         }
	s_setprio 1
	s_waitcnt lgkmcnt(7)
	v_mfma_f32_16x16x32_bf16 v[122:125], v[142:145], v[174:177], v[122:125]
	v_mfma_f32_16x16x32_bf16 v[114:117], v[150:153], v[174:177], v[114:117]
	s_waitcnt lgkmcnt(5)
	v_mfma_f32_16x16x32_bf16 v[94:97], v[142:145], v[182:185], v[94:97]
	v_mfma_f32_16x16x32_bf16 v[86:89], v[150:153], v[182:185], v[86:89]
	s_waitcnt lgkmcnt(3)
	v_mfma_f32_16x16x32_bf16 v[54:57], v[142:145], v[190:193], v[54:57]
	v_mfma_f32_16x16x32_bf16 v[50:53], v[150:153], v[190:193], v[50:53]
	s_waitcnt lgkmcnt(1)
	v_mfma_f32_16x16x32_bf16 v[14:17], v[142:145], v[198:201], v[14:17]
	v_mfma_f32_16x16x32_bf16 v[10:13], v[150:153], v[198:201], v[10:13]
	v_mfma_f32_16x16x32_bf16 v[122:125], v[146:149], v[178:181], v[122:125]
	v_mfma_f32_16x16x32_bf16 v[114:117], v[154:157], v[178:181], v[114:117]
	v_mfma_f32_16x16x32_bf16 v[94:97], v[146:149], v[186:189], v[94:97]
	v_mfma_f32_16x16x32_bf16 v[86:89], v[154:157], v[186:189], v[86:89]
	v_mfma_f32_16x16x32_bf16 v[54:57], v[146:149], v[194:197], v[54:57]
	v_mfma_f32_16x16x32_bf16 v[50:53], v[154:157], v[194:197], v[50:53]
	s_waitcnt lgkmcnt(0)
	v_mfma_f32_16x16x32_bf16 v[14:17], v[146:149], v[202:205], v[14:17]
	v_mfma_f32_16x16x32_bf16 v[10:13], v[154:157], v[202:205], v[10:13]
	s_setprio 0
	s_setprio 1
	v_mfma_f32_16x16x32_bf16 v[126:129], v[158:161], v[174:177], v[126:129]
	v_mfma_f32_16x16x32_bf16 v[118:121], v[166:169], v[174:177], v[118:121]
	v_mfma_f32_16x16x32_bf16 v[70:73], v[158:161], v[182:185], v[70:73]
	v_mfma_f32_16x16x32_bf16 v[66:69], v[166:169], v[182:185], v[66:69]
	v_mfma_f32_16x16x32_bf16 v[38:41], v[158:161], v[190:193], v[38:41]
	v_mfma_f32_16x16x32_bf16 v[34:37], v[166:169], v[190:193], v[34:37]
	v_mfma_f32_16x16x32_bf16 v[6:9], v[158:161], v[198:201], v[6:9]
	v_mfma_f32_16x16x32_bf16 v[2:5], v[166:169], v[198:201], v[2:5]
	v_mfma_f32_16x16x32_bf16 v[126:129], v[162:165], v[178:181], v[126:129]
	v_mfma_f32_16x16x32_bf16 v[118:121], v[170:173], v[178:181], v[118:121]
	v_mfma_f32_16x16x32_bf16 v[70:73], v[162:165], v[186:189], v[70:73]
	v_mfma_f32_16x16x32_bf16 v[66:69], v[170:173], v[186:189], v[66:69]
	v_mfma_f32_16x16x32_bf16 v[38:41], v[162:165], v[194:197], v[38:41]
	v_mfma_f32_16x16x32_bf16 v[34:37], v[170:173], v[194:197], v[34:37]
	v_mfma_f32_16x16x32_bf16 v[6:9], v[162:165], v[202:205], v[6:9]
	v_mfma_f32_16x16x32_bf16 v[2:5], v[170:173], v[202:205], v[2:5]
	s_setprio 0
	s_barrier
	ds_read_b128 v[174:177], v206 offset:49152
	ds_read_b128 v[178:181], v206 offset:50176
	ds_read_b128 v[182:185], v206 offset:51200
	ds_read_b128 v[186:189], v206 offset:52224
	ds_read_b128 v[190:193], v206 offset:53248
	ds_read_b128 v[194:197], v206 offset:54272
	ds_read_b128 v[198:201], v206 offset:55296
	ds_read_b128 v[202:205], v206 offset:56320
	s_add_u32 s44, s40, 0x80
	s_addc_u32 s45, s41, 0
	s_mov_b32 m0, s53
	s_nop 0
	global_load_lds_dwordx4 v132, s[44:45]
	s_add_u32 s40, s40, 0x80080
	s_mov_b32 m0, s54
	s_nop 0
	global_load_lds_dwordx4 v134, s[44:45]
	s_addc_u32 s41, s41, 0
	s_mov_b32 m0, s57
	s_nop 0
	global_load_lds_dwordx4 v132, s[40:41]
	s_nop 0
	s_mov_b32 m0, s58
	s_nop 0
	global_load_lds_dwordx4 v134, s[40:41]
	s_nop 0
	s_waitcnt vmcnt(6)
	s_waitcnt lgkmcnt(0)
	s_barrier
	s_setprio 1
	s_waitcnt lgkmcnt(7)
	v_mfma_f32_16x16x32_bf16 v[102:105], v[142:145], v[174:177], v[102:105]
	v_mfma_f32_16x16x32_bf16 v[98:101], v[150:153], v[174:177], v[98:101]
	s_waitcnt lgkmcnt(5)
	v_mfma_f32_16x16x32_bf16 v[78:81], v[142:145], v[182:185], v[78:81]
	v_mfma_f32_16x16x32_bf16 v[74:77], v[150:153], v[182:185], v[74:77]
	s_waitcnt lgkmcnt(3)
	v_mfma_f32_16x16x32_bf16 v[46:49], v[142:145], v[190:193], v[46:49]
	v_mfma_f32_16x16x32_bf16 v[42:45], v[150:153], v[190:193], v[42:45]
	s_waitcnt lgkmcnt(1)
	v_mfma_f32_16x16x32_bf16 v[22:25], v[142:145], v[198:201], v[22:25]
	v_mfma_f32_16x16x32_bf16 v[18:21], v[150:153], v[198:201], v[18:21]
	v_mfma_f32_16x16x32_bf16 v[102:105], v[146:149], v[178:181], v[102:105]
	v_mfma_f32_16x16x32_bf16 v[98:101], v[154:157], v[178:181], v[98:101]
	v_mfma_f32_16x16x32_bf16 v[78:81], v[146:149], v[186:189], v[78:81]
	v_mfma_f32_16x16x32_bf16 v[74:77], v[154:157], v[186:189], v[74:77]
	v_mfma_f32_16x16x32_bf16 v[46:49], v[146:149], v[194:197], v[46:49]
	v_mfma_f32_16x16x32_bf16 v[42:45], v[154:157], v[194:197], v[42:45]
	s_waitcnt lgkmcnt(0)
	v_mfma_f32_16x16x32_bf16 v[22:25], v[146:149], v[202:205], v[22:25]
	v_mfma_f32_16x16x32_bf16 v[18:21], v[154:157], v[202:205], v[18:21]
	s_setprio 0
	s_setprio 1
	v_mfma_f32_16x16x32_bf16 v[110:113], v[158:161], v[174:177], v[110:113]
	v_mfma_f32_16x16x32_bf16 v[106:109], v[166:169], v[174:177], v[106:109]
	v_mfma_f32_16x16x32_bf16 v[90:93], v[158:161], v[182:185], v[90:93]
	v_mfma_f32_16x16x32_bf16 v[82:85], v[166:169], v[182:185], v[82:85]
	v_mfma_f32_16x16x32_bf16 v[62:65], v[158:161], v[190:193], v[62:65]
	v_mfma_f32_16x16x32_bf16 v[58:61], v[166:169], v[190:193], v[58:61]
	v_mfma_f32_16x16x32_bf16 v[30:33], v[158:161], v[198:201], v[30:33]
	v_mfma_f32_16x16x32_bf16 v[26:29], v[166:169], v[198:201], v[26:29]
	v_mfma_f32_16x16x32_bf16 v[110:113], v[162:165], v[178:181], v[110:113]
	v_mfma_f32_16x16x32_bf16 v[106:109], v[170:173], v[178:181], v[106:109]
	v_mfma_f32_16x16x32_bf16 v[90:93], v[162:165], v[186:189], v[90:93]
	v_mfma_f32_16x16x32_bf16 v[82:85], v[170:173], v[186:189], v[82:85]
	v_mfma_f32_16x16x32_bf16 v[62:65], v[162:165], v[194:197], v[62:65]
	v_mfma_f32_16x16x32_bf16 v[58:61], v[170:173], v[194:197], v[58:61]
	v_mfma_f32_16x16x32_bf16 v[30:33], v[162:165], v[202:205], v[30:33]
	v_mfma_f32_16x16x32_bf16 v[26:29], v[170:173], v[202:205], v[26:29]
	s_setprio 0
	s_barrier
	s_cmp_gt_u32 s65, 29
	s_cbranch_scc1 .LBB0_1027
	s_mov_b32 s65, s4
	s_branch .LBB0_998

;     __device__ __forceinline__ void a_ready(const Unit&) const { wait_cnt(w_ready, w_need); }
;     __device__ __forceinline__ void half_ready(const Unit& u) const { wait_cnt(g_ready + 64 * u.pm, g_need); }
; #define PG8_STAGE(bufoff, gbase, voff) do { _Pragma("unroll") for (int _i = 0; _i < 2; ++_i) \
;         asm volatile("s_mov_b32 m0, %0\n\ts_nop 0\n\tglobal_load_lds_dwordx4 %1, %2" :: "s"(ldsb + (unsigned)(bufoff) + ldsw + (unsigned)(_i * 8192)), "v"((voff)[_i]), "s"((const char*)(gbase)) : "memory", "m0"); } while (0)
; #define PG8_LDA(dst, b, h) do { _Pragma("unroll") for (int m = 0; m < 4; ++m) _Pragma("unroll") for (int k = 0; k < 2; ++k) dst[m][k] = *(const LAS bf16x8*)(lds + PG8_SA(b, h) + aoff + m * 2048 + k * 1024); } while (0)
; #define PG8_LDB(dst, b, h) do { _Pragma("unroll") for (int n = 0; n < 2; ++n) _Pragma("unroll") for (int k = 0; k < 2; ++k) dst[n][k] = *(const LAS bf16x8*)(lds + PG8_SB(b, h) + boff + n * 2048 + k * 1024); } while (0)
; #define PG8_WAIT_V(n) asm volatile("s_waitcnt vmcnt(" #n ")" ::: "memory")
; #define PG8_WAIT_L(n) asm volatile("s_waitcnt lgkmcnt(" #n ")" ::: "memory")
; #define PG8_BAR __builtin_amdgcn_s_barrier()
; template <class Epi, class Sched>
; __device__ __forceinline__ void gemm_phase(LAS unsigned char* lds, const Gemm g, const Sched& S, const Epi& E) {
;     ...
;             const bool last = (t == nt - 2);
;             if (last && has_next) S.a_ready(nxt);
;             if constexpr (Sched::TWO_HALVES) { if (t == KSW - 2) S.half_ready(cur); }
;             const char* a1 = cA + PG8_KOFF(t + 1) * (long)kstep;
;             const char* a2 = last ? nA : cA + PG8_KOFF(t + 2) * (long)kstep; const char* b2 = last ? nB : cB + PG8_KOFF(t + 2) * (long)kstep;
;             const char* a3 = a2 + kstep; const char* b3 = b2 + kstep;
;             if constexpr (Epi::HAS_MID) { if (t == Epi::MID_T) E.mid(acc, cur, wr, wc, fr, fq); }
;             PG8_LDB(B0, 0, 0); PG8_LDB(B1, 0, 1); PG8_SCHED; PG8_LDA(At, 0, 0); PG8_STAGE(PG8_SA(1, 1), a1 + hstepA, voffA);
;             PG8_WAIT_V(8); PG8_WAIT_L(0); PG8_BAR; PG8_MMA(0, 0, At, B0); PG8_MMA(0, 1, At, B1); PG8_BAR; PG8_SCHED;
;             PG8_LDA(At, 0, 1); PG8_STAGE(PG8_SB(0, 0), b2, voffB); PG8_STAGE(PG8_SB(0, 1), b2 + hstepB, voffB); PG8_STAGE(PG8_SA(0, 0), a2, voffA);
;             PG8_WAIT_V(8); PG8_WAIT_L(0); PG8_BAR; PG8_BAR; PG8_SCHED;
.LBB0_1016:
	s_or_b32 s4, s65, 1
	s_lshl_b64 s[66:67], s[4:5], 7
	s_add_i32 s4, s65, 2
	s_lshl_b64 s[40:41], s[4:5], 7
	s_add_u32 s68, s30, s40
	v_add_u32_e32 v141, 0, v137
	s_addc_u32 s69, s31, s41
	v_add_u32_e32 v30, 0x10000, v141
	v_add_u32_e32 v62, 0x14000, v141
	s_and_b64 s[44:45], s[42:43], exec
	ds_read_b128 v[18:21], v30
	ds_read_b128 v[22:25], v30 offset:1024
	ds_read_b128 v[26:29], v30 offset:2048
	ds_read_b128 v[30:33], v30 offset:3072
	ds_read_b128 v[42:45], v62
	ds_read_b128 v[46:49], v62 offset:1024
	ds_read_b128 v[58:61], v62 offset:2048
	ds_read_b128 v[62:65], v62 offset:3072
	s_cselect_b32 s45, s13, s69
	s_cselect_b32 s44, s21, s68
	s_add_u32 s68, s36, s40
	s_addc_u32 s69, s37, s41
	s_add_u32 s40, s44, 0x80
	s_addc_u32 s41, s45, 0
	s_and_b64 s[42:43], s[42:43], exec
	s_cselect_b32 s43, s15, s69
	s_cselect_b32 s42, s64, s68
	s_add_u32 s66, s30, s66
	s_addc_u32 s67, s31, s67
	v_add_u32_e32 v146, 0, v136
	ds_read_b128 v[74:77], v146
	ds_read_b128 v[78:81], v146 offset:1024
	ds_read_b128 v[82:85], v146 offset:2048
	ds_read_b128 v[90:93], v146 offset:3072
	ds_read_b128 v[98:101], v146 offset:4096
	ds_read_b128 v[102:105], v146 offset:5120
	ds_read_b128 v[106:109], v146 offset:6144
	ds_read_b128 v[110:113], v146 offset:7168
	s_mov_b32 m0, s55
	s_nop 0
	global_load_lds_dwordx4 v1, s[66:67]
	s_mov_b32 m0, s56
	s_nop 0
	global_load_lds_dwordx4 v133, s[66:67]
	s_add_u32 s66, s66, 0x80000
	s_addc_u32 s67, s67, 0
	s_mov_b32 m0, s59
	s_nop 0
	global_load_lds_dwordx4 v1, s[66:67]
	s_nop 0
	s_mov_b32 m0, s60
	s_nop 0
	global_load_lds_dwordx4 v133, s[66:67]
	s_waitcnt vmcnt(8)
	s_waitcnt lgkmcnt(0)
	s_barrier
	s_setprio 1
	s_waitcnt lgkmcnt(7)
	v_mfma_f32_16x16x32_bf16 v[122:125], v[18:21], v[74:77], v[122:125]
	v_mfma_f32_16x16x32_bf16 v[114:117], v[26:29], v[74:77], v[114:117]
	s_waitcnt lgkmcnt(5)
	v_mfma_f32_16x16x32_bf16 v[94:97], v[18:21], v[82:85], v[94:97]
	v_mfma_f32_16x16x32_bf16 v[86:89], v[26:29], v[82:85], v[86:89]
	s_waitcnt lgkmcnt(3)
	v_mfma_f32_16x16x32_bf16 v[54:57], v[18:21], v[98:101], v[54:57]
	v_mfma_f32_16x16x32_bf16 v[50:53], v[26:29], v[98:101], v[50:53]
	s_waitcnt lgkmcnt(1)
	v_mfma_f32_16x16x32_bf16 v[14:17], v[18:21], v[106:109], v[14:17]
	v_mfma_f32_16x16x32_bf16 v[10:13], v[26:29], v[106:109], v[10:13]
	v_mfma_f32_16x16x32_bf16 v[122:125], v[22:25], v[78:81], v[122:125]
	v_mfma_f32_16x16x32_bf16 v[114:117], v[30:33], v[78:81], v[114:117]
	v_mfma_f32_16x16x32_bf16 v[94:97], v[22:25], v[90:93], v[94:97]
	v_mfma_f32_16x16x32_bf16 v[86:89], v[30:33], v[90:93], v[86:89]
	v_mfma_f32_16x16x32_bf16 v[54:57], v[22:25], v[102:105], v[54:57]
	v_mfma_f32_16x16x32_bf16 v[50:53], v[30:33], v[102:105], v[50:53]
	s_waitcnt lgkmcnt(0)
	v_mfma_f32_16x16x32_bf16 v[14:17], v[22:25], v[110:113], v[14:17]
	v_mfma_f32_16x16x32_bf16 v[10:13], v[30:33], v[110:113], v[10:13]
	s_setprio 0
	s_setprio 1
	v_mfma_f32_16x16x32_bf16 v[38:41], v[42:45], v[98:101], v[38:41]
	v_mfma_f32_16x16x32_bf16 v[34:37], v[58:61], v[98:101], v[34:37]
	v_mfma_f32_16x16x32_bf16 v[6:9], v[42:45], v[106:109], v[6:9]
	v_mfma_f32_16x16x32_bf16 v[2:5], v[58:61], v[106:109], v[2:5]
	v_mfma_f32_16x16x32_bf16 v[18:21], v[42:45], v[74:77], v[126:129]
	v_mfma_f32_16x16x32_bf16 v[22:25], v[58:61], v[74:77], v[118:121]
	v_mfma_f32_16x16x32_bf16 v[26:29], v[42:45], v[82:85], v[70:73]
	v_mfma_f32_16x16x32_bf16 v[30:33], v[58:61], v[82:85], v[66:69]
	v_mfma_f32_16x16x32_bf16 v[38:41], v[46:49], v[102:105], v[38:41]
	v_mfma_f32_16x16x32_bf16 v[34:37], v[62:65], v[102:105], v[34:37]
	v_mfma_f32_16x16x32_bf16 v[6:9], v[46:49], v[110:113], v[6:9]
	v_mfma_f32_16x16x32_bf16 v[2:5], v[62:65], v[110:113], v[2:5]
	v_mfma_f32_16x16x32_bf16 v[18:21], v[46:49], v[78:81], v[18:21]
	v_mfma_f32_16x16x32_bf16 v[22:25], v[62:65], v[78:81], v[22:25]
	v_mfma_f32_16x16x32_bf16 v[26:29], v[46:49], v[90:93], v[26:29]
	v_mfma_f32_16x16x32_bf16 v[30:33], v[62:65], v[90:93], v[30:33]
	s_setprio 0
	s_barrier
	s_mov_b32 m0, s46
	s_nop 0
	global_load_lds_dwordx4 v132, s[42:43]
	s_add_u32 s66, s42, 0x80000
	s_mov_b32 m0, s47
	s_nop 0
	global_load_lds_dwordx4 v134, s[42:43]
	s_addc_u32 s67, s43, 0
	s_mov_b32 m0, s48
	s_nop 0
	global_load_lds_dwordx4 v132, s[66:67]
	s_nop 0
	s_mov_b32 m0, s49
	s_nop 0
	global_load_lds_dwordx4 v134, s[66:67]
	s_nop 0
	s_waitcnt vmcnt(6)
	s_waitcnt lgkmcnt(0)
	s_barrier
; #define PG8_STAGE(bufoff, gbase, voff) do { _Pragma("unroll") for (int _i = 0; _i < 2; ++_i) \
;         asm volatile("s_mov_b32 m0, %0\n\ts_nop 0\n\tglobal_load_lds_dwordx4 %1, %2" :: "s"(ldsb + (unsigned)(bufoff) + ldsw + (unsigned)(_i * 8192)), "v"((voff)[_i]), "s"((const char*)(gbase)) : "memory", "m0"); } while (0)
; #define PG8_LDA(dst, b, h) do { _Pragma("unroll") for (int m = 0; m < 4; ++m) _Pragma("unroll") for (int k = 0; k < 2; ++k) dst[m][k] = *(const LAS bf16x8*)(lds + PG8_SA(b, h) + aoff + m * 2048 + k * 1024); } while (0)
; #define PG8_LDB(dst, b, h) do { _Pragma("unroll") for (int n = 0; n < 2; ++n) _Pragma("unroll") for (int k = 0; k < 2; ++k) dst[n][k] = *(const LAS bf16x8*)(lds + PG8_SB(b, h) + boff + n * 2048 + k * 1024); } while (0)
; #define PG8_MMA(ai, bj, At, Bt) do { __builtin_amdgcn_s_setprio(1); _Pragma("unroll") for (int m = 0; m < 4; ++m) _Pragma("unroll") for (int n = 0; n < 2; ++n) _Pragma("unroll") for (int k = 0; k < 2; ++k) \
;         acc[ai][bj][m][n] = __builtin_amdgcn_mfma_f32_16x16x32_bf16(Bt[n][k], At[m][k], acc[ai][bj][m][n], 0, 0, 0); __builtin_amdgcn_s_setprio(0); } while (0)
; #define PG8_WAIT_V(n) asm volatile("s_waitcnt vmcnt(" #n ")" ::: "memory")
; #define PG8_WAIT_L(n) asm volatile("s_waitcnt lgkmcnt(" #n ")" ::: "memory")
; #define PG8_BAR __builtin_amdgcn_s_barrier()
; #define PG8_SCHED __builtin_amdgcn_sched_barrier(0)
; template <class Epi, class Sched>
; __device__ __forceinline__ void gemm_phase(LAS unsigned char* lds, const Gemm g, const Sched& S, const Epi& E) {
;     ...
;             PG8_WAIT_V(8); PG8_WAIT_L(0); PG8_BAR; PG8_BAR; PG8_SCHED;
;             PG8_LDB(B0, 1, 0); PG8_LDB(B1, 1, 1); PG8_SCHED; PG8_LDA(At, 1, 0); PG8_STAGE(PG8_SA(0, 1), a2 + hstepA, voffA);
;             PG8_WAIT_V(8); PG8_WAIT_L(0); PG8_BAR; PG8_MMA(0, 0, At, B0); PG8_MMA(0, 1, At, B1); PG8_BAR; PG8_SCHED;
;             PG8_LDA(At, 1, 1); PG8_STAGE(PG8_SB(1, 0), b3, voffB); PG8_STAGE(PG8_SB(1, 1), b3 + hstepB, voffB); PG8_STAGE(PG8_SA(1, 0), a3, voffA);
;             PG8_WAIT_V(8); PG8_WAIT_L(0); PG8_BAR; PG8_BAR; PG8_SCHED;
;         }
	s_barrier
	v_add_u32_e32 v62, 0x18000, v141
	v_add_u32_e32 v66, 0x1c000, v141
	ds_read_b128 v[42:45], v62
	ds_read_b128 v[46:49], v62 offset:1024
	ds_read_b128 v[58:61], v62 offset:2048
	ds_read_b128 v[62:65], v62 offset:3072
	ds_read_b128 v[74:77], v66
	ds_read_b128 v[78:81], v66 offset:1024
	ds_read_b128 v[82:85], v66 offset:2048
	ds_read_b128 v[90:93], v66 offset:3072
	ds_read_b128 v[66:69], v146 offset:32768
	ds_read_b128 v[70:73], v146 offset:33792
	ds_read_b128 v[98:101], v146 offset:34816
	ds_read_b128 v[102:105], v146 offset:35840
	ds_read_b128 v[106:109], v146 offset:36864
	ds_read_b128 v[110:113], v146 offset:37888
	ds_read_b128 v[142:145], v146 offset:38912
	ds_read_b128 v[146:149], v146 offset:39936
	s_mov_b32 m0, s35
	s_nop 0
	global_load_lds_dwordx4 v1, s[44:45]
	s_mov_b32 m0, s50
	s_nop 0
	global_load_lds_dwordx4 v133, s[44:45]
	s_add_u32 s44, s44, 0x80000
	s_addc_u32 s45, s45, 0
	s_mov_b32 m0, s51
	s_nop 0
	global_load_lds_dwordx4 v1, s[44:45]
	s_nop 0
	s_mov_b32 m0, s52
	s_nop 0
	global_load_lds_dwordx4 v133, s[44:45]
	s_waitcnt vmcnt(8)
	s_waitcnt lgkmcnt(0)
	s_barrier
	s_setprio 1
	s_waitcnt lgkmcnt(7)
	v_mfma_f32_16x16x32_bf16 v[118:121], v[42:45], v[66:69], v[122:125]
	v_mfma_f32_16x16x32_bf16 v[114:117], v[58:61], v[66:69], v[114:117]
	s_waitcnt lgkmcnt(5)
	v_mfma_f32_16x16x32_bf16 v[94:97], v[42:45], v[98:101], v[94:97]
	v_mfma_f32_16x16x32_bf16 v[86:89], v[58:61], v[98:101], v[86:89]
	s_waitcnt lgkmcnt(3)
	v_mfma_f32_16x16x32_bf16 v[54:57], v[42:45], v[106:109], v[54:57]
	v_mfma_f32_16x16x32_bf16 v[50:53], v[58:61], v[106:109], v[50:53]
	s_waitcnt lgkmcnt(1)
	v_mfma_f32_16x16x32_bf16 v[14:17], v[42:45], v[142:145], v[14:17]
	v_mfma_f32_16x16x32_bf16 v[10:13], v[58:61], v[142:145], v[10:13]
	v_mfma_f32_16x16x32_bf16 v[122:125], v[46:49], v[70:73], v[118:121]
	v_mfma_f32_16x16x32_bf16 v[114:117], v[62:65], v[70:73], v[114:117]
	v_mfma_f32_16x16x32_bf16 v[94:97], v[46:49], v[102:105], v[94:97]
	v_mfma_f32_16x16x32_bf16 v[86:89], v[62:65], v[102:105], v[86:89]
	v_mfma_f32_16x16x32_bf16 v[54:57], v[46:49], v[110:113], v[54:57]
	v_mfma_f32_16x16x32_bf16 v[50:53], v[62:65], v[110:113], v[50:53]
	s_waitcnt lgkmcnt(0)
	v_mfma_f32_16x16x32_bf16 v[14:17], v[46:49], v[146:149], v[14:17]
	v_mfma_f32_16x16x32_bf16 v[10:13], v[62:65], v[146:149], v[10:13]
	s_setprio 0
	s_setprio 1
	v_mfma_f32_16x16x32_bf16 v[18:21], v[74:77], v[66:69], v[18:21]
	v_mfma_f32_16x16x32_bf16 v[126:129], v[78:81], v[70:73], v[18:21]
	v_mfma_f32_16x16x32_bf16 v[18:21], v[82:85], v[66:69], v[22:25]
	v_mfma_f32_16x16x32_bf16 v[118:121], v[90:93], v[70:73], v[18:21]
	v_mfma_f32_16x16x32_bf16 v[18:21], v[74:77], v[98:101], v[26:29]
	v_mfma_f32_16x16x32_bf16 v[70:73], v[78:81], v[102:105], v[18:21]
	v_mfma_f32_16x16x32_bf16 v[18:21], v[82:85], v[98:101], v[30:33]
	v_mfma_f32_16x16x32_bf16 v[66:69], v[90:93], v[102:105], v[18:21]
	v_mfma_f32_16x16x32_bf16 v[18:21], v[74:77], v[106:109], v[38:41]
	v_mfma_f32_16x16x32_bf16 v[38:41], v[78:81], v[110:113], v[18:21]
	v_mfma_f32_16x16x32_bf16 v[18:21], v[82:85], v[106:109], v[34:37]
	v_mfma_f32_16x16x32_bf16 v[6:9], v[74:77], v[142:145], v[6:9]
	v_mfma_f32_16x16x32_bf16 v[2:5], v[82:85], v[142:145], v[2:5]
	v_mfma_f32_16x16x32_bf16 v[34:37], v[90:93], v[110:113], v[18:21]
	v_mfma_f32_16x16x32_bf16 v[6:9], v[78:81], v[146:149], v[6:9]
	v_mfma_f32_16x16x32_bf16 v[2:5], v[90:93], v[146:149], v[2:5]
	s_setprio 0
	s_barrier
	s_add_u32 s44, s42, 0x80
	s_addc_u32 s45, s43, 0
	s_mov_b32 m0, s53
	s_nop 0
	global_load_lds_dwordx4 v132, s[44:45]
	s_add_u32 s42, s42, 0x80080
	s_mov_b32 m0, s54
	s_nop 0
	global_load_lds_dwordx4 v134, s[44:45]
	s_addc_u32 s43, s43, 0
	s_mov_b32 m0, s57
	s_nop 0
	global_load_lds_dwordx4 v132, s[42:43]
	s_nop 0
	s_mov_b32 m0, s58
	s_nop 0
	global_load_lds_dwordx4 v134, s[42:43]
	s_nop 0
	s_waitcnt vmcnt(6)
	s_waitcnt lgkmcnt(0)
	s_barrier
	s_barrier
	s_cmp_gt_u32 s65, 29
	s_mov_b32 s65, s4
	s_cbranch_scc1 .LBB0_1033

; #define PG8_STAGE(bufoff, gbase, voff) do { _Pragma("unroll") for (int _i = 0; _i < 2; ++_i) \
;         asm volatile("s_mov_b32 m0, %0\n\ts_nop 0\n\tglobal_load_lds_dwordx4 %1, %2" :: "s"(ldsb + (unsigned)(bufoff) + ldsw + (unsigned)(_i * 8192)), "v"((voff)[_i]), "s"((const char*)(gbase)) : "memory", "m0"); } while (0)
; #define PG8_LDA(dst, b, h) do { _Pragma("unroll") for (int m = 0; m < 4; ++m) _Pragma("unroll") for (int k = 0; k < 2; ++k) dst[m][k] = *(const LAS bf16x8*)(lds + PG8_SA(b, h) + aoff + m * 2048 + k * 1024); } while (0)
; #define PG8_LDB(dst, b, h) do { _Pragma("unroll") for (int n = 0; n < 2; ++n) _Pragma("unroll") for (int k = 0; k < 2; ++k) dst[n][k] = *(const LAS bf16x8*)(lds + PG8_SB(b, h) + boff + n * 2048 + k * 1024); } while (0)
; #define PG8_MMA(ai, bj, At, Bt) do { __builtin_amdgcn_s_setprio(1); _Pragma("unroll") for (int m = 0; m < 4; ++m) _Pragma("unroll") for (int n = 0; n < 2; ++n) _Pragma("unroll") for (int k = 0; k < 2; ++k) \
;         acc[ai][bj][m][n] = __builtin_amdgcn_mfma_f32_16x16x32_bf16(Bt[n][k], At[m][k], acc[ai][bj][m][n], 0, 0, 0); __builtin_amdgcn_s_setprio(0); } while (0)
; #define PG8_WAIT_V(n) asm volatile("s_waitcnt vmcnt(" #n ")" ::: "memory")
; #define PG8_WAIT_L(n) asm volatile("s_waitcnt lgkmcnt(" #n ")" ::: "memory")
; #define PG8_BAR __builtin_amdgcn_s_barrier()
; template <class Epi, class Sched>
; __device__ __forceinline__ void gemm_phase(LAS unsigned char* lds, const Gemm g, const Sched& S, const Epi& E) {
;     ...
;             const char* a1 = cA + PG8_KOFF(t + 1) * (long)kstep;
;             const char* a2 = last ? nA : cA + PG8_KOFF(t + 2) * (long)kstep; const char* b2 = last ? nB : cB + PG8_KOFF(t + 2) * (long)kstep;
;             const char* a3 = a2 + kstep; const char* b3 = b2 + kstep;
;             if constexpr (Epi::HAS_MID) { if (t == Epi::MID_T) E.mid(acc, cur, wr, wc, fr, fq); }
;             PG8_LDB(B0, 0, 0); PG8_LDB(B1, 0, 1); PG8_SCHED; PG8_LDA(At, 0, 0); PG8_STAGE(PG8_SA(1, 1), a1 + hstepA, voffA);
;             PG8_WAIT_V(8); PG8_WAIT_L(0); PG8_BAR; PG8_MMA(0, 0, At, B0); PG8_MMA(0, 1, At, B1); PG8_BAR; PG8_SCHED;
;             PG8_LDA(At, 0, 1); PG8_STAGE(PG8_SB(0, 0), b2, voffB); PG8_STAGE(PG8_SB(0, 1), b2 + hstepB, voffB); PG8_STAGE(PG8_SA(0, 0), a2, voffA);
;             PG8_WAIT_V(8); PG8_WAIT_L(0); PG8_BAR; PG8_MMA(1, 0, At, B0); PG8_MMA(1, 1, At, B1); PG8_BAR; PG8_SCHED;
.LBB0_1102:
	ds_read_b128 v[134:137], v187
	ds_read_b128 v[138:141], v187 offset:1024
	ds_read_b128 v[142:145], v187 offset:2048
	ds_read_b128 v[146:149], v187 offset:3072
	ds_read_b128 v[150:153], v188
	ds_read_b128 v[154:157], v188 offset:1024
	ds_read_b128 v[158:161], v188 offset:2048
	ds_read_b128 v[162:165], v188 offset:3072
	s_add_i32 s82, s12, 2
	s_cmp_eq_u32 s20, s12
	s_cselect_b32 s16, s4, s78
	s_cselect_b32 s17, s5, s79
	s_cselect_b32 s14, s30, s80
	s_cselect_b32 s15, s31, s81
	s_add_u32 s12, s16, 0x80
	s_addc_u32 s13, s17, 0
	ds_read_b128 v[166:169], v189
	ds_read_b128 v[170:173], v189 offset:1024
	ds_read_b128 v[174:177], v189 offset:2048
	ds_read_b128 v[178:181], v189 offset:3072
	ds_read_b128 v[194:197], v189 offset:4096
	ds_read_b128 v[198:201], v189 offset:5120
	ds_read_b128 v[202:205], v189 offset:6144
	ds_read_b128 v[206:209], v189 offset:7168
	s_add_u32 s84, s78, 0xffffff80
	s_addc_u32 s85, s79, -1
	s_mov_b32 m0, s64
	s_nop 0
	global_load_lds_dwordx4 v1, s[84:85]
	s_mov_b32 m0, s65
	s_nop 0
	global_load_lds_dwordx4 v183, s[84:85]
	s_add_u32 s84, s78, 0x15ff80
	s_addc_u32 s85, s79, 0
	s_mov_b32 m0, s68
	s_nop 0
	global_load_lds_dwordx4 v1, s[84:85]
	s_nop 0
	s_mov_b32 m0, s69
	s_nop 0
	global_load_lds_dwordx4 v183, s[84:85]
	s_waitcnt vmcnt(8)
	s_waitcnt lgkmcnt(0)
	s_barrier
	s_setprio 1
	s_waitcnt lgkmcnt(7)
	v_mfma_f32_16x16x32_bf16 v[62:65], v[134:137], v[166:169], v[62:65]
	v_mfma_f32_16x16x32_bf16 v[58:61], v[142:145], v[166:169], v[58:61]
	s_waitcnt lgkmcnt(5)
	v_mfma_f32_16x16x32_bf16 v[54:57], v[134:137], v[174:177], v[54:57]
	v_mfma_f32_16x16x32_bf16 v[50:53], v[142:145], v[174:177], v[50:53]
	s_waitcnt lgkmcnt(3)
	v_mfma_f32_16x16x32_bf16 v[46:49], v[134:137], v[194:197], v[46:49]
	v_mfma_f32_16x16x32_bf16 v[42:45], v[142:145], v[194:197], v[42:45]
	s_waitcnt lgkmcnt(1)
	v_mfma_f32_16x16x32_bf16 v[30:33], v[134:137], v[202:205], v[30:33]
	v_mfma_f32_16x16x32_bf16 v[26:29], v[142:145], v[202:205], v[26:29]
	v_mfma_f32_16x16x32_bf16 v[62:65], v[138:141], v[170:173], v[62:65]
	v_mfma_f32_16x16x32_bf16 v[58:61], v[146:149], v[170:173], v[58:61]
	v_mfma_f32_16x16x32_bf16 v[54:57], v[138:141], v[178:181], v[54:57]
	v_mfma_f32_16x16x32_bf16 v[50:53], v[146:149], v[178:181], v[50:53]
	v_mfma_f32_16x16x32_bf16 v[46:49], v[138:141], v[198:201], v[46:49]
	v_mfma_f32_16x16x32_bf16 v[42:45], v[146:149], v[198:201], v[42:45]
	s_waitcnt lgkmcnt(0)
	v_mfma_f32_16x16x32_bf16 v[30:33], v[138:141], v[206:209], v[30:33]
	v_mfma_f32_16x16x32_bf16 v[26:29], v[146:149], v[206:209], v[26:29]
	s_setprio 0
	s_setprio 1
	v_mfma_f32_16x16x32_bf16 v[38:41], v[150:153], v[166:169], v[38:41]
	v_mfma_f32_16x16x32_bf16 v[34:37], v[158:161], v[166:169], v[34:37]
	v_mfma_f32_16x16x32_bf16 v[22:25], v[150:153], v[174:177], v[22:25]
	v_mfma_f32_16x16x32_bf16 v[18:21], v[158:161], v[174:177], v[18:21]
	v_mfma_f32_16x16x32_bf16 v[14:17], v[150:153], v[194:197], v[14:17]
	v_mfma_f32_16x16x32_bf16 v[10:13], v[158:161], v[194:197], v[10:13]
	v_mfma_f32_16x16x32_bf16 v[6:9], v[150:153], v[202:205], v[6:9]
	v_mfma_f32_16x16x32_bf16 v[2:5], v[158:161], v[202:205], v[2:5]
	v_mfma_f32_16x16x32_bf16 v[38:41], v[154:157], v[170:173], v[38:41]
	v_mfma_f32_16x16x32_bf16 v[34:37], v[162:165], v[170:173], v[34:37]
	v_mfma_f32_16x16x32_bf16 v[22:25], v[154:157], v[178:181], v[22:25]
	v_mfma_f32_16x16x32_bf16 v[18:21], v[162:165], v[178:181], v[18:21]
	v_mfma_f32_16x16x32_bf16 v[14:17], v[154:157], v[198:201], v[14:17]
	v_mfma_f32_16x16x32_bf16 v[10:13], v[162:165], v[198:201], v[10:13]
	v_mfma_f32_16x16x32_bf16 v[6:9], v[154:157], v[206:209], v[6:9]
	v_mfma_f32_16x16x32_bf16 v[2:5], v[162:165], v[206:209], v[2:5]
	s_setprio 0
	s_barrier
	ds_read_b128 v[166:169], v189 offset:16384
	ds_read_b128 v[170:173], v189 offset:17408
	ds_read_b128 v[174:177], v189 offset:18432
	ds_read_b128 v[178:181], v189 offset:19456
	ds_read_b128 v[194:197], v189 offset:20480
	ds_read_b128 v[198:201], v189 offset:21504
	ds_read_b128 v[202:205], v189 offset:22528
	ds_read_b128 v[206:209], v189 offset:23552
	s_mov_b32 m0, s37
	s_nop 0
	global_load_lds_dwordx4 v182, s[14:15]
	s_add_u32 s84, s14, 0x160000
	s_mov_b32 m0, s45
	s_nop 0
	global_load_lds_dwordx4 v184, s[14:15]
	s_addc_u32 s85, s15, 0
	s_mov_b32 m0, s47
	s_nop 0
	global_load_lds_dwordx4 v182, s[84:85]
	s_nop 0
	s_mov_b32 m0, s56
	s_nop 0
	global_load_lds_dwordx4 v184, s[84:85]
	s_nop 0
	s_waitcnt vmcnt(6)
	s_waitcnt lgkmcnt(0)
	s_barrier
; #define PG8_STAGE(bufoff, gbase, voff) do { _Pragma("unroll") for (int _i = 0; _i < 2; ++_i) \
;         asm volatile("s_mov_b32 m0, %0\n\ts_nop 0\n\tglobal_load_lds_dwordx4 %1, %2" :: "s"(ldsb + (unsigned)(bufoff) + ldsw + (unsigned)(_i * 8192)), "v"((voff)[_i]), "s"((const char*)(gbase)) : "memory", "m0"); } while (0)
; #define PG8_LDA(dst, b, h) do { _Pragma("unroll") for (int m = 0; m < 4; ++m) _Pragma("unroll") for (int k = 0; k < 2; ++k) dst[m][k] = *(const LAS bf16x8*)(lds + PG8_SA(b, h) + aoff + m * 2048 + k * 1024); } while (0)
; #define PG8_LDB(dst, b, h) do { _Pragma("unroll") for (int n = 0; n < 2; ++n) _Pragma("unroll") for (int k = 0; k < 2; ++k) dst[n][k] = *(const LAS bf16x8*)(lds + PG8_SB(b, h) + boff + n * 2048 + k * 1024); } while (0)
; #define PG8_MMA(ai, bj, At, Bt) do { __builtin_amdgcn_s_setprio(1); _Pragma("unroll") for (int m = 0; m < 4; ++m) _Pragma("unroll") for (int n = 0; n < 2; ++n) _Pragma("unroll") for (int k = 0; k < 2; ++k) \
;         acc[ai][bj][m][n] = __builtin_amdgcn_mfma_f32_16x16x32_bf16(Bt[n][k], At[m][k], acc[ai][bj][m][n], 0, 0, 0); __builtin_amdgcn_s_setprio(0); } while (0)
; #define PG8_WAIT_V(n) asm volatile("s_waitcnt vmcnt(" #n ")" ::: "memory")
; #define PG8_WAIT_L(n) asm volatile("s_waitcnt lgkmcnt(" #n ")" ::: "memory")
; #define PG8_BAR __builtin_amdgcn_s_barrier()
; template <class Epi, class Sched>
; __device__ __forceinline__ void gemm_phase(LAS unsigned char* lds, const Gemm g, const Sched& S, const Epi& E) {
;     ...
;             PG8_WAIT_V(8); PG8_WAIT_L(0); PG8_BAR; PG8_MMA(0, 0, At, B0); PG8_MMA(0, 1, At, B1); PG8_BAR; PG8_SCHED;
;             PG8_LDA(At, 0, 1); PG8_STAGE(PG8_SB(0, 0), b2, voffB); PG8_STAGE(PG8_SB(0, 1), b2 + hstepB, voffB); PG8_STAGE(PG8_SA(0, 0), a2, voffA);
;             PG8_WAIT_V(8); PG8_WAIT_L(0); PG8_BAR; PG8_MMA(1, 0, At, B0); PG8_MMA(1, 1, At, B1); PG8_BAR; PG8_SCHED;
;             PG8_LDB(B0, 1, 0); PG8_LDB(B1, 1, 1); PG8_SCHED; PG8_LDA(At, 1, 0); PG8_STAGE(PG8_SA(0, 1), a2 + hstepA, voffA);
;             PG8_WAIT_V(8); PG8_WAIT_L(0); PG8_BAR; PG8_MMA(0, 0, At, B0); PG8_MMA(0, 1, At, B1); PG8_BAR; PG8_SCHED;
;             PG8_LDA(At, 1, 1); PG8_STAGE(PG8_SB(1, 0), b3, voffB); PG8_STAGE(PG8_SB(1, 1), b3 + hstepB, voffB); PG8_STAGE(PG8_SA(1, 0), a3, voffA);
;             PG8_WAIT_V(8); PG8_WAIT_L(0); PG8_BAR; PG8_MMA(1, 0, At, B0); PG8_MMA(1, 1, At, B1); PG8_BAR; PG8_SCHED;
	s_setprio 1
	s_waitcnt lgkmcnt(7)
	v_mfma_f32_16x16x32_bf16 v[126:129], v[134:137], v[166:169], v[126:129]
	v_mfma_f32_16x16x32_bf16 v[122:125], v[142:145], v[166:169], v[122:125]
	s_waitcnt lgkmcnt(5)
	v_mfma_f32_16x16x32_bf16 v[118:121], v[134:137], v[174:177], v[118:121]
	v_mfma_f32_16x16x32_bf16 v[114:117], v[142:145], v[174:177], v[114:117]
	s_waitcnt lgkmcnt(3)
	v_mfma_f32_16x16x32_bf16 v[106:109], v[134:137], v[194:197], v[106:109]
	v_mfma_f32_16x16x32_bf16 v[98:101], v[142:145], v[194:197], v[98:101]
	s_waitcnt lgkmcnt(1)
	v_mfma_f32_16x16x32_bf16 v[90:93], v[134:137], v[202:205], v[90:93]
	v_mfma_f32_16x16x32_bf16 v[82:85], v[142:145], v[202:205], v[82:85]
	v_mfma_f32_16x16x32_bf16 v[126:129], v[138:141], v[170:173], v[126:129]
	v_mfma_f32_16x16x32_bf16 v[122:125], v[146:149], v[170:173], v[122:125]
	v_mfma_f32_16x16x32_bf16 v[118:121], v[138:141], v[178:181], v[118:121]
	v_mfma_f32_16x16x32_bf16 v[114:117], v[146:149], v[178:181], v[114:117]
	v_mfma_f32_16x16x32_bf16 v[106:109], v[138:141], v[198:201], v[106:109]
	v_mfma_f32_16x16x32_bf16 v[98:101], v[146:149], v[198:201], v[98:101]
	s_waitcnt lgkmcnt(0)
	v_mfma_f32_16x16x32_bf16 v[90:93], v[138:141], v[206:209], v[90:93]
	v_mfma_f32_16x16x32_bf16 v[82:85], v[146:149], v[206:209], v[82:85]
	s_setprio 0
	s_setprio 1
	v_mfma_f32_16x16x32_bf16 v[110:113], v[150:153], v[166:169], v[110:113]
	v_mfma_f32_16x16x32_bf16 v[102:105], v[158:161], v[166:169], v[102:105]
	v_mfma_f32_16x16x32_bf16 v[94:97], v[150:153], v[174:177], v[94:97]
	v_mfma_f32_16x16x32_bf16 v[86:89], v[158:161], v[174:177], v[86:89]
	v_mfma_f32_16x16x32_bf16 v[78:81], v[150:153], v[194:197], v[78:81]
	v_mfma_f32_16x16x32_bf16 v[74:77], v[158:161], v[194:197], v[74:77]
	v_mfma_f32_16x16x32_bf16 v[70:73], v[150:153], v[202:205], v[70:73]
	v_mfma_f32_16x16x32_bf16 v[66:69], v[158:161], v[202:205], v[66:69]
	v_mfma_f32_16x16x32_bf16 v[110:113], v[154:157], v[170:173], v[110:113]
	v_mfma_f32_16x16x32_bf16 v[102:105], v[162:165], v[170:173], v[102:105]
	v_mfma_f32_16x16x32_bf16 v[94:97], v[154:157], v[178:181], v[94:97]
	v_mfma_f32_16x16x32_bf16 v[86:89], v[162:165], v[178:181], v[86:89]
	v_mfma_f32_16x16x32_bf16 v[78:81], v[154:157], v[198:201], v[78:81]
	v_mfma_f32_16x16x32_bf16 v[74:77], v[162:165], v[198:201], v[74:77]
	v_mfma_f32_16x16x32_bf16 v[70:73], v[154:157], v[206:209], v[70:73]
	v_mfma_f32_16x16x32_bf16 v[66:69], v[162:165], v[206:209], v[66:69]
	s_setprio 0
	s_barrier
	ds_read_b128 v[134:137], v190
	ds_read_b128 v[138:141], v190 offset:1024
	ds_read_b128 v[142:145], v190 offset:2048
	ds_read_b128 v[146:149], v190 offset:3072
	ds_read_b128 v[150:153], v191
	ds_read_b128 v[154:157], v191 offset:1024
	ds_read_b128 v[158:161], v191 offset:2048
	ds_read_b128 v[162:165], v191 offset:3072
	ds_read_b128 v[166:169], v189 offset:32768
	ds_read_b128 v[170:173], v189 offset:33792
	ds_read_b128 v[174:177], v189 offset:34816
	ds_read_b128 v[178:181], v189 offset:35840
	ds_read_b128 v[194:197], v189 offset:36864
	ds_read_b128 v[198:201], v189 offset:37888
	ds_read_b128 v[202:205], v189 offset:38912
	ds_read_b128 v[206:209], v189 offset:39936
	s_mov_b32 m0, s35
	s_nop 0
	global_load_lds_dwordx4 v1, s[16:17]
	s_mov_b32 m0, s57
	s_nop 0
	global_load_lds_dwordx4 v183, s[16:17]
	s_add_u32 s16, s16, 0x160000
	s_addc_u32 s17, s17, 0
	s_mov_b32 m0, s58
	s_nop 0
	global_load_lds_dwordx4 v1, s[16:17]
	s_nop 0
	s_mov_b32 m0, s59
	s_nop 0
	global_load_lds_dwordx4 v183, s[16:17]
	s_waitcnt vmcnt(8)
	s_waitcnt lgkmcnt(0)
	s_barrier
	s_setprio 1
	s_waitcnt lgkmcnt(7)
	v_mfma_f32_16x16x32_bf16 v[62:65], v[134:137], v[166:169], v[62:65]
	v_mfma_f32_16x16x32_bf16 v[58:61], v[142:145], v[166:169], v[58:61]
	s_waitcnt lgkmcnt(5)
	v_mfma_f32_16x16x32_bf16 v[54:57], v[134:137], v[174:177], v[54:57]
	v_mfma_f32_16x16x32_bf16 v[50:53], v[142:145], v[174:177], v[50:53]
	s_waitcnt lgkmcnt(3)
	v_mfma_f32_16x16x32_bf16 v[46:49], v[134:137], v[194:197], v[46:49]
	v_mfma_f32_16x16x32_bf16 v[42:45], v[142:145], v[194:197], v[42:45]
	s_waitcnt lgkmcnt(1)
	v_mfma_f32_16x16x32_bf16 v[30:33], v[134:137], v[202:205], v[30:33]
	v_mfma_f32_16x16x32_bf16 v[26:29], v[142:145], v[202:205], v[26:29]
	v_mfma_f32_16x16x32_bf16 v[62:65], v[138:141], v[170:173], v[62:65]
	v_mfma_f32_16x16x32_bf16 v[58:61], v[146:149], v[170:173], v[58:61]
	v_mfma_f32_16x16x32_bf16 v[54:57], v[138:141], v[178:181], v[54:57]
	v_mfma_f32_16x16x32_bf16 v[50:53], v[146:149], v[178:181], v[50:53]
	v_mfma_f32_16x16x32_bf16 v[46:49], v[138:141], v[198:201], v[46:49]
	v_mfma_f32_16x16x32_bf16 v[42:45], v[146:149], v[198:201], v[42:45]
	s_waitcnt lgkmcnt(0)
	v_mfma_f32_16x16x32_bf16 v[30:33], v[138:141], v[206:209], v[30:33]
	v_mfma_f32_16x16x32_bf16 v[26:29], v[146:149], v[206:209], v[26:29]
	s_setprio 0
	s_setprio 1
	v_mfma_f32_16x16x32_bf16 v[38:41], v[150:153], v[166:169], v[38:41]
	v_mfma_f32_16x16x32_bf16 v[34:37], v[158:161], v[166:169], v[34:37]
	v_mfma_f32_16x16x32_bf16 v[22:25], v[150:153], v[174:177], v[22:25]
	v_mfma_f32_16x16x32_bf16 v[18:21], v[158:161], v[174:177], v[18:21]
	v_mfma_f32_16x16x32_bf16 v[14:17], v[150:153], v[194:197], v[14:17]
	v_mfma_f32_16x16x32_bf16 v[10:13], v[158:161], v[194:197], v[10:13]
	v_mfma_f32_16x16x32_bf16 v[6:9], v[150:153], v[202:205], v[6:9]
	v_mfma_f32_16x16x32_bf16 v[2:5], v[158:161], v[202:205], v[2:5]
	v_mfma_f32_16x16x32_bf16 v[38:41], v[154:157], v[170:173], v[38:41]
	v_mfma_f32_16x16x32_bf16 v[34:37], v[162:165], v[170:173], v[34:37]
	v_mfma_f32_16x16x32_bf16 v[22:25], v[154:157], v[178:181], v[22:25]
	v_mfma_f32_16x16x32_bf16 v[18:21], v[162:165], v[178:181], v[18:21]
	v_mfma_f32_16x16x32_bf16 v[14:17], v[154:157], v[198:201], v[14:17]
	v_mfma_f32_16x16x32_bf16 v[10:13], v[162:165], v[198:201], v[10:13]
	v_mfma_f32_16x16x32_bf16 v[6:9], v[154:157], v[206:209], v[6:9]
	v_mfma_f32_16x16x32_bf16 v[2:5], v[162:165], v[206:209], v[2:5]
	s_setprio 0
	s_barrier
; #define PG8_STAGE(bufoff, gbase, voff) do { _Pragma("unroll") for (int _i = 0; _i < 2; ++_i) \
;         asm volatile("s_mov_b32 m0, %0\n\ts_nop 0\n\tglobal_load_lds_dwordx4 %1, %2" :: "s"(ldsb + (unsigned)(bufoff) + ldsw + (unsigned)(_i * 8192)), "v"((voff)[_i]), "s"((const char*)(gbase)) : "memory", "m0"); } while (0)
; #define PG8_LDA(dst, b, h) do { _Pragma("unroll") for (int m = 0; m < 4; ++m) _Pragma("unroll") for (int k = 0; k < 2; ++k) dst[m][k] = *(const LAS bf16x8*)(lds + PG8_SA(b, h) + aoff + m * 2048 + k * 1024); } while (0)
; #define PG8_MMA(ai, bj, At, Bt) do { __builtin_amdgcn_s_setprio(1); _Pragma("unroll") for (int m = 0; m < 4; ++m) _Pragma("unroll") for (int n = 0; n < 2; ++n) _Pragma("unroll") for (int k = 0; k < 2; ++k) \
;         acc[ai][bj][m][n] = __builtin_amdgcn_mfma_f32_16x16x32_bf16(Bt[n][k], At[m][k], acc[ai][bj][m][n], 0, 0, 0); __builtin_amdgcn_s_setprio(0); } while (0)
; #define PG8_WAIT_V(n) asm volatile("s_waitcnt vmcnt(" #n ")" ::: "memory")
; #define PG8_WAIT_L(n) asm volatile("s_waitcnt lgkmcnt(" #n ")" ::: "memory")
; #define PG8_BAR __builtin_amdgcn_s_barrier()
; #define PG8_SCHED __builtin_amdgcn_sched_barrier(0)
; template <class Epi, class Sched>
; __device__ __forceinline__ void gemm_phase(LAS unsigned char* lds, const Gemm g, const Sched& S, const Epi& E) {
;     ...
;             PG8_WAIT_V(8); PG8_WAIT_L(0); PG8_BAR; PG8_MMA(0, 0, At, B0); PG8_MMA(0, 1, At, B1); PG8_BAR; PG8_SCHED;
;             PG8_LDA(At, 1, 1); PG8_STAGE(PG8_SB(1, 0), b3, voffB); PG8_STAGE(PG8_SB(1, 1), b3 + hstepB, voffB); PG8_STAGE(PG8_SA(1, 0), a3, voffA);
;             PG8_WAIT_V(8); PG8_WAIT_L(0); PG8_BAR; PG8_MMA(1, 0, At, B0); PG8_MMA(1, 1, At, B1); PG8_BAR; PG8_SCHED;
;         }
	ds_read_b128 v[166:169], v189 offset:49152
	ds_read_b128 v[170:173], v189 offset:50176
	ds_read_b128 v[174:177], v189 offset:51200
	ds_read_b128 v[178:181], v189 offset:52224
	ds_read_b128 v[194:197], v189 offset:53248
	ds_read_b128 v[198:201], v189 offset:54272
	ds_read_b128 v[202:205], v189 offset:55296
	ds_read_b128 v[206:209], v189 offset:56320
	s_add_u32 s16, s14, 0x80
	s_addc_u32 s17, s15, 0
	s_mov_b32 m0, s62
	s_nop 0
	global_load_lds_dwordx4 v182, s[16:17]
	s_add_u32 s14, s14, 0x160080
	s_mov_b32 m0, s63
	s_nop 0
	global_load_lds_dwordx4 v184, s[16:17]
	s_addc_u32 s15, s15, 0
	s_mov_b32 m0, s66
	s_nop 0
	global_load_lds_dwordx4 v182, s[14:15]
	s_nop 0
	s_mov_b32 m0, s67
	s_nop 0
	global_load_lds_dwordx4 v184, s[14:15]
	s_nop 0
	s_waitcnt vmcnt(6)
	s_waitcnt lgkmcnt(0)
	s_barrier
	s_setprio 1
	s_waitcnt lgkmcnt(7)
	v_mfma_f32_16x16x32_bf16 v[126:129], v[134:137], v[166:169], v[126:129]
	v_mfma_f32_16x16x32_bf16 v[122:125], v[142:145], v[166:169], v[122:125]
	s_waitcnt lgkmcnt(5)
	v_mfma_f32_16x16x32_bf16 v[118:121], v[134:137], v[174:177], v[118:121]
	v_mfma_f32_16x16x32_bf16 v[114:117], v[142:145], v[174:177], v[114:117]
	s_waitcnt lgkmcnt(3)
	v_mfma_f32_16x16x32_bf16 v[106:109], v[134:137], v[194:197], v[106:109]
	v_mfma_f32_16x16x32_bf16 v[98:101], v[142:145], v[194:197], v[98:101]
	s_waitcnt lgkmcnt(1)
	v_mfma_f32_16x16x32_bf16 v[90:93], v[134:137], v[202:205], v[90:93]
	v_mfma_f32_16x16x32_bf16 v[82:85], v[142:145], v[202:205], v[82:85]
	v_mfma_f32_16x16x32_bf16 v[126:129], v[138:141], v[170:173], v[126:129]
	v_mfma_f32_16x16x32_bf16 v[122:125], v[146:149], v[170:173], v[122:125]
	v_mfma_f32_16x16x32_bf16 v[118:121], v[138:141], v[178:181], v[118:121]
	v_mfma_f32_16x16x32_bf16 v[114:117], v[146:149], v[178:181], v[114:117]
	v_mfma_f32_16x16x32_bf16 v[106:109], v[138:141], v[198:201], v[106:109]
	v_mfma_f32_16x16x32_bf16 v[98:101], v[146:149], v[198:201], v[98:101]
	s_waitcnt lgkmcnt(0)
	v_mfma_f32_16x16x32_bf16 v[90:93], v[138:141], v[206:209], v[90:93]
	v_mfma_f32_16x16x32_bf16 v[82:85], v[146:149], v[206:209], v[82:85]
	s_setprio 0
	s_setprio 1
	v_mfma_f32_16x16x32_bf16 v[110:113], v[150:153], v[166:169], v[110:113]
	v_mfma_f32_16x16x32_bf16 v[102:105], v[158:161], v[166:169], v[102:105]
	v_mfma_f32_16x16x32_bf16 v[94:97], v[150:153], v[174:177], v[94:97]
	v_mfma_f32_16x16x32_bf16 v[86:89], v[158:161], v[174:177], v[86:89]
	v_mfma_f32_16x16x32_bf16 v[78:81], v[150:153], v[194:197], v[78:81]
	v_mfma_f32_16x16x32_bf16 v[74:77], v[158:161], v[194:197], v[74:77]
	v_mfma_f32_16x16x32_bf16 v[70:73], v[150:153], v[202:205], v[70:73]
	v_mfma_f32_16x16x32_bf16 v[66:69], v[158:161], v[202:205], v[66:69]
	v_mfma_f32_16x16x32_bf16 v[110:113], v[154:157], v[170:173], v[110:113]
	v_mfma_f32_16x16x32_bf16 v[102:105], v[162:165], v[170:173], v[102:105]
	v_mfma_f32_16x16x32_bf16 v[94:97], v[154:157], v[178:181], v[94:97]
	v_mfma_f32_16x16x32_bf16 v[86:89], v[162:165], v[178:181], v[86:89]
	v_mfma_f32_16x16x32_bf16 v[78:81], v[154:157], v[198:201], v[78:81]
	v_mfma_f32_16x16x32_bf16 v[74:77], v[162:165], v[198:201], v[74:77]
	v_mfma_f32_16x16x32_bf16 v[70:73], v[154:157], v[206:209], v[70:73]
	v_mfma_f32_16x16x32_bf16 v[66:69], v[162:165], v[206:209], v[66:69]
	s_setprio 0
	s_barrier
	s_add_u32 s78, s78, 0x100
	s_addc_u32 s79, s79, 0
	s_add_u32 s80, s80, 0x100
	s_addc_u32 s81, s81, 0
	s_cmp_ge_i32 s82, s33
	s_mov_b32 s12, s82
	s_cbranch_scc0 .LBB0_1102
	v_pk_mul_f32 v[154:155], v[128:129], 0.5 op_sel_hi:[1,0]
	v_pk_mul_f32 v[156:157], v[126:127], 0.5 op_sel_hi:[1,0]
	v_pk_mul_f32 v[158:159], v[124:125], 0.5 op_sel_hi:[1,0]
	v_pk_mul_f32 v[160:161], v[122:123], 0.5 op_sel_hi:[1,0]
	v_pk_mul_f32 v[162:163], v[112:113], 0.5 op_sel_hi:[1,0]
	v_pk_mul_f32 v[164:165], v[110:111], 0.5 op_sel_hi:[1,0]
	v_pk_mul_f32 v[168:169], v[104:105], 0.5 op_sel_hi:[1,0]
	v_pk_mul_f32 v[166:167], v[102:103], 0.5 op_sel_hi:[1,0]
	v_pk_mul_f32 v[144:145], v[120:121], 0.5 op_sel_hi:[1,0]
	v_pk_mul_f32 v[142:143], v[118:119], 0.5 op_sel_hi:[1,0]
	v_pk_mul_f32 v[140:141], v[116:117], 0.5 op_sel_hi:[1,0]
	v_pk_mul_f32 v[138:139], v[114:115], 0.5 op_sel_hi:[1,0]
	v_pk_mul_f32 v[152:153], v[96:97], 0.5 op_sel_hi:[1,0]
	v_pk_mul_f32 v[150:151], v[94:95], 0.5 op_sel_hi:[1,0]
	v_pk_mul_f32 v[148:149], v[88:89], 0.5 op_sel_hi:[1,0]
	v_pk_mul_f32 v[146:147], v[86:87], 0.5 op_sel_hi:[1,0]
	v_pk_mul_f32 v[118:119], v[108:109], 0.5 op_sel_hi:[1,0]
	v_pk_mul_f32 v[116:117], v[106:107], 0.5 op_sel_hi:[1,0]
	v_pk_mul_f32 v[114:115], v[100:101], 0.5 op_sel_hi:[1,0]
	v_pk_mul_f32 v[112:113], v[98:99], 0.5 op_sel_hi:[1,0]
	v_pk_mul_f32 v[126:127], v[80:81], 0.5 op_sel_hi:[1,0]
	v_pk_mul_f32 v[124:125], v[78:79], 0.5 op_sel_hi:[1,0]
	v_pk_mul_f32 v[122:123], v[76:77], 0.5 op_sel_hi:[1,0]
	v_pk_mul_f32 v[120:121], v[74:75], 0.5 op_sel_hi:[1,0]
	v_pk_mul_f32 v[98:99], v[92:93], 0.5 op_sel_hi:[1,0]
	v_pk_mul_f32 v[96:97], v[90:91], 0.5 op_sel_hi:[1,0]
	v_pk_mul_f32 v[94:95], v[84:85], 0.5 op_sel_hi:[1,0]
	v_pk_mul_f32 v[92:93], v[82:83], 0.5 op_sel_hi:[1,0]
	v_pk_mul_f32 v[108:109], v[72:73], 0.5 op_sel_hi:[1,0]
	v_pk_mul_f32 v[106:107], v[70:71], 0.5 op_sel_hi:[1,0]
	v_pk_mul_f32 v[104:105], v[68:69], 0.5 op_sel_hi:[1,0]
	v_pk_mul_f32 v[102:103], v[66:67], 0.5 op_sel_hi:[1,0]

;     __device__ __forceinline__ void a_ready(const Unit&) const { wait_cnt(w_ready, w_need); }
;     __device__ __forceinline__ void half_ready(const Unit& u) const { wait_cnt(g_ready + 64 * u.pm, g_need); }
; #define PG8_STAGE(bufoff, gbase, voff) do { _Pragma("unroll") for (int _i = 0; _i < 2; ++_i) \
;         asm volatile("s_mov_b32 m0, %0\n\ts_nop 0\n\tglobal_load_lds_dwordx4 %1, %2" :: "s"(ldsb + (unsigned)(bufoff) + ldsw + (unsigned)(_i * 8192)), "v"((voff)[_i]), "s"((const char*)(gbase)) : "memory", "m0"); } while (0)
; #define PG8_LDA(dst, b, h) do { _Pragma("unroll") for (int m = 0; m < 4; ++m) _Pragma("unroll") for (int k = 0; k < 2; ++k) dst[m][k] = *(const LAS bf16x8*)(lds + PG8_SA(b, h) + aoff + m * 2048 + k * 1024); } while (0)
; #define PG8_LDB(dst, b, h) do { _Pragma("unroll") for (int n = 0; n < 2; ++n) _Pragma("unroll") for (int k = 0; k < 2; ++k) dst[n][k] = *(const LAS bf16x8*)(lds + PG8_SB(b, h) + boff + n * 2048 + k * 1024); } while (0)
; #define PG8_BAR __builtin_amdgcn_s_barrier()
; template <class Epi, class Sched>
; __device__ __forceinline__ void gemm_phase(LAS unsigned char* lds, const Gemm g, const Sched& S, const Epi& E) {
;     ...
;         for (int t = 0; t < nt; t += 2) {
;             const bool last = (t == nt - 2);
;             if (last && has_next) S.a_ready(nxt);
;             if constexpr (Sched::TWO_HALVES) { if (t == KSW - 2) S.half_ready(cur); }
;             const char* a1 = cA + PG8_KOFF(t + 1) * (long)kstep;
;             const char* a2 = last ? nA : cA + PG8_KOFF(t + 2) * (long)kstep; const char* b2 = last ? nB : cB + PG8_KOFF(t + 2) * (long)kstep;
;             const char* a3 = a2 + kstep; const char* b3 = b2 + kstep;
;             if constexpr (Epi::HAS_MID) { if (t == Epi::MID_T) E.mid(acc, cur, wr, wc, fr, fq); }
;             PG8_LDB(B0, 0, 0); PG8_LDB(B1, 0, 1); PG8_SCHED; PG8_LDA(At, 0, 0); PG8_STAGE(PG8_SA(1, 1), a1 + hstepA, voffA);
;             PG8_WAIT_V(8); PG8_WAIT_L(0); PG8_BAR; PG8_MMA(0, 0, At, B0); PG8_MMA(0, 1, At, B1); PG8_BAR; PG8_SCHED;
;             PG8_LDA(At, 0, 1); PG8_STAGE(PG8_SB(0, 0), b2, voffB); PG8_STAGE(PG8_SB(0, 1), b2 + hstepB, voffB); PG8_STAGE(PG8_SA(0, 0), a2, voffA);
;             PG8_WAIT_V(8); PG8_WAIT_L(0); PG8_BAR; PG8_BAR; PG8_SCHED;
;             PG8_LDB(B0, 1, 0); PG8_LDB(B1, 1, 1); PG8_SCHED; PG8_LDA(At, 1, 0); PG8_STAGE(PG8_SA(0, 1), a2 + hstepA, voffA);
.LBB0_1110:
	ds_read_b128 v[66:69], v187
	s_waitcnt vmcnt(0)
	ds_read_b128 v[70:73], v187 offset:1024
	ds_read_b128 v[74:77], v187 offset:2048
	ds_read_b128 v[78:81], v187 offset:3072
	ds_read_b128 v[82:85], v188
	ds_read_b128 v[86:89], v188 offset:1024
	ds_read_b128 v[90:93], v188 offset:2048
	ds_read_b128 v[94:97], v188 offset:3072
	s_add_i32 s78, s12, 2
	s_cmp_eq_u32 s20, s12
	s_cselect_b32 s16, s4, s23
	s_cselect_b32 s17, s5, s55
	s_cselect_b32 s14, s30, s21
	s_cselect_b32 s15, s31, s22
	s_add_u32 s12, s16, 0x80
	s_addc_u32 s13, s17, 0
	ds_read_b128 v[98:101], v189
	ds_read_b128 v[102:105], v189 offset:1024
	ds_read_b128 v[106:109], v189 offset:2048
	ds_read_b128 v[110:113], v189 offset:3072
	ds_read_b128 v[114:117], v189 offset:4096
	ds_read_b128 v[118:121], v189 offset:5120
	ds_read_b128 v[122:125], v189 offset:6144
	ds_read_b128 v[126:129], v189 offset:7168
	s_add_u32 s80, s23, 0xffffff80
	s_addc_u32 s81, s55, -1
	s_mov_b32 m0, s64
	s_nop 0
	global_load_lds_dwordx4 v1, s[80:81]
	s_mov_b32 m0, s65
	s_nop 0
	global_load_lds_dwordx4 v183, s[80:81]
	s_add_u32 s80, s23, 0x15ff80
	s_addc_u32 s81, s55, 0
	s_mov_b32 m0, s68
	s_nop 0
	global_load_lds_dwordx4 v1, s[80:81]
	s_nop 0
	s_mov_b32 m0, s69
	s_nop 0
	global_load_lds_dwordx4 v183, s[80:81]
	s_waitcnt vmcnt(8)
	s_waitcnt lgkmcnt(0)
	s_barrier
	s_setprio 1
	s_waitcnt lgkmcnt(7)
	v_mfma_f32_16x16x32_bf16 v[62:65], v[66:69], v[98:101], v[62:65]
	v_mfma_f32_16x16x32_bf16 v[58:61], v[74:77], v[98:101], v[58:61]
	s_waitcnt lgkmcnt(5)
	v_mfma_f32_16x16x32_bf16 v[54:57], v[66:69], v[106:109], v[54:57]
	v_mfma_f32_16x16x32_bf16 v[50:53], v[74:77], v[106:109], v[50:53]
	s_waitcnt lgkmcnt(3)
	v_mfma_f32_16x16x32_bf16 v[46:49], v[66:69], v[114:117], v[46:49]
	v_mfma_f32_16x16x32_bf16 v[42:45], v[74:77], v[114:117], v[42:45]
	s_waitcnt lgkmcnt(1)
	v_mfma_f32_16x16x32_bf16 v[30:33], v[66:69], v[122:125], v[30:33]
	v_mfma_f32_16x16x32_bf16 v[26:29], v[74:77], v[122:125], v[26:29]
	v_mfma_f32_16x16x32_bf16 v[62:65], v[70:73], v[102:105], v[62:65]
	v_mfma_f32_16x16x32_bf16 v[58:61], v[78:81], v[102:105], v[58:61]
	v_mfma_f32_16x16x32_bf16 v[54:57], v[70:73], v[110:113], v[54:57]
	v_mfma_f32_16x16x32_bf16 v[50:53], v[78:81], v[110:113], v[50:53]
	v_mfma_f32_16x16x32_bf16 v[46:49], v[70:73], v[118:121], v[46:49]
	v_mfma_f32_16x16x32_bf16 v[42:45], v[78:81], v[118:121], v[42:45]
	s_waitcnt lgkmcnt(0)
	v_mfma_f32_16x16x32_bf16 v[30:33], v[70:73], v[126:129], v[30:33]
	v_mfma_f32_16x16x32_bf16 v[26:29], v[78:81], v[126:129], v[26:29]
	s_setprio 0
	s_setprio 1
	v_mfma_f32_16x16x32_bf16 v[38:41], v[82:85], v[98:101], v[38:41]
	v_mfma_f32_16x16x32_bf16 v[34:37], v[90:93], v[98:101], v[34:37]
	v_mfma_f32_16x16x32_bf16 v[22:25], v[82:85], v[106:109], v[22:25]
	v_mfma_f32_16x16x32_bf16 v[18:21], v[90:93], v[106:109], v[18:21]
	v_mfma_f32_16x16x32_bf16 v[14:17], v[82:85], v[114:117], v[14:17]
	v_mfma_f32_16x16x32_bf16 v[10:13], v[90:93], v[114:117], v[10:13]
	v_mfma_f32_16x16x32_bf16 v[6:9], v[82:85], v[122:125], v[6:9]
	v_mfma_f32_16x16x32_bf16 v[2:5], v[90:93], v[122:125], v[2:5]
	v_mfma_f32_16x16x32_bf16 v[38:41], v[86:89], v[102:105], v[38:41]
	v_mfma_f32_16x16x32_bf16 v[34:37], v[94:97], v[102:105], v[34:37]
	v_mfma_f32_16x16x32_bf16 v[22:25], v[86:89], v[110:113], v[22:25]
	v_mfma_f32_16x16x32_bf16 v[18:21], v[94:97], v[110:113], v[18:21]
	v_mfma_f32_16x16x32_bf16 v[14:17], v[86:89], v[118:121], v[14:17]
	v_mfma_f32_16x16x32_bf16 v[10:13], v[94:97], v[118:121], v[10:13]
	v_mfma_f32_16x16x32_bf16 v[6:9], v[86:89], v[126:129], v[6:9]
	v_mfma_f32_16x16x32_bf16 v[2:5], v[94:97], v[126:129], v[2:5]
	s_setprio 0
	s_barrier
	s_mov_b32 m0, s37
	s_nop 0
	global_load_lds_dwordx4 v182, s[14:15]
	s_add_u32 s80, s14, 0x160000
	s_mov_b32 m0, s45
	s_nop 0
	global_load_lds_dwordx4 v184, s[14:15]
	s_addc_u32 s81, s15, 0
	s_mov_b32 m0, s47
	s_nop 0
	global_load_lds_dwordx4 v182, s[80:81]
	s_nop 0
	s_mov_b32 m0, s56
	s_nop 0
	global_load_lds_dwordx4 v184, s[80:81]
	s_nop 0
	s_waitcnt vmcnt(6)
	s_waitcnt lgkmcnt(0)
	s_barrier
	s_barrier
	ds_read_b128 v[66:69], v190
	ds_read_b128 v[70:73], v190 offset:1024
	ds_read_b128 v[74:77], v190 offset:2048
	ds_read_b128 v[78:81], v190 offset:3072
	ds_read_b128 v[82:85], v191
	ds_read_b128 v[86:89], v191 offset:1024
	ds_read_b128 v[90:93], v191 offset:2048
	ds_read_b128 v[94:97], v191 offset:3072
	ds_read_b128 v[98:101], v189 offset:32768
	ds_read_b128 v[102:105], v189 offset:33792
	ds_read_b128 v[106:109], v189 offset:34816
	ds_read_b128 v[110:113], v189 offset:35840
	ds_read_b128 v[114:117], v189 offset:36864
	ds_read_b128 v[118:121], v189 offset:37888
	ds_read_b128 v[122:125], v189 offset:38912
	ds_read_b128 v[126:129], v189 offset:39936
	s_mov_b32 m0, s35
	s_nop 0
	global_load_lds_dwordx4 v1, s[16:17]
	s_mov_b32 m0, s57
	s_nop 0
	global_load_lds_dwordx4 v183, s[16:17]
	s_add_u32 s16, s16, 0x160000
	s_addc_u32 s17, s17, 0
	s_mov_b32 m0, s58
	s_nop 0
	global_load_lds_dwordx4 v1, s[16:17]
	s_nop 0
	s_mov_b32 m0, s59
	s_nop 0
	global_load_lds_dwordx4 v183, s[16:17]
	s_waitcnt vmcnt(8)
	s_waitcnt lgkmcnt(0)
	s_barrier
; #define PG8_STAGE(bufoff, gbase, voff) do { _Pragma("unroll") for (int _i = 0; _i < 2; ++_i) \
;         asm volatile("s_mov_b32 m0, %0\n\ts_nop 0\n\tglobal_load_lds_dwordx4 %1, %2" :: "s"(ldsb + (unsigned)(bufoff) + ldsw + (unsigned)(_i * 8192)), "v"((voff)[_i]), "s"((const char*)(gbase)) : "memory", "m0"); } while (0)
; #define PG8_LDA(dst, b, h) do { _Pragma("unroll") for (int m = 0; m < 4; ++m) _Pragma("unroll") for (int k = 0; k < 2; ++k) dst[m][k] = *(const LAS bf16x8*)(lds + PG8_SA(b, h) + aoff + m * 2048 + k * 1024); } while (0)
; #define PG8_LDB(dst, b, h) do { _Pragma("unroll") for (int n = 0; n < 2; ++n) _Pragma("unroll") for (int k = 0; k < 2; ++k) dst[n][k] = *(const LAS bf16x8*)(lds + PG8_SB(b, h) + boff + n * 2048 + k * 1024); } while (0)
; #define PG8_MMA(ai, bj, At, Bt) do { __builtin_amdgcn_s_setprio(1); _Pragma("unroll") for (int m = 0; m < 4; ++m) _Pragma("unroll") for (int n = 0; n < 2; ++n) _Pragma("unroll") for (int k = 0; k < 2; ++k) \
;         acc[ai][bj][m][n] = __builtin_amdgcn_mfma_f32_16x16x32_bf16(Bt[n][k], At[m][k], acc[ai][bj][m][n], 0, 0, 0); __builtin_amdgcn_s_setprio(0); } while (0)
; #define PG8_WAIT_V(n) asm volatile("s_waitcnt vmcnt(" #n ")" ::: "memory")
; #define PG8_WAIT_L(n) asm volatile("s_waitcnt lgkmcnt(" #n ")" ::: "memory")
; #define PG8_BAR __builtin_amdgcn_s_barrier()
; #define PG8_SCHED __builtin_amdgcn_sched_barrier(0)
; template <class Epi, class Sched>
; __device__ __forceinline__ void gemm_phase(LAS unsigned char* lds, const Gemm g, const Sched& S, const Epi& E) {
;     ...
;             PG8_WAIT_V(8); PG8_WAIT_L(0); PG8_BAR; PG8_MMA(0, 0, At, B0); PG8_MMA(0, 1, At, B1); PG8_BAR; PG8_SCHED;
;             PG8_LDA(At, 0, 1); PG8_STAGE(PG8_SB(0, 0), b2, voffB); PG8_STAGE(PG8_SB(0, 1), b2 + hstepB, voffB); PG8_STAGE(PG8_SA(0, 0), a2, voffA);
;             PG8_WAIT_V(8); PG8_WAIT_L(0); PG8_BAR; PG8_BAR; PG8_SCHED;
;             PG8_LDB(B0, 1, 0); PG8_LDB(B1, 1, 1); PG8_SCHED; PG8_LDA(At, 1, 0); PG8_STAGE(PG8_SA(0, 1), a2 + hstepA, voffA);
;             PG8_WAIT_V(8); PG8_WAIT_L(0); PG8_BAR; PG8_MMA(0, 0, At, B0); PG8_MMA(0, 1, At, B1); PG8_BAR; PG8_SCHED;
;             PG8_LDA(At, 1, 1); PG8_STAGE(PG8_SB(1, 0), b3, voffB); PG8_STAGE(PG8_SB(1, 1), b3 + hstepB, voffB); PG8_STAGE(PG8_SA(1, 0), a3, voffA);
;             PG8_WAIT_V(8); PG8_WAIT_L(0); PG8_BAR; PG8_BAR; PG8_SCHED;
;         }
;         }
	s_setprio 1
	s_waitcnt lgkmcnt(7)
	v_mfma_f32_16x16x32_bf16 v[62:65], v[66:69], v[98:101], v[62:65]
	v_mfma_f32_16x16x32_bf16 v[58:61], v[74:77], v[98:101], v[58:61]
	s_waitcnt lgkmcnt(5)
	v_mfma_f32_16x16x32_bf16 v[54:57], v[66:69], v[106:109], v[54:57]
	v_mfma_f32_16x16x32_bf16 v[50:53], v[74:77], v[106:109], v[50:53]
	s_waitcnt lgkmcnt(3)
	v_mfma_f32_16x16x32_bf16 v[46:49], v[66:69], v[114:117], v[46:49]
	v_mfma_f32_16x16x32_bf16 v[42:45], v[74:77], v[114:117], v[42:45]
	s_waitcnt lgkmcnt(1)
	v_mfma_f32_16x16x32_bf16 v[30:33], v[66:69], v[122:125], v[30:33]
	v_mfma_f32_16x16x32_bf16 v[26:29], v[74:77], v[122:125], v[26:29]
	v_mfma_f32_16x16x32_bf16 v[62:65], v[70:73], v[102:105], v[62:65]
	v_mfma_f32_16x16x32_bf16 v[58:61], v[78:81], v[102:105], v[58:61]
	v_mfma_f32_16x16x32_bf16 v[54:57], v[70:73], v[110:113], v[54:57]
	v_mfma_f32_16x16x32_bf16 v[50:53], v[78:81], v[110:113], v[50:53]
	v_mfma_f32_16x16x32_bf16 v[46:49], v[70:73], v[118:121], v[46:49]
	v_mfma_f32_16x16x32_bf16 v[42:45], v[78:81], v[118:121], v[42:45]
	s_waitcnt lgkmcnt(0)
	v_mfma_f32_16x16x32_bf16 v[30:33], v[70:73], v[126:129], v[30:33]
	v_mfma_f32_16x16x32_bf16 v[26:29], v[78:81], v[126:129], v[26:29]
	s_setprio 0
	s_setprio 1
	v_mfma_f32_16x16x32_bf16 v[38:41], v[82:85], v[98:101], v[38:41]
	v_mfma_f32_16x16x32_bf16 v[34:37], v[90:93], v[98:101], v[34:37]
	v_mfma_f32_16x16x32_bf16 v[22:25], v[82:85], v[106:109], v[22:25]
	v_mfma_f32_16x16x32_bf16 v[18:21], v[90:93], v[106:109], v[18:21]
	v_mfma_f32_16x16x32_bf16 v[14:17], v[82:85], v[114:117], v[14:17]
	v_mfma_f32_16x16x32_bf16 v[10:13], v[90:93], v[114:117], v[10:13]
	v_mfma_f32_16x16x32_bf16 v[6:9], v[82:85], v[122:125], v[6:9]
	v_mfma_f32_16x16x32_bf16 v[2:5], v[90:93], v[122:125], v[2:5]
	v_mfma_f32_16x16x32_bf16 v[38:41], v[86:89], v[102:105], v[38:41]
	v_mfma_f32_16x16x32_bf16 v[34:37], v[94:97], v[102:105], v[34:37]
	v_mfma_f32_16x16x32_bf16 v[22:25], v[86:89], v[110:113], v[22:25]
	v_mfma_f32_16x16x32_bf16 v[18:21], v[94:97], v[110:113], v[18:21]
	v_mfma_f32_16x16x32_bf16 v[14:17], v[86:89], v[118:121], v[14:17]
	v_mfma_f32_16x16x32_bf16 v[10:13], v[94:97], v[118:121], v[10:13]
	v_mfma_f32_16x16x32_bf16 v[6:9], v[86:89], v[126:129], v[6:9]
	v_mfma_f32_16x16x32_bf16 v[2:5], v[94:97], v[126:129], v[2:5]
	s_setprio 0
	s_barrier
	s_add_u32 s16, s14, 0x80
	s_addc_u32 s17, s15, 0
	s_mov_b32 m0, s62
	s_nop 0
	global_load_lds_dwordx4 v182, s[16:17]
	s_add_u32 s14, s14, 0x160080
	s_mov_b32 m0, s63
	s_nop 0
	global_load_lds_dwordx4 v184, s[16:17]
	s_addc_u32 s15, s15, 0
	s_mov_b32 m0, s66
	s_nop 0
	global_load_lds_dwordx4 v182, s[14:15]
	s_nop 0
	s_mov_b32 m0, s67
	s_nop 0
	global_load_lds_dwordx4 v184, s[14:15]
	s_nop 0
	s_waitcnt vmcnt(6)
	s_waitcnt lgkmcnt(0)
	s_barrier
	s_barrier
	s_add_u32 s23, s23, 0x100
	s_addc_u32 s55, s55, 0
	s_add_u32 s21, s21, 0x100
	s_addc_u32 s22, s22, 0
	s_cmp_ge_i32 s78, s33
	s_mov_b32 s12, s78
	s_cbranch_scc0 .LBB0_1110
	v_mov_b32_e32 v155, 0
	v_mov_b32_e32 v154, v155
	v_mov_b32_e32 v157, v155
	v_mov_b32_e32 v156, v155
	v_mov_b32_e32 v159, v155
	v_mov_b32_e32 v158, v155
	v_mov_b32_e32 v161, v155
	v_mov_b32_e32 v160, v155
	v_mov_b32_e32 v145, v155
	v_mov_b32_e32 v144, v155
	v_mov_b32_e32 v143, v155
	v_mov_b32_e32 v142, v155
	v_mov_b32_e32 v141, v155
	v_mov_b32_e32 v140, v155
	v_mov_b32_e32 v139, v155
	v_mov_b32_e32 v138, v155
	v_mov_b32_e32 v119, v155
	v_mov_b32_e32 v118, v155
	v_mov_b32_e32 v117, v155
	v_mov_b32_e32 v116, v155
	v_mov_b32_e32 v115, v155
	v_mov_b32_e32 v114, v155
	v_mov_b32_e32 v113, v155
	v_mov_b32_e32 v112, v155
	v_mov_b32_e32 v99, v155
	v_mov_b32_e32 v98, v155
	v_mov_b32_e32 v97, v155
	v_mov_b32_e32 v96, v155
	v_mov_b32_e32 v95, v155
	v_mov_b32_e32 v94, v155
	v_mov_b32_e32 v93, v155
	v_mov_b32_e32 v92, v155
	v_mov_b32_e32 v163, v155
	v_mov_b32_e32 v162, v155
	v_mov_b32_e32 v165, v155
	v_mov_b32_e32 v164, v155
	v_mov_b32_e32 v169, v155
	v_mov_b32_e32 v168, v155
	v_mov_b32_e32 v167, v155
	v_mov_b32_e32 v166, v155
	v_mov_b32_e32 v153, v155
	v_mov_b32_e32 v152, v155
	v_mov_b32_e32 v151, v155
	v_mov_b32_e32 v150, v155
	v_mov_b32_e32 v149, v155
	v_mov_b32_e32 v148, v155
	v_mov_b32_e32 v147, v155
	v_mov_b32_e32 v146, v155
	v_mov_b32_e32 v127, v155
	v_mov_b32_e32 v126, v155
	v_mov_b32_e32 v125, v155
	v_mov_b32_e32 v124, v155
	v_mov_b32_e32 v123, v155
	v_mov_b32_e32 v122, v155
	v_mov_b32_e32 v121, v155
	v_mov_b32_e32 v120, v155
	v_mov_b32_e32 v109, v155
	v_mov_b32_e32 v108, v155
	v_mov_b32_e32 v107, v155
	v_mov_b32_e32 v106, v155
	v_mov_b32_e32 v105, v155
	v_mov_b32_e32 v104, v155
	v_mov_b32_e32 v103, v155
	v_mov_b32_e32 v102, v155
	s_andn2_b64 vcc, exec, s[42:43]
	s_cbranch_vccz .LBB0_1105
